# y_b stored pair-major ([channel pair][token][2]): hyena epilogue writes coalesced dwords, out-proj loop stages k-tiles 8..15 from that layout (16-byte loads of 4 tokens, ds_write_b32 into the same swi
# speedup vs baseline: 1.1662x; 1.0071x over previous
.Lhy_ep1_comb_L0:
	s_mov_b32 s98, 0x5040100
	s_mov_b32 s99, 0x7060302
	v_lshlrev_b32_e32 v109, 1, v10
	v_add_u32_e32 v254, 0x1e00, v10
	v_add_u32_e32 v253, 0x1000, v109
	v_cmp_gt_i32_e32 vcc, 0x1fff, v254
	v_add_u32_e32 v251, 0x2000, v109
	v_add_u32_e32 v250, 0x3000, v109
	v_min_i32_e32 v254, 0x1ffe, v254
	v_cndmask_b32_e64 v255, 0, 1.0, vcc
	v_lshlrev_b32_e32 v254, 1, v254
	global_load_ushort v9, v109, s[0:1]
	global_load_ushort v11, v109, s[4:5]
	global_load_ushort v13, v109, s[36:37] offset:1022
	global_load_ushort v15, v109, s[36:37] offset:1024
	global_load_ushort v81, v109, s[36:37] offset:1026
	global_load_ushort v83, v109, s[88:89] offset:1022
	global_load_ushort v85, v109, s[88:89] offset:1024
	global_load_ushort v87, v109, s[88:89] offset:1026
	global_load_ushort v89, v109, s[0:1] offset:1024
	global_load_ushort v91, v109, s[4:5] offset:1024
	global_load_ushort v93, v109, s[36:37] offset:2046
	global_load_ushort v94, v109, s[36:37] offset:2048
	global_load_ushort v95, v109, s[36:37] offset:2050
	global_load_ushort v96, v109, s[88:89] offset:2046
	global_load_ushort v97, v109, s[88:89] offset:2048
	global_load_ushort v98, v109, s[88:89] offset:2050
	global_load_ushort v99, v109, s[0:1] offset:2048
	global_load_ushort v100, v109, s[4:5] offset:2048
	global_load_ushort v101, v109, s[36:37] offset:3070
	global_load_ushort v102, v109, s[36:37] offset:3072
	global_load_ushort v103, v109, s[36:37] offset:3074
	global_load_ushort v104, v109, s[88:89] offset:3070
	global_load_ushort v105, v109, s[88:89] offset:3072
	global_load_ushort v106, v109, s[88:89] offset:3074
	global_load_ushort v107, v109, s[0:1] offset:3072
	global_load_ushort v108, v109, s[4:5] offset:3072
	global_load_ushort v111, v253, s[36:37] offset:-2
	global_load_ushort v112, v253, s[36:37]
	global_load_ushort v113, v253, s[36:37] offset:2
	global_load_ushort v114, v253, s[88:89] offset:-2
	global_load_ushort v115, v253, s[88:89]
	global_load_ushort v116, v253, s[88:89] offset:2
	global_load_ushort v117, v253, s[0:1]
	global_load_ushort v118, v253, s[4:5]
	global_load_ushort v119, v253, s[36:37] offset:1022
	global_load_ushort v120, v253, s[36:37] offset:1024
	global_load_ushort v121, v253, s[36:37] offset:1026
	global_load_ushort v122, v253, s[88:89] offset:1022
	global_load_ushort v123, v253, s[88:89] offset:1024
	global_load_ushort v124, v253, s[88:89] offset:1026
	global_load_ushort v125, v253, s[0:1] offset:1024
	global_load_ushort v126, v253, s[4:5] offset:1024
	global_load_ushort v127, v253, s[36:37] offset:2046
	global_load_ushort v128, v253, s[36:37] offset:2048
	global_load_ushort v129, v253, s[36:37] offset:2050
	global_load_ushort v130, v253, s[88:89] offset:2046
	global_load_ushort v131, v253, s[88:89] offset:2048
	global_load_ushort v132, v253, s[88:89] offset:2050
	global_load_ushort v133, v253, s[0:1] offset:2048
	global_load_ushort v134, v253, s[4:5] offset:2048
	global_load_ushort v135, v253, s[36:37] offset:3070
	global_load_ushort v136, v253, s[36:37] offset:3072
	global_load_ushort v137, v253, s[36:37] offset:3074
	global_load_ushort v138, v253, s[88:89] offset:3070
	global_load_ushort v139, v253, s[88:89] offset:3072
	global_load_ushort v140, v253, s[88:89] offset:3074
	global_load_ushort v141, v253, s[0:1] offset:3072
	global_load_ushort v142, v253, s[4:5] offset:3072
	global_load_ushort v143, v251, s[36:37] offset:-2
	global_load_ushort v163, v251, s[36:37]
	global_load_ushort v164, v251, s[36:37] offset:2
	global_load_ushort v165, v251, s[88:89] offset:-2
	global_load_ushort v166, v251, s[88:89]
	global_load_ushort v167, v251, s[88:89] offset:2
	global_load_ushort v168, v251, s[0:1]
	global_load_ushort v169, v251, s[4:5]
	global_load_ushort v170, v251, s[36:37] offset:1022
	global_load_ushort v171, v251, s[36:37] offset:1024
	global_load_ushort v172, v251, s[36:37] offset:1026
	global_load_ushort v173, v251, s[88:89] offset:1022
	global_load_ushort v174, v251, s[88:89] offset:1024
	global_load_ushort v175, v251, s[88:89] offset:1026
	global_load_ushort v176, v251, s[0:1] offset:1024
	global_load_ushort v177, v251, s[4:5] offset:1024
	global_load_ushort v178, v251, s[36:37] offset:2046
	global_load_ushort v179, v251, s[36:37] offset:2048
	global_load_ushort v180, v251, s[36:37] offset:2050
	global_load_ushort v181, v251, s[88:89] offset:2046
	global_load_ushort v182, v251, s[88:89] offset:2048
	global_load_ushort v183, v251, s[88:89] offset:2050
	global_load_ushort v184, v251, s[0:1] offset:2048
	global_load_ushort v185, v251, s[4:5] offset:2048
	global_load_ushort v186, v251, s[36:37] offset:3070
	global_load_ushort v187, v251, s[36:37] offset:3072
	global_load_ushort v188, v251, s[36:37] offset:3074
	global_load_ushort v189, v251, s[88:89] offset:3070
	global_load_ushort v190, v251, s[88:89] offset:3072
	global_load_ushort v191, v251, s[88:89] offset:3074
	global_load_ushort v192, v251, s[0:1] offset:3072
	global_load_ushort v193, v251, s[4:5] offset:3072
	global_load_ushort v194, v250, s[36:37] offset:-2
	global_load_ushort v195, v250, s[36:37]
	global_load_ushort v196, v250, s[36:37] offset:2
	global_load_ushort v197, v250, s[88:89] offset:-2
	global_load_ushort v221, v250, s[88:89]
	global_load_ushort v222, v250, s[88:89] offset:2
	global_load_ushort v223, v250, s[0:1]
	global_load_ushort v224, v250, s[4:5]
	global_load_ushort v225, v250, s[36:37] offset:1022
	global_load_ushort v226, v250, s[36:37] offset:1024
	global_load_ushort v227, v250, s[36:37] offset:1026
	global_load_ushort v228, v250, s[88:89] offset:1022
	global_load_ushort v229, v250, s[88:89] offset:1024
	global_load_ushort v230, v250, s[88:89] offset:1026
	global_load_ushort v231, v250, s[0:1] offset:1024
	global_load_ushort v232, v250, s[4:5] offset:1024
	global_load_ushort v233, v250, s[36:37] offset:2046
	global_load_ushort v234, v250, s[36:37] offset:2048
	global_load_ushort v235, v250, s[36:37] offset:2050
	global_load_ushort v236, v250, s[88:89] offset:2046
	global_load_ushort v237, v250, s[88:89] offset:2048
	global_load_ushort v238, v250, s[88:89] offset:2050
	global_load_ushort v239, v250, s[0:1] offset:2048
	global_load_ushort v240, v250, s[4:5] offset:2048
	global_load_ushort v241, v250, s[36:37] offset:3070
	global_load_ushort v242, v250, s[36:37] offset:3072
	global_load_ushort v243, v254, s[36:37] offset:2
	global_load_ushort v244, v250, s[88:89] offset:3070
	global_load_ushort v245, v250, s[88:89] offset:3072
	global_load_ushort v246, v254, s[88:89] offset:2
	global_load_ushort v247, v250, s[0:1] offset:3072
	global_load_ushort v248, v250, s[4:5] offset:3072
	v_readlane_b32 s0, v252, 50
	v_readlane_b32 s1, v252, 51
	s_lshr_b32 s4, s68, 1
	s_lshl_b32 s4, s4, 16
	s_add_u32 s0, s0, s4
	s_addc_u32 s1, s1, 0
	s_add_u32 s4, s0, 0x8000
	s_addc_u32 s5, s1, 0
	s_waitcnt vmcnt(63)
	v_lshlrev_b32_e32 v26, 2, v10
	v_fma_f32 v27, v32, v8, v78
	v_mul_f32_e32 v70, v80, v27
	v_lshlrev_b32_e32 v9, 16, v9
	v_mul_f32_e32 v84, 0xbfb8aa3b, v9
	v_exp_f32_e32 v84, v84
	s_nop 0
	v_add_f32_e32 v84, 1.0, v84
	v_div_scale_f32 v71, s[28:29], v84, v84, v9
	v_rcp_f32_e32 v82, v71
	s_nop 0
	v_fma_f32 v92, -v71, v82, 1.0
	v_fmac_f32_e32 v82, v92, v82
	v_div_scale_f32 v88, vcc, v9, v84, v9
	v_mul_f32_e32 v90, v88, v82
	v_fma_f32 v92, -v71, v90, v88
	v_fmac_f32_e32 v90, v92, v82
	v_fma_f32 v71, -v71, v90, v88
	v_div_fmas_f32 v71, v71, v82, v90
	v_div_fixup_f32 v9, v71, v84, v9
	v_mul_f32_e32 v70, v70, v9
	v_fma_f32 v27, v34, v8, v79
	v_mul_f32_e32 v110, v86, v27
	v_lshlrev_b32_e32 v11, 16, v11
	v_mul_f32_e32 v84, 0xbfb8aa3b, v11
	v_exp_f32_e32 v84, v84
	s_nop 0
	v_add_f32_e32 v84, 1.0, v84
	v_div_scale_f32 v71, s[28:29], v84, v84, v11
	v_rcp_f32_e32 v82, v71
	s_nop 0
	v_fma_f32 v92, -v71, v82, 1.0
	v_fmac_f32_e32 v82, v92, v82
	v_div_scale_f32 v88, vcc, v11, v84, v11
	v_mul_f32_e32 v90, v88, v82
	v_fma_f32 v92, -v71, v90, v88
	v_fmac_f32_e32 v90, v92, v82
	v_fma_f32 v71, -v71, v90, v88
	v_div_fmas_f32 v71, v71, v82, v90
	v_div_fixup_f32 v11, v71, v84, v11
	v_mul_f32_e32 v110, v110, v11
	v_cvt_pk_bf16_f32 v70, v70, v110
	v_perm_b32 v110, v70, v198, s98
	v_perm_b32 v70, v70, v198, s99
	global_store_dword v26, v110, s[0:1]
	global_store_dword v26, v70, s[4:5]
	v_add_u32_e32 v26, 0x800, v26
	v_lshlrev_b32_e32 v15, 16, v15
	v_lshlrev_b32_e32 v81, 16, v81
	v_lshlrev_b32_e32 v13, 16, v13
	v_mul_f32_e32 v13, v16, v13
	v_fmac_f32_e32 v13, v14, v15
	v_fmac_f32_e32 v13, v17, v81
	v_add_f32_e32 v13, v12, v13
	v_fma_f32 v27, v33, v8, v76
	v_mul_f32_e32 v70, v27, v13
	v_lshlrev_b32_e32 v89, 16, v89
	v_mul_f32_e32 v84, 0xbfb8aa3b, v89
	v_exp_f32_e32 v84, v84
	s_nop 0
	v_add_f32_e32 v84, 1.0, v84
	v_div_scale_f32 v71, s[28:29], v84, v84, v89
	v_rcp_f32_e32 v82, v71
	s_nop 0
	v_fma_f32 v92, -v71, v82, 1.0
	v_fmac_f32_e32 v82, v92, v82
	v_div_scale_f32 v88, vcc, v89, v84, v89
	v_mul_f32_e32 v90, v88, v82
	v_fma_f32 v92, -v71, v90, v88
	v_fmac_f32_e32 v90, v92, v82
	v_fma_f32 v71, -v71, v90, v88
	v_div_fmas_f32 v71, v71, v82, v90
	v_div_fixup_f32 v89, v71, v84, v89
	v_mul_f32_e32 v70, v70, v89
	v_lshlrev_b32_e32 v85, 16, v85
	v_lshlrev_b32_e32 v87, 16, v87
	v_lshlrev_b32_e32 v83, 16, v83
	v_mul_f32_e32 v83, v16, v83
	v_fmac_f32_e32 v83, v14, v85
	v_fmac_f32_e32 v83, v17, v87
	v_add_f32_e32 v83, v12, v83
	v_fma_f32 v27, v35, v8, v77
	v_mul_f32_e32 v110, v27, v83
	v_lshlrev_b32_e32 v91, 16, v91
	v_mul_f32_e32 v84, 0xbfb8aa3b, v91
	v_exp_f32_e32 v84, v84
	s_nop 0
	v_add_f32_e32 v84, 1.0, v84
	v_div_scale_f32 v71, s[28:29], v84, v84, v91
	v_rcp_f32_e32 v82, v71
	s_nop 0
	v_fma_f32 v92, -v71, v82, 1.0
	v_fmac_f32_e32 v82, v92, v82
	v_div_scale_f32 v88, vcc, v91, v84, v91
	v_mul_f32_e32 v90, v88, v82
	v_fma_f32 v92, -v71, v90, v88
	v_fmac_f32_e32 v90, v92, v82
	v_fma_f32 v71, -v71, v90, v88
	v_div_fmas_f32 v71, v71, v82, v90
	v_div_fixup_f32 v91, v71, v84, v91
	v_mul_f32_e32 v110, v110, v91
	v_cvt_pk_bf16_f32 v70, v70, v110
	v_perm_b32 v110, v70, v199, s98
	v_perm_b32 v70, v70, v199, s99
	global_store_dword v26, v110, s[0:1]
	global_store_dword v26, v70, s[4:5]
	v_add_u32_e32 v26, 0x800, v26
	v_lshlrev_b32_e32 v94, 16, v94
	v_lshlrev_b32_e32 v95, 16, v95
	v_lshlrev_b32_e32 v93, 16, v93
	v_mul_f32_e32 v93, v16, v93
	v_fmac_f32_e32 v93, v14, v94
	v_fmac_f32_e32 v93, v17, v95
	v_add_f32_e32 v93, v12, v93
	v_fma_f32 v27, v37, v8, v72
	v_mul_f32_e32 v70, v27, v93
	v_lshlrev_b32_e32 v99, 16, v99
	v_mul_f32_e32 v84, 0xbfb8aa3b, v99
	v_exp_f32_e32 v84, v84
	s_nop 0
	v_add_f32_e32 v84, 1.0, v84
	v_div_scale_f32 v71, s[28:29], v84, v84, v99
	v_rcp_f32_e32 v82, v71
	s_nop 0
	v_fma_f32 v92, -v71, v82, 1.0
	v_fmac_f32_e32 v82, v92, v82
	v_div_scale_f32 v88, vcc, v99, v84, v99
	v_mul_f32_e32 v90, v88, v82
	v_fma_f32 v92, -v71, v90, v88
	v_fmac_f32_e32 v90, v92, v82
	v_fma_f32 v71, -v71, v90, v88
	v_div_fmas_f32 v71, v71, v82, v90
	v_div_fixup_f32 v99, v71, v84, v99
	v_mul_f32_e32 v70, v70, v99
	v_lshlrev_b32_e32 v97, 16, v97
	v_lshlrev_b32_e32 v98, 16, v98
	v_lshlrev_b32_e32 v96, 16, v96
	v_mul_f32_e32 v96, v16, v96
	v_fmac_f32_e32 v96, v14, v97
	v_fmac_f32_e32 v96, v17, v98
	v_add_f32_e32 v96, v12, v96
	v_fma_f32 v27, v31, v8, v73
	v_mul_f32_e32 v110, v27, v96
	v_lshlrev_b32_e32 v100, 16, v100
	v_mul_f32_e32 v84, 0xbfb8aa3b, v100
	v_exp_f32_e32 v84, v84
	s_nop 0
	v_add_f32_e32 v84, 1.0, v84
	v_div_scale_f32 v71, s[28:29], v84, v84, v100
	v_rcp_f32_e32 v82, v71
	s_nop 0
	v_fma_f32 v92, -v71, v82, 1.0
	v_fmac_f32_e32 v82, v92, v82
	v_div_scale_f32 v88, vcc, v100, v84, v100
	v_mul_f32_e32 v90, v88, v82
	v_fma_f32 v92, -v71, v90, v88
	v_fmac_f32_e32 v90, v92, v82
	v_fma_f32 v71, -v71, v90, v88
	v_div_fmas_f32 v71, v71, v82, v90
	v_div_fixup_f32 v100, v71, v84, v100
	v_mul_f32_e32 v110, v110, v100
	v_cvt_pk_bf16_f32 v70, v70, v110
	v_perm_b32 v110, v70, v200, s98
	v_perm_b32 v70, v70, v200, s99
	global_store_dword v26, v110, s[0:1]
	global_store_dword v26, v70, s[4:5]
	v_add_u32_e32 v26, 0x800, v26
	v_lshlrev_b32_e32 v102, 16, v102
	v_lshlrev_b32_e32 v103, 16, v103
	v_lshlrev_b32_e32 v101, 16, v101
	v_mul_f32_e32 v101, v16, v101
	v_fmac_f32_e32 v101, v14, v102
	v_fmac_f32_e32 v101, v17, v103
	v_add_f32_e32 v101, v12, v101
	v_fma_f32 v27, v36, v8, v74
	v_mul_f32_e32 v70, v27, v101
	v_lshlrev_b32_e32 v107, 16, v107
	v_mul_f32_e32 v84, 0xbfb8aa3b, v107
	v_exp_f32_e32 v84, v84
	s_nop 0
	v_add_f32_e32 v84, 1.0, v84
	v_div_scale_f32 v71, s[28:29], v84, v84, v107
	v_rcp_f32_e32 v82, v71
	s_nop 0
	v_fma_f32 v92, -v71, v82, 1.0
	v_fmac_f32_e32 v82, v92, v82
	v_div_scale_f32 v88, vcc, v107, v84, v107
	v_mul_f32_e32 v90, v88, v82
	v_fma_f32 v92, -v71, v90, v88
	v_fmac_f32_e32 v90, v92, v82
	v_fma_f32 v71, -v71, v90, v88
	v_div_fmas_f32 v71, v71, v82, v90
	v_div_fixup_f32 v107, v71, v84, v107
	v_mul_f32_e32 v70, v70, v107
	v_lshlrev_b32_e32 v105, 16, v105
	v_lshlrev_b32_e32 v106, 16, v106
	v_lshlrev_b32_e32 v104, 16, v104
	v_mul_f32_e32 v104, v16, v104
	v_fmac_f32_e32 v104, v14, v105
	v_fmac_f32_e32 v104, v17, v106
	v_add_f32_e32 v104, v12, v104
	v_fma_f32 v27, v30, v8, v75
	v_mul_f32_e32 v110, v27, v104
	v_lshlrev_b32_e32 v108, 16, v108
	v_mul_f32_e32 v84, 0xbfb8aa3b, v108
	v_exp_f32_e32 v84, v84
	s_nop 0
	v_add_f32_e32 v84, 1.0, v84
	v_div_scale_f32 v71, s[28:29], v84, v84, v108
	v_rcp_f32_e32 v82, v71
	s_nop 0
	v_fma_f32 v92, -v71, v82, 1.0
	v_fmac_f32_e32 v82, v92, v82
	v_div_scale_f32 v88, vcc, v108, v84, v108
	v_mul_f32_e32 v90, v88, v82
	v_fma_f32 v92, -v71, v90, v88
	v_fmac_f32_e32 v90, v92, v82
	v_fma_f32 v71, -v71, v90, v88
	v_div_fmas_f32 v71, v71, v82, v90
	v_div_fixup_f32 v108, v71, v84, v108
	v_mul_f32_e32 v110, v110, v108
	v_cvt_pk_bf16_f32 v70, v70, v110
	v_perm_b32 v110, v70, v201, s98
	v_perm_b32 v70, v70, v201, s99
	global_store_dword v26, v110, s[0:1]
	global_store_dword v26, v70, s[4:5]
	s_waitcnt vmcnt(63)
	v_add_u32_e32 v26, 0x800, v26
	v_lshlrev_b32_e32 v112, 16, v112
	v_lshlrev_b32_e32 v113, 16, v113
	v_lshlrev_b32_e32 v111, 16, v111
	v_mul_f32_e32 v111, v16, v111
	v_fmac_f32_e32 v111, v14, v112
	v_fmac_f32_e32 v111, v17, v113
	v_add_f32_e32 v111, v12, v111
	v_fma_f32 v27, v39, v8, v66
	v_mul_f32_e32 v70, v27, v111
	v_lshlrev_b32_e32 v117, 16, v117
	v_mul_f32_e32 v84, 0xbfb8aa3b, v117
	v_exp_f32_e32 v84, v84
	s_nop 0
	v_add_f32_e32 v84, 1.0, v84
	v_div_scale_f32 v71, s[28:29], v84, v84, v117
	v_rcp_f32_e32 v82, v71
	s_nop 0
	v_fma_f32 v92, -v71, v82, 1.0
	v_fmac_f32_e32 v82, v92, v82
	v_div_scale_f32 v88, vcc, v117, v84, v117
	v_mul_f32_e32 v90, v88, v82
	v_fma_f32 v92, -v71, v90, v88
	v_fmac_f32_e32 v90, v92, v82
	v_fma_f32 v71, -v71, v90, v88
	v_div_fmas_f32 v71, v71, v82, v90
	v_div_fixup_f32 v117, v71, v84, v117
	v_mul_f32_e32 v70, v70, v117
	v_lshlrev_b32_e32 v115, 16, v115
	v_lshlrev_b32_e32 v116, 16, v116
	v_lshlrev_b32_e32 v114, 16, v114
	v_mul_f32_e32 v114, v16, v114
	v_fmac_f32_e32 v114, v14, v115
	v_fmac_f32_e32 v114, v17, v116
	v_add_f32_e32 v114, v12, v114
	v_fma_f32 v27, v41, v8, v67
	v_mul_f32_e32 v110, v27, v114
	v_lshlrev_b32_e32 v118, 16, v118
	v_mul_f32_e32 v84, 0xbfb8aa3b, v118
	v_exp_f32_e32 v84, v84
	s_nop 0
	v_add_f32_e32 v84, 1.0, v84
	v_div_scale_f32 v71, s[28:29], v84, v84, v118
	v_rcp_f32_e32 v82, v71
	s_nop 0
	v_fma_f32 v92, -v71, v82, 1.0
	v_fmac_f32_e32 v82, v92, v82
	v_div_scale_f32 v88, vcc, v118, v84, v118
	v_mul_f32_e32 v90, v88, v82
	v_fma_f32 v92, -v71, v90, v88
	v_fmac_f32_e32 v90, v92, v82
	v_fma_f32 v71, -v71, v90, v88
	v_div_fmas_f32 v71, v71, v82, v90
	v_div_fixup_f32 v118, v71, v84, v118
	v_mul_f32_e32 v110, v110, v118
	v_cvt_pk_bf16_f32 v70, v70, v110
	v_perm_b32 v110, v70, v202, s98
	v_perm_b32 v70, v70, v202, s99
	global_store_dword v26, v110, s[0:1]
	global_store_dword v26, v70, s[4:5]
	v_add_u32_e32 v26, 0x800, v26
	v_lshlrev_b32_e32 v120, 16, v120
	v_lshlrev_b32_e32 v121, 16, v121
	v_lshlrev_b32_e32 v119, 16, v119
	v_mul_f32_e32 v119, v16, v119
	v_fmac_f32_e32 v119, v14, v120
	v_fmac_f32_e32 v119, v17, v121
	v_add_f32_e32 v119, v12, v119
	v_fma_f32 v27, v38, v8, v68
	v_mul_f32_e32 v70, v27, v119
	v_lshlrev_b32_e32 v125, 16, v125
	v_mul_f32_e32 v84, 0xbfb8aa3b, v125
	v_exp_f32_e32 v84, v84
	s_nop 0
	v_add_f32_e32 v84, 1.0, v84
	v_div_scale_f32 v71, s[28:29], v84, v84, v125
	v_rcp_f32_e32 v82, v71
	s_nop 0
	v_fma_f32 v92, -v71, v82, 1.0
	v_fmac_f32_e32 v82, v92, v82
	v_div_scale_f32 v88, vcc, v125, v84, v125
	v_mul_f32_e32 v90, v88, v82
	v_fma_f32 v92, -v71, v90, v88
	v_fmac_f32_e32 v90, v92, v82
	v_fma_f32 v71, -v71, v90, v88
	v_div_fmas_f32 v71, v71, v82, v90
	v_div_fixup_f32 v125, v71, v84, v125
	v_mul_f32_e32 v70, v70, v125
	v_lshlrev_b32_e32 v123, 16, v123
	v_lshlrev_b32_e32 v124, 16, v124
	v_lshlrev_b32_e32 v122, 16, v122
	v_mul_f32_e32 v122, v16, v122
	v_fmac_f32_e32 v122, v14, v123
	v_fmac_f32_e32 v122, v17, v124
	v_add_f32_e32 v122, v12, v122
	v_fma_f32 v27, v40, v8, v69
	v_mul_f32_e32 v110, v27, v122
	v_lshlrev_b32_e32 v126, 16, v126
	v_mul_f32_e32 v84, 0xbfb8aa3b, v126
	v_exp_f32_e32 v84, v84
	s_nop 0
	v_add_f32_e32 v84, 1.0, v84
	v_div_scale_f32 v71, s[28:29], v84, v84, v126
	v_rcp_f32_e32 v82, v71
	s_nop 0
	v_fma_f32 v92, -v71, v82, 1.0
	v_fmac_f32_e32 v82, v92, v82
	v_div_scale_f32 v88, vcc, v126, v84, v126
	v_mul_f32_e32 v90, v88, v82
	v_fma_f32 v92, -v71, v90, v88
	v_fmac_f32_e32 v90, v92, v82
	v_fma_f32 v71, -v71, v90, v88
	v_div_fmas_f32 v71, v71, v82, v90
	v_div_fixup_f32 v126, v71, v84, v126
	v_mul_f32_e32 v110, v110, v126
	v_cvt_pk_bf16_f32 v70, v70, v110
	v_perm_b32 v110, v70, v203, s98
	v_perm_b32 v70, v70, v203, s99
	global_store_dword v26, v110, s[0:1]
	global_store_dword v26, v70, s[4:5]
	v_add_u32_e32 v26, 0x800, v26
	v_lshlrev_b32_e32 v128, 16, v128
	v_lshlrev_b32_e32 v129, 16, v129
	v_lshlrev_b32_e32 v127, 16, v127
	v_mul_f32_e32 v127, v16, v127
	v_fmac_f32_e32 v127, v14, v128
	v_fmac_f32_e32 v127, v17, v129
	v_add_f32_e32 v127, v12, v127
	v_fma_f32 v27, v43, v8, v62
	v_mul_f32_e32 v70, v27, v127
	v_lshlrev_b32_e32 v133, 16, v133
	v_mul_f32_e32 v84, 0xbfb8aa3b, v133
	v_exp_f32_e32 v84, v84
	s_nop 0
	v_add_f32_e32 v84, 1.0, v84
	v_div_scale_f32 v71, s[28:29], v84, v84, v133
	v_rcp_f32_e32 v82, v71
	s_nop 0
	v_fma_f32 v92, -v71, v82, 1.0
	v_fmac_f32_e32 v82, v92, v82
	v_div_scale_f32 v88, vcc, v133, v84, v133
	v_mul_f32_e32 v90, v88, v82
	v_fma_f32 v92, -v71, v90, v88
	v_fmac_f32_e32 v90, v92, v82
	v_fma_f32 v71, -v71, v90, v88
	v_div_fmas_f32 v71, v71, v82, v90
	v_div_fixup_f32 v133, v71, v84, v133
	v_mul_f32_e32 v70, v70, v133
	v_lshlrev_b32_e32 v131, 16, v131
	v_lshlrev_b32_e32 v132, 16, v132
	v_lshlrev_b32_e32 v130, 16, v130
	v_mul_f32_e32 v130, v16, v130
	v_fmac_f32_e32 v130, v14, v131
	v_fmac_f32_e32 v130, v17, v132
	v_add_f32_e32 v130, v12, v130
	v_fma_f32 v27, v45, v8, v63
	v_mul_f32_e32 v110, v27, v130
	v_lshlrev_b32_e32 v134, 16, v134
	v_mul_f32_e32 v84, 0xbfb8aa3b, v134
	v_exp_f32_e32 v84, v84
	s_nop 0
	v_add_f32_e32 v84, 1.0, v84
	v_div_scale_f32 v71, s[28:29], v84, v84, v134
	v_rcp_f32_e32 v82, v71
	s_nop 0
	v_fma_f32 v92, -v71, v82, 1.0
	v_fmac_f32_e32 v82, v92, v82
	v_div_scale_f32 v88, vcc, v134, v84, v134
	v_mul_f32_e32 v90, v88, v82
	v_fma_f32 v92, -v71, v90, v88
	v_fmac_f32_e32 v90, v92, v82
	v_fma_f32 v71, -v71, v90, v88
	v_div_fmas_f32 v71, v71, v82, v90
	v_div_fixup_f32 v134, v71, v84, v134
	v_mul_f32_e32 v110, v110, v134
	v_cvt_pk_bf16_f32 v70, v70, v110
	v_perm_b32 v110, v70, v204, s98
	v_perm_b32 v70, v70, v204, s99
	global_store_dword v26, v110, s[0:1]
	global_store_dword v26, v70, s[4:5]
	v_add_u32_e32 v26, 0x800, v26
	v_lshlrev_b32_e32 v136, 16, v136
	v_lshlrev_b32_e32 v137, 16, v137
	v_lshlrev_b32_e32 v135, 16, v135
	v_mul_f32_e32 v135, v16, v135
	v_fmac_f32_e32 v135, v14, v136
	v_fmac_f32_e32 v135, v17, v137
	v_add_f32_e32 v135, v12, v135
	v_fma_f32 v27, v42, v8, v64
	v_mul_f32_e32 v70, v27, v135
	v_lshlrev_b32_e32 v141, 16, v141
	v_mul_f32_e32 v84, 0xbfb8aa3b, v141
	v_exp_f32_e32 v84, v84
	s_nop 0
	v_add_f32_e32 v84, 1.0, v84
	v_div_scale_f32 v71, s[28:29], v84, v84, v141
	v_rcp_f32_e32 v82, v71
	s_nop 0
	v_fma_f32 v92, -v71, v82, 1.0
	v_fmac_f32_e32 v82, v92, v82
	v_div_scale_f32 v88, vcc, v141, v84, v141
	v_mul_f32_e32 v90, v88, v82
	v_fma_f32 v92, -v71, v90, v88
	v_fmac_f32_e32 v90, v92, v82
	v_fma_f32 v71, -v71, v90, v88
	v_div_fmas_f32 v71, v71, v82, v90
	v_div_fixup_f32 v141, v71, v84, v141
	v_mul_f32_e32 v70, v70, v141
	v_lshlrev_b32_e32 v139, 16, v139
	v_lshlrev_b32_e32 v140, 16, v140
	v_lshlrev_b32_e32 v138, 16, v138
	v_mul_f32_e32 v138, v16, v138
	v_fmac_f32_e32 v138, v14, v139
	v_fmac_f32_e32 v138, v17, v140
	v_add_f32_e32 v138, v12, v138
	v_fma_f32 v27, v44, v8, v65
	v_mul_f32_e32 v110, v27, v138
	v_lshlrev_b32_e32 v142, 16, v142
	v_mul_f32_e32 v84, 0xbfb8aa3b, v142
	v_exp_f32_e32 v84, v84
	s_nop 0
	v_add_f32_e32 v84, 1.0, v84
	v_div_scale_f32 v71, s[28:29], v84, v84, v142
	v_rcp_f32_e32 v82, v71
	s_nop 0
	v_fma_f32 v92, -v71, v82, 1.0
	v_fmac_f32_e32 v82, v92, v82
	v_div_scale_f32 v88, vcc, v142, v84, v142
	v_mul_f32_e32 v90, v88, v82
	v_fma_f32 v92, -v71, v90, v88
	v_fmac_f32_e32 v90, v92, v82
	v_fma_f32 v71, -v71, v90, v88
	v_div_fmas_f32 v71, v71, v82, v90
	v_div_fixup_f32 v142, v71, v84, v142
	v_mul_f32_e32 v110, v110, v142
	v_cvt_pk_bf16_f32 v70, v70, v110
	v_perm_b32 v110, v70, v205, s98
	v_perm_b32 v70, v70, v205, s99
	global_store_dword v26, v110, s[0:1]
	global_store_dword v26, v70, s[4:5]
	s_waitcnt vmcnt(48)
	v_add_u32_e32 v26, 0x800, v26
	v_lshlrev_b32_e32 v163, 16, v163
	v_lshlrev_b32_e32 v164, 16, v164
	v_lshlrev_b32_e32 v143, 16, v143
	v_mul_f32_e32 v143, v16, v143
	v_fmac_f32_e32 v143, v14, v163
	v_fmac_f32_e32 v143, v17, v164
	v_add_f32_e32 v143, v12, v143
	v_fma_f32 v27, v47, v8, v22
	v_mul_f32_e32 v70, v27, v143
	v_lshlrev_b32_e32 v168, 16, v168
	v_mul_f32_e32 v84, 0xbfb8aa3b, v168
	v_exp_f32_e32 v84, v84
	s_nop 0
	v_add_f32_e32 v84, 1.0, v84
	v_div_scale_f32 v71, s[28:29], v84, v84, v168
	v_rcp_f32_e32 v82, v71
	s_nop 0
	v_fma_f32 v92, -v71, v82, 1.0
	v_fmac_f32_e32 v82, v92, v82
	v_div_scale_f32 v88, vcc, v168, v84, v168
	v_mul_f32_e32 v90, v88, v82
	v_fma_f32 v92, -v71, v90, v88
	v_fmac_f32_e32 v90, v92, v82
	v_fma_f32 v71, -v71, v90, v88
	v_div_fmas_f32 v71, v71, v82, v90
	v_div_fixup_f32 v168, v71, v84, v168
	v_mul_f32_e32 v70, v70, v168
	v_lshlrev_b32_e32 v166, 16, v166
	v_lshlrev_b32_e32 v167, 16, v167
	v_lshlrev_b32_e32 v165, 16, v165
	v_mul_f32_e32 v165, v16, v165
	v_fmac_f32_e32 v165, v14, v166
	v_fmac_f32_e32 v165, v17, v167
	v_add_f32_e32 v165, v12, v165
	v_fma_f32 v27, v49, v8, v23
	v_mul_f32_e32 v110, v27, v165
	v_lshlrev_b32_e32 v169, 16, v169
	v_mul_f32_e32 v84, 0xbfb8aa3b, v169
	v_exp_f32_e32 v84, v84
	s_nop 0
	v_add_f32_e32 v84, 1.0, v84
	v_div_scale_f32 v71, s[28:29], v84, v84, v169
	v_rcp_f32_e32 v82, v71
	s_nop 0
	v_fma_f32 v92, -v71, v82, 1.0
	v_fmac_f32_e32 v82, v92, v82
	v_div_scale_f32 v88, vcc, v169, v84, v169
	v_mul_f32_e32 v90, v88, v82
	v_fma_f32 v92, -v71, v90, v88
	v_fmac_f32_e32 v90, v92, v82
	v_fma_f32 v71, -v71, v90, v88
	v_div_fmas_f32 v71, v71, v82, v90
	v_div_fixup_f32 v169, v71, v84, v169
	v_mul_f32_e32 v110, v110, v169
	v_cvt_pk_bf16_f32 v70, v70, v110
	v_perm_b32 v110, v70, v206, s98
	v_perm_b32 v70, v70, v206, s99
	global_store_dword v26, v110, s[0:1]
	global_store_dword v26, v70, s[4:5]
	v_add_u32_e32 v26, 0x800, v26
	v_lshlrev_b32_e32 v171, 16, v171
	v_lshlrev_b32_e32 v172, 16, v172
	v_lshlrev_b32_e32 v170, 16, v170
	v_mul_f32_e32 v170, v16, v170
	v_fmac_f32_e32 v170, v14, v171
	v_fmac_f32_e32 v170, v17, v172
	v_add_f32_e32 v170, v12, v170
	v_fma_f32 v27, v46, v8, v24
	v_mul_f32_e32 v70, v27, v170
	v_lshlrev_b32_e32 v176, 16, v176
	v_mul_f32_e32 v84, 0xbfb8aa3b, v176
	v_exp_f32_e32 v84, v84
	s_nop 0
	v_add_f32_e32 v84, 1.0, v84
	v_div_scale_f32 v71, s[28:29], v84, v84, v176
	v_rcp_f32_e32 v82, v71
	s_nop 0
	v_fma_f32 v92, -v71, v82, 1.0
	v_fmac_f32_e32 v82, v92, v82
	v_div_scale_f32 v88, vcc, v176, v84, v176
	v_mul_f32_e32 v90, v88, v82
	v_fma_f32 v92, -v71, v90, v88
	v_fmac_f32_e32 v90, v92, v82
	v_fma_f32 v71, -v71, v90, v88
	v_div_fmas_f32 v71, v71, v82, v90
	v_div_fixup_f32 v176, v71, v84, v176
	v_mul_f32_e32 v70, v70, v176
	v_lshlrev_b32_e32 v174, 16, v174
	v_lshlrev_b32_e32 v175, 16, v175
	v_lshlrev_b32_e32 v173, 16, v173
	v_mul_f32_e32 v173, v16, v173
	v_fmac_f32_e32 v173, v14, v174
	v_fmac_f32_e32 v173, v17, v175
	v_add_f32_e32 v173, v12, v173
	v_fma_f32 v27, v48, v8, v25
	v_mul_f32_e32 v110, v27, v173
	v_lshlrev_b32_e32 v177, 16, v177
	v_mul_f32_e32 v84, 0xbfb8aa3b, v177
	v_exp_f32_e32 v84, v84
	s_nop 0
	v_add_f32_e32 v84, 1.0, v84
	v_div_scale_f32 v71, s[28:29], v84, v84, v177
	v_rcp_f32_e32 v82, v71
	s_nop 0
	v_fma_f32 v92, -v71, v82, 1.0
	v_fmac_f32_e32 v82, v92, v82
	v_div_scale_f32 v88, vcc, v177, v84, v177
	v_mul_f32_e32 v90, v88, v82
	v_fma_f32 v92, -v71, v90, v88
	v_fmac_f32_e32 v90, v92, v82
	v_fma_f32 v71, -v71, v90, v88
	v_div_fmas_f32 v71, v71, v82, v90
	v_div_fixup_f32 v177, v71, v84, v177
	v_mul_f32_e32 v110, v110, v177
	v_cvt_pk_bf16_f32 v70, v70, v110
	v_perm_b32 v110, v70, v207, s98
	v_perm_b32 v70, v70, v207, s99
	global_store_dword v26, v110, s[0:1]
	global_store_dword v26, v70, s[4:5]
	v_add_u32_e32 v26, 0x800, v26
	v_lshlrev_b32_e32 v179, 16, v179
	v_lshlrev_b32_e32 v180, 16, v180
	v_lshlrev_b32_e32 v178, 16, v178
	v_mul_f32_e32 v178, v16, v178
	v_fmac_f32_e32 v178, v14, v179
	v_fmac_f32_e32 v178, v17, v180
	v_add_f32_e32 v178, v12, v178
	v_fma_f32 v27, v51, v8, v18
	v_mul_f32_e32 v70, v27, v178
	v_lshlrev_b32_e32 v184, 16, v184
	v_mul_f32_e32 v84, 0xbfb8aa3b, v184
	v_exp_f32_e32 v84, v84
	s_nop 0
	v_add_f32_e32 v84, 1.0, v84
	v_div_scale_f32 v71, s[28:29], v84, v84, v184
	v_rcp_f32_e32 v82, v71
	s_nop 0
	v_fma_f32 v92, -v71, v82, 1.0
	v_fmac_f32_e32 v82, v92, v82
	v_div_scale_f32 v88, vcc, v184, v84, v184
	v_mul_f32_e32 v90, v88, v82
	v_fma_f32 v92, -v71, v90, v88
	v_fmac_f32_e32 v90, v92, v82
	v_fma_f32 v71, -v71, v90, v88
	v_div_fmas_f32 v71, v71, v82, v90
	v_div_fixup_f32 v184, v71, v84, v184
	v_mul_f32_e32 v70, v70, v184
	v_lshlrev_b32_e32 v182, 16, v182
	v_lshlrev_b32_e32 v183, 16, v183
	v_lshlrev_b32_e32 v181, 16, v181
	v_mul_f32_e32 v181, v16, v181
	v_fmac_f32_e32 v181, v14, v182
	v_fmac_f32_e32 v181, v17, v183
	v_add_f32_e32 v181, v12, v181
	v_fma_f32 v27, v53, v8, v19
	v_mul_f32_e32 v110, v27, v181
	v_lshlrev_b32_e32 v185, 16, v185
	v_mul_f32_e32 v84, 0xbfb8aa3b, v185
	v_exp_f32_e32 v84, v84
	s_nop 0
	v_add_f32_e32 v84, 1.0, v84
	v_div_scale_f32 v71, s[28:29], v84, v84, v185
	v_rcp_f32_e32 v82, v71
	s_nop 0
	v_fma_f32 v92, -v71, v82, 1.0
	v_fmac_f32_e32 v82, v92, v82
	v_div_scale_f32 v88, vcc, v185, v84, v185
	v_mul_f32_e32 v90, v88, v82
	v_fma_f32 v92, -v71, v90, v88
	v_fmac_f32_e32 v90, v92, v82
	v_fma_f32 v71, -v71, v90, v88
	v_div_fmas_f32 v71, v71, v82, v90
	v_div_fixup_f32 v185, v71, v84, v185
	v_mul_f32_e32 v110, v110, v185
	v_cvt_pk_bf16_f32 v70, v70, v110
	v_perm_b32 v110, v70, v208, s98
	v_perm_b32 v70, v70, v208, s99
	global_store_dword v26, v110, s[0:1]
	global_store_dword v26, v70, s[4:5]
	v_add_u32_e32 v26, 0x800, v26
	v_lshlrev_b32_e32 v187, 16, v187
	v_lshlrev_b32_e32 v188, 16, v188
	v_lshlrev_b32_e32 v186, 16, v186
	v_mul_f32_e32 v186, v16, v186
	v_fmac_f32_e32 v186, v14, v187
	v_fmac_f32_e32 v186, v17, v188
	v_add_f32_e32 v186, v12, v186
	v_fma_f32 v27, v50, v8, v20
	v_mul_f32_e32 v70, v27, v186
	v_lshlrev_b32_e32 v192, 16, v192
	v_mul_f32_e32 v84, 0xbfb8aa3b, v192
	v_exp_f32_e32 v84, v84
	s_nop 0
	v_add_f32_e32 v84, 1.0, v84
	v_div_scale_f32 v71, s[28:29], v84, v84, v192
	v_rcp_f32_e32 v82, v71
	s_nop 0
	v_fma_f32 v92, -v71, v82, 1.0
	v_fmac_f32_e32 v82, v92, v82
	v_div_scale_f32 v88, vcc, v192, v84, v192
	v_mul_f32_e32 v90, v88, v82
	v_fma_f32 v92, -v71, v90, v88
	v_fmac_f32_e32 v90, v92, v82
	v_fma_f32 v71, -v71, v90, v88
	v_div_fmas_f32 v71, v71, v82, v90
	v_div_fixup_f32 v192, v71, v84, v192
	v_mul_f32_e32 v70, v70, v192
	v_lshlrev_b32_e32 v190, 16, v190
	v_lshlrev_b32_e32 v191, 16, v191
	v_lshlrev_b32_e32 v189, 16, v189
	v_mul_f32_e32 v189, v16, v189
	v_fmac_f32_e32 v189, v14, v190
	v_fmac_f32_e32 v189, v17, v191
	v_add_f32_e32 v189, v12, v189
	v_fma_f32 v27, v52, v8, v21
	v_mul_f32_e32 v110, v27, v189
	v_lshlrev_b32_e32 v193, 16, v193
	v_mul_f32_e32 v84, 0xbfb8aa3b, v193
	v_exp_f32_e32 v84, v84
	s_nop 0
	v_add_f32_e32 v84, 1.0, v84
	v_div_scale_f32 v71, s[28:29], v84, v84, v193
	v_rcp_f32_e32 v82, v71
	s_nop 0
	v_fma_f32 v92, -v71, v82, 1.0
	v_fmac_f32_e32 v82, v92, v82
	v_div_scale_f32 v88, vcc, v193, v84, v193
	v_mul_f32_e32 v90, v88, v82
	v_fma_f32 v92, -v71, v90, v88
	v_fmac_f32_e32 v90, v92, v82
	v_fma_f32 v71, -v71, v90, v88
	v_div_fmas_f32 v71, v71, v82, v90
	v_div_fixup_f32 v193, v71, v84, v193
	v_mul_f32_e32 v110, v110, v193
	v_cvt_pk_bf16_f32 v70, v70, v110
	v_perm_b32 v110, v70, v209, s98
	v_perm_b32 v70, v70, v209, s99
	global_store_dword v26, v110, s[0:1]
	global_store_dword v26, v70, s[4:5]
	s_waitcnt vmcnt(24)
	v_add_u32_e32 v26, 0x800, v26
	v_lshlrev_b32_e32 v195, 16, v195
	v_lshlrev_b32_e32 v196, 16, v196
	v_lshlrev_b32_e32 v194, 16, v194
	v_mul_f32_e32 v194, v16, v194
	v_fmac_f32_e32 v194, v14, v195
	v_fmac_f32_e32 v194, v17, v196
	v_add_f32_e32 v194, v12, v194
	v_fma_f32 v27, v55, v8, v4
	v_mul_f32_e32 v70, v27, v194
	v_lshlrev_b32_e32 v223, 16, v223
	v_mul_f32_e32 v84, 0xbfb8aa3b, v223
	v_exp_f32_e32 v84, v84
	s_nop 0
	v_add_f32_e32 v84, 1.0, v84
	v_div_scale_f32 v71, s[28:29], v84, v84, v223
	v_rcp_f32_e32 v82, v71
	s_nop 0
	v_fma_f32 v92, -v71, v82, 1.0
	v_fmac_f32_e32 v82, v92, v82
	v_div_scale_f32 v88, vcc, v223, v84, v223
	v_mul_f32_e32 v90, v88, v82
	v_fma_f32 v92, -v71, v90, v88
	v_fmac_f32_e32 v90, v92, v82
	v_fma_f32 v71, -v71, v90, v88
	v_div_fmas_f32 v71, v71, v82, v90
	v_div_fixup_f32 v223, v71, v84, v223
	v_mul_f32_e32 v70, v70, v223
	v_lshlrev_b32_e32 v221, 16, v221
	v_lshlrev_b32_e32 v222, 16, v222
	v_lshlrev_b32_e32 v197, 16, v197
	v_mul_f32_e32 v197, v16, v197
	v_fmac_f32_e32 v197, v14, v221
	v_fmac_f32_e32 v197, v17, v222
	v_add_f32_e32 v197, v12, v197
	v_fma_f32 v27, v57, v8, v5
	v_mul_f32_e32 v110, v27, v197
	v_lshlrev_b32_e32 v224, 16, v224
	v_mul_f32_e32 v84, 0xbfb8aa3b, v224
	v_exp_f32_e32 v84, v84
	s_nop 0
	v_add_f32_e32 v84, 1.0, v84
	v_div_scale_f32 v71, s[28:29], v84, v84, v224
	v_rcp_f32_e32 v82, v71
	s_nop 0
	v_fma_f32 v92, -v71, v82, 1.0
	v_fmac_f32_e32 v82, v92, v82
	v_div_scale_f32 v88, vcc, v224, v84, v224
	v_mul_f32_e32 v90, v88, v82
	v_fma_f32 v92, -v71, v90, v88
	v_fmac_f32_e32 v90, v92, v82
	v_fma_f32 v71, -v71, v90, v88
	v_div_fmas_f32 v71, v71, v82, v90
	v_div_fixup_f32 v224, v71, v84, v224
	v_mul_f32_e32 v110, v110, v224
	v_cvt_pk_bf16_f32 v70, v70, v110
	v_perm_b32 v110, v70, v210, s98
	v_perm_b32 v70, v70, v210, s99
	global_store_dword v26, v110, s[0:1]
	global_store_dword v26, v70, s[4:5]
	v_add_u32_e32 v26, 0x800, v26
	v_lshlrev_b32_e32 v226, 16, v226
	v_lshlrev_b32_e32 v227, 16, v227
	v_lshlrev_b32_e32 v225, 16, v225
	v_mul_f32_e32 v225, v16, v225
	v_fmac_f32_e32 v225, v14, v226
	v_fmac_f32_e32 v225, v17, v227
	v_add_f32_e32 v225, v12, v225
	v_fma_f32 v27, v54, v8, v6
	v_mul_f32_e32 v70, v27, v225
	v_lshlrev_b32_e32 v231, 16, v231
	v_mul_f32_e32 v84, 0xbfb8aa3b, v231
	v_exp_f32_e32 v84, v84
	s_nop 0
	v_add_f32_e32 v84, 1.0, v84
	v_div_scale_f32 v71, s[28:29], v84, v84, v231
	v_rcp_f32_e32 v82, v71
	s_nop 0
	v_fma_f32 v92, -v71, v82, 1.0
	v_fmac_f32_e32 v82, v92, v82
	v_div_scale_f32 v88, vcc, v231, v84, v231
	v_mul_f32_e32 v90, v88, v82
	v_fma_f32 v92, -v71, v90, v88
	v_fmac_f32_e32 v90, v92, v82
	v_fma_f32 v71, -v71, v90, v88
	v_div_fmas_f32 v71, v71, v82, v90
	v_div_fixup_f32 v231, v71, v84, v231
	v_mul_f32_e32 v70, v70, v231
	v_lshlrev_b32_e32 v229, 16, v229
	v_lshlrev_b32_e32 v230, 16, v230
	v_lshlrev_b32_e32 v228, 16, v228
	v_mul_f32_e32 v228, v16, v228
	v_fmac_f32_e32 v228, v14, v229
	v_fmac_f32_e32 v228, v17, v230
	v_add_f32_e32 v228, v12, v228
	v_fma_f32 v27, v56, v8, v7
	v_mul_f32_e32 v110, v27, v228
	v_lshlrev_b32_e32 v232, 16, v232
	v_mul_f32_e32 v84, 0xbfb8aa3b, v232
	v_exp_f32_e32 v84, v84
	s_nop 0
	v_add_f32_e32 v84, 1.0, v84
	v_div_scale_f32 v71, s[28:29], v84, v84, v232
	v_rcp_f32_e32 v82, v71
	s_nop 0
	v_fma_f32 v92, -v71, v82, 1.0
	v_fmac_f32_e32 v82, v92, v82
	v_div_scale_f32 v88, vcc, v232, v84, v232
	v_mul_f32_e32 v90, v88, v82
	v_fma_f32 v92, -v71, v90, v88
	v_fmac_f32_e32 v90, v92, v82
	v_fma_f32 v71, -v71, v90, v88
	v_div_fmas_f32 v71, v71, v82, v90
	v_div_fixup_f32 v232, v71, v84, v232
	v_mul_f32_e32 v110, v110, v232
	v_cvt_pk_bf16_f32 v70, v70, v110
	v_perm_b32 v110, v70, v211, s98
	v_perm_b32 v70, v70, v211, s99
	global_store_dword v26, v110, s[0:1]
	global_store_dword v26, v70, s[4:5]
	v_add_u32_e32 v26, 0x800, v26
	v_lshlrev_b32_e32 v234, 16, v234
	v_lshlrev_b32_e32 v235, 16, v235
	v_lshlrev_b32_e32 v233, 16, v233
	v_mul_f32_e32 v233, v16, v233
	v_fmac_f32_e32 v233, v14, v234
	v_fmac_f32_e32 v233, v17, v235
	v_add_f32_e32 v233, v12, v233
	v_fma_f32 v27, v59, v8, v0
	v_mul_f32_e32 v70, v27, v233
	v_lshlrev_b32_e32 v239, 16, v239
	v_mul_f32_e32 v84, 0xbfb8aa3b, v239
	v_exp_f32_e32 v84, v84
	s_nop 0
	v_add_f32_e32 v84, 1.0, v84
	v_div_scale_f32 v71, s[28:29], v84, v84, v239
	v_rcp_f32_e32 v82, v71
	s_nop 0
	v_fma_f32 v92, -v71, v82, 1.0
	v_fmac_f32_e32 v82, v92, v82
	v_div_scale_f32 v88, vcc, v239, v84, v239
	v_mul_f32_e32 v90, v88, v82
	v_fma_f32 v92, -v71, v90, v88
	v_fmac_f32_e32 v90, v92, v82
	v_fma_f32 v71, -v71, v90, v88
	v_div_fmas_f32 v71, v71, v82, v90
	v_div_fixup_f32 v239, v71, v84, v239
	v_mul_f32_e32 v70, v70, v239
	v_lshlrev_b32_e32 v237, 16, v237
	v_lshlrev_b32_e32 v238, 16, v238
	v_lshlrev_b32_e32 v236, 16, v236
	v_mul_f32_e32 v236, v16, v236
	v_fmac_f32_e32 v236, v14, v237
	v_fmac_f32_e32 v236, v17, v238
	v_add_f32_e32 v236, v12, v236
	v_fma_f32 v27, v61, v8, v1
	v_mul_f32_e32 v110, v27, v236
	v_lshlrev_b32_e32 v240, 16, v240
	v_mul_f32_e32 v84, 0xbfb8aa3b, v240
	v_exp_f32_e32 v84, v84
	s_nop 0
	v_add_f32_e32 v84, 1.0, v84
	v_div_scale_f32 v71, s[28:29], v84, v84, v240
	v_rcp_f32_e32 v82, v71
	s_nop 0
	v_fma_f32 v92, -v71, v82, 1.0
	v_fmac_f32_e32 v82, v92, v82
	v_div_scale_f32 v88, vcc, v240, v84, v240
	v_mul_f32_e32 v90, v88, v82
	v_fma_f32 v92, -v71, v90, v88
	v_fmac_f32_e32 v90, v92, v82
	v_fma_f32 v71, -v71, v90, v88
	v_div_fmas_f32 v71, v71, v82, v90
	v_div_fixup_f32 v240, v71, v84, v240
	v_mul_f32_e32 v110, v110, v240
	v_cvt_pk_bf16_f32 v70, v70, v110
	v_perm_b32 v110, v70, v212, s98
	v_perm_b32 v70, v70, v212, s99
	global_store_dword v26, v110, s[0:1]
	global_store_dword v26, v70, s[4:5]
	v_add_u32_e32 v26, 0x800, v26
	v_lshlrev_b32_e32 v242, 16, v242
	v_lshlrev_b32_e32 v243, 16, v243
	v_lshlrev_b32_e32 v241, 16, v241
	v_mul_f32_e32 v241, v16, v241
	v_mul_f32_e32 v243, v255, v243
	v_fmac_f32_e32 v241, v14, v242
	v_fmac_f32_e32 v241, v17, v243
	v_add_f32_e32 v241, v12, v241
	v_fma_f32 v27, v58, v8, v2
	v_mul_f32_e32 v70, v27, v241
	v_lshlrev_b32_e32 v247, 16, v247
	v_mul_f32_e32 v84, 0xbfb8aa3b, v247
	v_exp_f32_e32 v84, v84
	s_nop 0
	v_add_f32_e32 v84, 1.0, v84
	v_div_scale_f32 v71, s[28:29], v84, v84, v247
	v_rcp_f32_e32 v82, v71
	s_nop 0
	v_fma_f32 v92, -v71, v82, 1.0
	v_fmac_f32_e32 v82, v92, v82
	v_div_scale_f32 v88, vcc, v247, v84, v247
	v_mul_f32_e32 v90, v88, v82
	v_fma_f32 v92, -v71, v90, v88
	v_fmac_f32_e32 v90, v92, v82
	v_fma_f32 v71, -v71, v90, v88
	v_div_fmas_f32 v71, v71, v82, v90
	v_div_fixup_f32 v247, v71, v84, v247
	v_mul_f32_e32 v70, v70, v247
	v_lshlrev_b32_e32 v245, 16, v245
	v_lshlrev_b32_e32 v246, 16, v246
	v_lshlrev_b32_e32 v244, 16, v244
	v_mul_f32_e32 v244, v16, v244
	v_mul_f32_e32 v246, v255, v246
	v_fmac_f32_e32 v244, v14, v245
	v_fmac_f32_e32 v244, v17, v246
	v_add_f32_e32 v244, v12, v244
	v_fma_f32 v27, v60, v8, v3
	v_mul_f32_e32 v110, v27, v244
	v_lshlrev_b32_e32 v248, 16, v248
	v_mul_f32_e32 v84, 0xbfb8aa3b, v248
	v_exp_f32_e32 v84, v84
	s_nop 0
	v_add_f32_e32 v84, 1.0, v84
	v_div_scale_f32 v71, s[28:29], v84, v84, v248
	v_rcp_f32_e32 v82, v71
	s_nop 0
	v_fma_f32 v92, -v71, v82, 1.0
	v_fmac_f32_e32 v82, v92, v82
	v_div_scale_f32 v88, vcc, v248, v84, v248
	v_mul_f32_e32 v90, v88, v82
	v_fma_f32 v92, -v71, v90, v88
	v_fmac_f32_e32 v90, v92, v82
	v_fma_f32 v71, -v71, v90, v88
	v_div_fmas_f32 v71, v71, v82, v90
	v_div_fixup_f32 v248, v71, v84, v248
	v_mul_f32_e32 v110, v110, v248
	v_cvt_pk_bf16_f32 v70, v70, v110
	v_perm_b32 v110, v70, v213, s98
	v_perm_b32 v70, v70, v213, s99
	global_store_dword v26, v110, s[0:1]
	global_store_dword v26, v70, s[4:5]

.LBB0_619:
	v_and_b32_e32 v235, 31, v214
	v_bfe_u32 v236, v214, 5, 1
	v_lshrrev_b32_e32 v237, 6, v214
	v_lshlrev_b32_e32 v230, 16, v235
	v_lshl_or_b32 v230, v237, 7, v230
	v_lshl_or_b32 v230, v236, 4, v230
	v_and_b32_e32 v238, 3, v235
	v_lshrrev_b32_e32 v235, 2, v235
	v_lshlrev_b32_e32 v237, 12, v237
	v_lshl_or_b32 v237, v236, 9, v237
	v_lshl_or_b32 v237, v238, 2, v237
	v_add_u32_e32 v237, 16, v237
	v_lshlrev_b32_e32 v236, 1, v236
	v_xor_b32_e32 v235, v235, v236
	v_lshl_add_u32 v231, v235, 4, v237
	v_xor_b32_e32 v236, 1, v235
	v_lshl_add_u32 v232, v236, 4, v237
	v_xor_b32_e32 v236, 4, v235
	v_lshl_add_u32 v233, v236, 4, v237
	v_xor_b32_e32 v236, 5, v235
	v_lshl_add_u32 v234, v236, 4, v237
	s_lshl_b32 s0, s2, 8
	s_and_b32 s19, s0, 0x3f00
	s_lshl_b32 s0, s2, 2
	s_and_b32 s21, s9, 0xffffff00
	s_and_b32 s20, s0, 0xffffff00
	s_lshl_b32 s22, s19, 9
	s_lshl_b32 s0, s19, 10
	v_mov_b32_e32 v35, v221
	s_add_u32 s0, s7, s0
	s_addc_u32 s1, s8, 0
	v_ashrrev_i32_e32 v32, 3, v35
	s_mul_i32 s4, s20, 0xc00
	v_lshlrev_b32_e32 v0, 3, v35
	s_mul_hi_i32 s5, s20, 0xc00
	s_add_u32 s4, s3, s4
	v_and_b32_e32 v34, 56, v0
	v_add_u32_e32 v8, 64, v32
	v_add_u32_e32 v22, 0x80, v32
	v_add_u32_e32 v30, 0xc0, v32
	s_addc_u32 s5, s6, s5
	v_lshlrev_b32_e32 v208, 1, v34
	v_ashrrev_i32_e32 v33, 31, v32
	v_ashrrev_i32_e32 v9, 31, v8
	v_ashrrev_i32_e32 v23, 31, v22
	v_ashrrev_i32_e32 v31, 31, v30
	v_lshl_add_u64 v[20:21], s[0:1], 0, v[208:209]
	v_lshl_add_u64 v[28:29], s[4:5], 0, v[208:209]
	v_lshlrev_b64 v[128:129], 10, v[32:33]
	v_lshlrev_b64 v[130:131], 10, v[8:9]
	v_lshlrev_b64 v[132:133], 10, v[22:23]
	v_lshlrev_b64 v[134:135], 10, v[30:31]
	v_lshl_add_u64 v[0:1], v[20:21], 0, v[128:129]
	v_mad_i64_i32 v[4:5], s[0:1], v32, s11, v[28:29]
	v_lshl_add_u64 v[10:11], v[20:21], 0, v[130:131]
	v_mad_i64_i32 v[12:13], s[0:1], v8, s11, v[28:29]
	v_lshl_add_u64 v[16:17], v[20:21], 0, v[132:133]
	v_mad_i64_i32 v[24:25], s[0:1], v22, s11, v[28:29]
	v_lshl_add_u64 v[20:21], v[20:21], 0, v[134:135]
	s_barrier
	global_load_dwordx4 v[0:3], v[0:1], off
	s_nop 0
	global_load_dwordx4 v[4:7], v[4:5], off
	s_nop 0
	global_load_dwordx4 v[8:11], v[10:11], off
	s_nop 0
	global_load_dwordx4 v[12:15], v[12:13], off
	v_mad_i64_i32 v[28:29], s[0:1], v30, s11, v[28:29]
	global_load_dwordx4 v[16:19], v[16:17], off
	s_nop 0
	global_load_dwordx4 v[20:23], v[20:21], off
	s_nop 0
	global_load_dwordx4 v[24:27], v[24:25], off
	v_lshrrev_b32_e32 v33, 5, v35
	global_load_dwordx4 v[28:31], v[28:29], off
	v_bfe_u32 v38, v35, 1, 3
	v_lshrrev_b32_e32 v40, 1, v32
	v_bitop3_b32 v33, v33, v38, 1 bitop3:0x6c
	v_xor_b32_e32 v40, v40, v35
	v_lshlrev_b32_e32 v39, 7, v32
	v_lshlrev_b32_e32 v139, 4, v33
	v_lshlrev_b32_e32 v33, 4, v40
	v_and_or_b32 v33, v33, s12, v39
	s_mul_hi_i32 s0, s21, 0xc00
	s_mulk_i32 s21, 0xc00
	v_bfe_u32 v212, v35, 5, 1
	v_add_u32_e32 v140, 16, v33
	v_mov_b32_e32 v36, s21
	v_mov_b32_e32 v37, s0
	v_ashrrev_i32_e32 v211, 8, v35
	v_and_b32_e32 v210, 31, v35
	v_bfe_u32 v213, v35, 6, 2
	v_bitop3_b32 v41, v212, v38, 2 bitop3:0x36
	v_bitop3_b32 v42, v212, v38, 4 bitop3:0x36
	v_lshlrev_b32_e32 v166, 14, v211
	v_lshlrev_b32_e32 v164, 7, v210
	v_lshlrev_b32_e32 v165, 13, v213
	v_lshlrev_b32_e32 v138, 4, v41
	v_lshlrev_b32_e32 v144, 4, v42
	s_lshl_b32 s21, s22, 1
	v_lshlrev_b32_e32 v208, 1, v34
	s_mov_b32 s22, 64
	s_mov_b32 s23, 0
	s_mov_b32 s4, 0
	v_mov_b32_e32 v33, v209
	v_mov_b32_e32 v34, v209
	v_mov_b32_e32 v39, v209
	v_mov_b32_e32 v40, v209
	v_mov_b32_e32 v41, v209
	v_mov_b32_e32 v42, v209
	v_mov_b32_e32 v43, v209
	s_waitcnt vmcnt(7)
	ds_write_b128 v140, v[0:3]
	s_waitcnt vmcnt(5)
	ds_write_b128 v140, v[8:11] offset:8192
	s_waitcnt vmcnt(3)
	ds_write_b128 v140, v[16:19] offset:16384
	s_waitcnt vmcnt(2)
	ds_write_b128 v140, v[20:23] offset:24576
	ds_write_b128 v140, v[4:7] offset:32768
	ds_write_b128 v140, v[12:15] offset:40960
	s_waitcnt vmcnt(1)
	ds_write_b128 v140, v[24:27] offset:49152
	s_waitcnt vmcnt(0)
	ds_write_b128 v140, v[28:31] offset:57344
	v_bitop3_b32 v0, v212, v38, 6 bitop3:0x36
	v_lshlrev_b32_e32 v167, 4, v0
	v_mad_i64_i32 v[0:1], s[0:1], v32, s11, v[36:37]
	v_and_b32_e32 v2, 7, v35
	v_lshl_or_b32 v0, v2, 4, v0
	v_lshl_add_u64 v[136:137], s[86:87], 0, v[0:1]
	s_mov_b64 s[0:1], 0
	v_mov_b32_e32 v0, v209
	v_mov_b32_e32 v1, v209
	v_mov_b32_e32 v2, v209
	v_mov_b32_e32 v3, v209
	v_mov_b32_e32 v4, v209
	v_mov_b32_e32 v5, v209
	v_mov_b32_e32 v6, v209
	v_mov_b32_e32 v7, v209
	v_mov_b32_e32 v8, v209
	v_mov_b32_e32 v9, v209
	v_mov_b32_e32 v10, v209
	v_mov_b32_e32 v11, v209
	v_mov_b32_e32 v12, v209
	v_mov_b32_e32 v13, v209
	v_mov_b32_e32 v14, v209
	v_mov_b32_e32 v15, v209
	v_mov_b32_e32 v16, v209
	v_mov_b32_e32 v17, v209
	v_mov_b32_e32 v18, v209
	v_mov_b32_e32 v19, v209
	v_mov_b32_e32 v20, v209
	v_mov_b32_e32 v21, v209
	v_mov_b32_e32 v22, v209
	v_mov_b32_e32 v23, v209
	v_mov_b32_e32 v24, v209
	v_mov_b32_e32 v25, v209
	v_mov_b32_e32 v26, v209
	v_mov_b32_e32 v27, v209
	v_mov_b32_e32 v28, v209
	v_mov_b32_e32 v29, v209
	v_mov_b32_e32 v30, v209
	v_mov_b32_e32 v31, v209
	v_mov_b32_e32 v32, v209
	v_mov_b32_e32 v35, v209
	v_mov_b32_e32 v36, v209
	v_mov_b32_e32 v37, v209
	v_mov_b32_e32 v38, v209
	v_mov_b32_e32 v44, v209
	v_mov_b32_e32 v45, v209
	v_mov_b32_e32 v46, v209
	v_mov_b32_e32 v47, v209
	v_mov_b32_e32 v48, v209
	v_mov_b32_e32 v49, v209
	v_mov_b32_e32 v50, v209
	v_mov_b32_e32 v51, v209
	v_mov_b32_e32 v52, v209
	v_mov_b32_e32 v53, v209
	v_mov_b32_e32 v54, v209
	v_mov_b32_e32 v55, v209
	v_mov_b32_e32 v56, v209
	v_mov_b32_e32 v57, v209
	v_mov_b32_e32 v58, v209
	v_mov_b32_e32 v59, v209
	v_mov_b32_e32 v60, v209
	v_mov_b32_e32 v61, v209
	v_mov_b32_e32 v62, v209
	v_mov_b32_e32 v63, v209
	v_mov_b32_e32 v64, v209
	v_mov_b32_e32 v65, v209
	v_mov_b32_e32 v66, v209
	v_mov_b32_e32 v67, v209
	v_mov_b32_e32 v68, v209
	v_mov_b32_e32 v69, v209
	v_mov_b32_e32 v70, v209
	v_mov_b32_e32 v71, v209
	v_mov_b32_e32 v72, v209
	v_mov_b32_e32 v73, v209
	v_mov_b32_e32 v74, v209
	v_mov_b32_e32 v75, v209
	v_mov_b32_e32 v76, v209
	v_mov_b32_e32 v77, v209
	v_mov_b32_e32 v78, v209
	v_mov_b32_e32 v79, v209
	v_mov_b32_e32 v80, v209
	v_mov_b32_e32 v81, v209
	v_mov_b32_e32 v82, v209
	v_mov_b32_e32 v83, v209
	v_mov_b32_e32 v84, v209
	v_mov_b32_e32 v85, v209
	v_mov_b32_e32 v86, v209
	v_mov_b32_e32 v87, v209
	v_mov_b32_e32 v88, v209
	v_mov_b32_e32 v89, v209
	v_mov_b32_e32 v90, v209
	v_mov_b32_e32 v91, v209
	v_mov_b32_e32 v92, v209
	v_mov_b32_e32 v93, v209
	v_mov_b32_e32 v94, v209
	v_mov_b32_e32 v95, v209
	v_mov_b32_e32 v96, v209
	v_mov_b32_e32 v97, v209
	v_mov_b32_e32 v98, v209
	v_mov_b32_e32 v99, v209
	v_mov_b32_e32 v100, v209
	v_mov_b32_e32 v101, v209
	v_mov_b32_e32 v102, v209
	v_mov_b32_e32 v103, v209
	v_mov_b32_e32 v104, v209
	v_mov_b32_e32 v105, v209
	v_mov_b32_e32 v106, v209
	v_mov_b32_e32 v107, v209
	v_mov_b32_e32 v108, v209
	v_mov_b32_e32 v109, v209
	v_mov_b32_e32 v110, v209
	v_mov_b32_e32 v111, v209
	v_mov_b32_e32 v112, v209
	v_mov_b32_e32 v113, v209
	v_mov_b32_e32 v114, v209
	v_mov_b32_e32 v115, v209
	v_mov_b32_e32 v116, v209
	v_mov_b32_e32 v117, v209
	v_mov_b32_e32 v118, v209
	v_mov_b32_e32 v119, v209
	v_mov_b32_e32 v120, v209
	v_mov_b32_e32 v121, v209
	v_mov_b32_e32 v122, v209
	v_mov_b32_e32 v123, v209
	v_mov_b32_e32 v124, v209
	v_mov_b32_e32 v125, v209
	v_mov_b32_e32 v126, v209
	v_mov_b32_e32 v127, v209
	s_waitcnt lgkmcnt(0)
	s_barrier
.LBB0_620:
	s_add_i32 s24, s4, 1
	s_and_b32 s5, s24, 56
	s_cmp_eq_u32 s5, 8
	s_cselect_b32 s5, s13, 0x3000000
	s_add_u32 s5, s86, s5
	s_addc_u32 s25, s87, 0
	s_cmp_lt_u32 s4, 7
	s_cselect_b32 s4, s8, s25
	s_cselect_b32 s5, s7, s5
	s_and_b32 s25, s22, 0x1c0
	s_add_u32 s5, s5, s21
	s_addc_u32 s26, s4, 0
	s_lshl_b32 s4, s25, 1
	s_add_u32 s4, s5, s4
	s_addc_u32 s5, s26, 0
	s_and_b32 s25, s23, 0x10000
	s_add_i32 s25, s25, 16
	v_add_u32_e32 v141, s25, v139
	v_add3_u32 v142, v141, v166, v164
	v_add3_u32 v141, v141, v165, v164
	ds_read_b128 v[146:149], v142
	ds_read_b128 v[150:153], v141 offset:32768
	ds_read_b128 v[154:157], v142 offset:4096
	ds_read_b128 v[158:161], v141 offset:36864
	s_waitcnt lgkmcnt(2)
	v_mfma_f32_32x32x16_bf16 v[112:127], v[146:149], v[150:153], v[112:127]
	v_add_u32_e32 v141, s25, v138
	s_add_i32 s23, s23, 0x10000
	s_waitcnt lgkmcnt(0)
	v_mfma_f32_32x32x16_bf16 v[96:111], v[146:149], v[158:161], v[96:111]
	v_mfma_f32_32x32x16_bf16 v[80:95], v[154:157], v[150:153], v[80:95]
	v_mfma_f32_32x32x16_bf16 v[64:79], v[154:157], v[158:161], v[64:79]
	ds_read_b128 v[146:149], v142 offset:8192
	ds_read_b128 v[154:157], v142 offset:12288
	v_add3_u32 v142, v141, v166, v164
	v_add3_u32 v141, v141, v165, v164
	s_waitcnt lgkmcnt(1)
	v_mfma_f32_32x32x16_bf16 v[48:63], v[146:149], v[150:153], v[48:63]
	v_mfma_f32_32x32x16_bf16 v[32:47], v[146:149], v[158:161], v[32:47]
	s_waitcnt lgkmcnt(0)
	v_mfma_f32_32x32x16_bf16 v[16:31], v[154:157], v[150:153], v[16:31]
	v_mfma_f32_32x32x16_bf16 v[0:15], v[154:157], v[158:161], v[0:15]
	ds_read_b128 v[146:149], v142
	ds_read_b128 v[150:153], v141 offset:32768
	ds_read_b128 v[154:157], v142 offset:4096
	ds_read_b128 v[158:161], v141 offset:36864
	v_add_u32_e32 v141, s25, v144
	s_waitcnt lgkmcnt(2)
	v_mfma_f32_32x32x16_bf16 v[112:127], v[146:149], v[150:153], v[112:127]
	s_waitcnt lgkmcnt(0)
	v_mfma_f32_32x32x16_bf16 v[96:111], v[146:149], v[158:161], v[96:111]
	v_mfma_f32_32x32x16_bf16 v[80:95], v[154:157], v[150:153], v[80:95]
	v_mfma_f32_32x32x16_bf16 v[64:79], v[154:157], v[158:161], v[64:79]
	ds_read_b128 v[146:149], v142 offset:8192
	ds_read_b128 v[154:157], v142 offset:12288
	v_add3_u32 v142, v141, v166, v164
	v_add3_u32 v141, v141, v165, v164
	s_waitcnt lgkmcnt(1)
	v_mfma_f32_32x32x16_bf16 v[48:63], v[146:149], v[150:153], v[48:63]
	v_mfma_f32_32x32x16_bf16 v[32:47], v[146:149], v[158:161], v[32:47]
	s_waitcnt lgkmcnt(0)
	v_mfma_f32_32x32x16_bf16 v[16:31], v[154:157], v[150:153], v[16:31]
	v_mfma_f32_32x32x16_bf16 v[0:15], v[154:157], v[158:161], v[0:15]
	ds_read_b128 v[146:149], v142
	ds_read_b128 v[150:153], v141 offset:32768
	ds_read_b128 v[154:157], v142 offset:4096
	ds_read_b128 v[158:161], v141 offset:36864
	v_add_u32_e32 v141, s25, v167
	v_add3_u32 v145, v141, v166, v164
	v_add3_u32 v141, v141, v165, v164
	s_waitcnt lgkmcnt(2)
	v_mfma_f32_32x32x16_bf16 v[112:127], v[146:149], v[150:153], v[112:127]
	s_waitcnt lgkmcnt(0)
	v_mfma_f32_32x32x16_bf16 v[96:111], v[146:149], v[158:161], v[96:111]
	v_mfma_f32_32x32x16_bf16 v[80:95], v[154:157], v[150:153], v[80:95]
	v_mfma_f32_32x32x16_bf16 v[64:79], v[154:157], v[158:161], v[64:79]
	ds_read_b128 v[146:149], v142 offset:8192
	ds_read_b128 v[154:157], v142 offset:12288
	v_lshl_add_u64 v[142:143], v[136:137], 0, s[0:1]
	v_add_co_u32_e32 v162, vcc, s14, v142
	s_nop 1
	v_addc_co_u32_e32 v163, vcc, 0, v143, vcc
	v_add_co_u32_e32 v168, vcc, s15, v142
	s_waitcnt lgkmcnt(1)
	v_mfma_f32_32x32x16_bf16 v[48:63], v[146:149], v[150:153], v[48:63]
	v_addc_co_u32_e32 v169, vcc, 0, v143, vcc
	v_add_co_u32_e32 v172, vcc, s16, v142
	s_nop 1
	v_addc_co_u32_e32 v173, vcc, 0, v143, vcc
	v_mfma_f32_32x32x16_bf16 v[32:47], v[146:149], v[158:161], v[32:47]
	v_add_co_u32_e32 v142, vcc, s17, v142
	s_nop 1
	v_addc_co_u32_e32 v143, vcc, 0, v143, vcc
	s_waitcnt lgkmcnt(0)
	v_mfma_f32_32x32x16_bf16 v[16:31], v[154:157], v[150:153], v[16:31]
	v_mfma_f32_32x32x16_bf16 v[0:15], v[154:157], v[158:161], v[0:15]
	ds_read_b128 v[146:149], v145
	ds_read_b128 v[150:153], v141 offset:32768
	ds_read_b128 v[154:157], v145 offset:4096
	ds_read_b128 v[158:161], v141 offset:36864
	s_waitcnt lgkmcnt(2)
	v_mfma_f32_32x32x16_bf16 v[112:127], v[146:149], v[150:153], v[112:127]
	s_waitcnt lgkmcnt(0)
	v_mfma_f32_32x32x16_bf16 v[96:111], v[146:149], v[158:161], v[96:111]
	global_load_dwordx4 v[146:149], v[162:163], off offset:128
	s_nop 0
	global_load_dwordx4 v[168:171], v[168:169], off offset:128
	s_nop 0
	global_load_dwordx4 v[172:175], v[172:173], off offset:128
	s_nop 0
	global_load_dwordx4 v[176:179], v[142:143], off offset:128
	v_lshl_add_u64 v[142:143], s[4:5], 0, v[208:209]
	v_lshl_add_u64 v[162:163], v[142:143], 0, v[128:129]
	v_lshl_add_u64 v[188:189], v[142:143], 0, v[130:131]
	v_lshl_add_u64 v[192:193], v[142:143], 0, v[132:133]
	v_lshl_add_u64 v[142:143], v[142:143], 0, v[134:135]
	s_and_b32 s98, s24, 56
	s_cmp_eq_u32 s98, 8
	s_cselect_b64 vcc, -1, 0
	s_sub_i32 s98, s24, 8
	s_lshl_b32 s98, s98, 21
	s_lshl_b32 s99, s19, 2
	s_add_u32 s98, s98, s99
	s_add_u32 s98, s98, 0xa000000
	s_add_u32 s98, s86, s98
	s_addc_u32 s99, s87, 0
	s_and_b32 s5, s23, 0x10000
	v_mfma_f32_32x32x16_bf16 v[80:95], v[154:157], v[150:153], v[80:95]
	s_add_u32 s0, s0, 0x80
	s_addc_u32 s1, s1, 0
	s_add_i32 s22, s22, 64
	s_mov_b32 s4, s24
	v_add_u32_e32 v141, s5, v140
	s_cmpk_lg_i32 s0, 0xb80
	v_mfma_f32_32x32x16_bf16 v[64:79], v[154:157], v[158:161], v[64:79]
	ds_read_b128 v[154:157], v145 offset:8192
	ds_read_b128 v[180:183], v145 offset:12288
	s_cbranch_vccnz .Lyb_ld_L0
	global_load_dwordx4 v[184:187], v[162:163], off
	s_nop 0
	global_load_dwordx4 v[188:191], v[188:189], off
	s_nop 0
	global_load_dwordx4 v[192:195], v[192:193], off
	s_waitcnt lgkmcnt(1)
	v_mfma_f32_32x32x16_bf16 v[48:63], v[154:157], v[150:153], v[48:63]
	v_mfma_f32_32x32x16_bf16 v[32:47], v[154:157], v[158:161], v[32:47]
	global_load_dwordx4 v[154:157], v[142:143], off
	s_branch .Lyb_ld_done_L0
.Lyb_ld_L0:
	global_load_dwordx4 v[184:187], v230, s[98:99]
	global_load_dwordx4 v[188:191], v230, s[98:99] offset:32
	global_load_dwordx4 v[192:195], v230, s[98:99] offset:64
	s_waitcnt lgkmcnt(1)
	v_mfma_f32_32x32x16_bf16 v[48:63], v[154:157], v[150:153], v[48:63]
	v_mfma_f32_32x32x16_bf16 v[32:47], v[154:157], v[158:161], v[32:47]
	global_load_dwordx4 v[154:157], v230, s[98:99] offset:96
.Lyb_ld_done_L0:
	s_waitcnt vmcnt(7)
	ds_write_b128 v141, v[146:149] offset:32768
	s_waitcnt vmcnt(6)
	ds_write_b128 v141, v[168:171] offset:40960
	s_waitcnt vmcnt(5)
	ds_write_b128 v141, v[172:175] offset:49152
	s_waitcnt vmcnt(4)
	ds_write_b128 v141, v[176:179] offset:57344
	s_cbranch_vccnz .Lyb_wr_L0
	s_waitcnt vmcnt(3)
	ds_write_b128 v141, v[184:187]
	s_waitcnt vmcnt(2)
	ds_write_b128 v141, v[188:191] offset:8192
	s_waitcnt vmcnt(1)
	ds_write_b128 v141, v[192:195] offset:16384
	s_waitcnt vmcnt(0)
	ds_write_b128 v141, v[154:157] offset:24576
	s_branch .Lyb_wr_done_L0
.Lyb_wr_L0:
	v_add_u32_e32 v235, s5, v231
	v_add_u32_e32 v236, s5, v232
	v_add_u32_e32 v237, s5, v233
	v_add_u32_e32 v238, s5, v234
	s_waitcnt vmcnt(3)
	ds_write_b32 v235, v184
	ds_write_b32 v235, v185 offset:128
	ds_write_b32 v236, v186 offset:256
	ds_write_b32 v236, v187 offset:384
	s_waitcnt vmcnt(2)
	ds_write_b32 v237, v188 offset:1024
	ds_write_b32 v237, v189 offset:1152
	ds_write_b32 v238, v190 offset:1280
	ds_write_b32 v238, v191 offset:1408
	s_waitcnt vmcnt(1)
	ds_write_b32 v235, v192 offset:2048
	ds_write_b32 v235, v193 offset:2176
	ds_write_b32 v236, v194 offset:2304
	ds_write_b32 v236, v195 offset:2432
	s_waitcnt vmcnt(0)
	ds_write_b32 v237, v154 offset:3072
	ds_write_b32 v237, v155 offset:3200
	ds_write_b32 v238, v156 offset:3328
	ds_write_b32 v238, v157 offset:3456
.Lyb_wr_done_L0:
	s_waitcnt lgkmcnt(8)
	v_mfma_f32_32x32x16_bf16 v[16:31], v[180:183], v[150:153], v[16:31]
	s_waitcnt lgkmcnt(0)
	s_barrier
	v_mfma_f32_32x32x16_bf16 v[0:15], v[180:183], v[158:161], v[0:15]
	s_cbranch_scc1 .LBB0_620
	s_mov_b32 s0, 0x10000
	v_add3_u32 v226, v166, v164, 16
	v_add3_u32 v227, v165, v164, 16
	v_add3_u32 v229, v139, v227, s0
	v_add3_u32 v228, v139, v226, s0
	ds_read_b128 v[192:195], v229 offset:32768
	ds_read_b128 v[200:203], v229 offset:36864
	ds_read_b128 v[172:175], v228
	ds_read_b128 v[176:179], v228 offset:4096
	ds_read_b128 v[180:183], v228 offset:8192
	ds_read_b128 v[184:187], v228 offset:12288
	v_add3_u32 v228, v138, v226, s0
	ds_read_b128 v[188:191], v228
	v_add3_u32 v229, v138, v227, s0
	ds_read_b128 v[204:207], v229 offset:32768
	ds_read_b128 v[222:225], v229 offset:36864
	s_waitcnt lgkmcnt(6)
	v_mfma_f32_32x32x16_bf16 v[112:127], v[172:175], v[192:195], v[112:127]
	v_mfma_f32_32x32x16_bf16 v[96:111], v[172:175], v[200:203], v[96:111]
	ds_read_b128 v[172:175], v228 offset:4096
	s_waitcnt lgkmcnt(6)
	v_mfma_f32_32x32x16_bf16 v[80:95], v[176:179], v[192:195], v[80:95]
	v_mfma_f32_32x32x16_bf16 v[64:79], v[176:179], v[200:203], v[64:79]
	ds_read_b128 v[176:179], v228 offset:8192
	s_waitcnt lgkmcnt(6)
	v_mfma_f32_32x32x16_bf16 v[48:63], v[180:183], v[192:195], v[48:63]
	v_mfma_f32_32x32x16_bf16 v[32:47], v[180:183], v[200:203], v[32:47]
	ds_read_b128 v[180:183], v228 offset:12288
	s_waitcnt lgkmcnt(6)
	v_mfma_f32_32x32x16_bf16 v[16:31], v[184:187], v[192:195], v[16:31]
	v_mfma_f32_32x32x16_bf16 v[0:15], v[184:187], v[200:203], v[0:15]
	v_add3_u32 v228, v144, v226, s0
	ds_read_b128 v[184:187], v228
	v_add3_u32 v229, v144, v227, s0
	ds_read_b128 v[192:195], v229 offset:32768
	ds_read_b128 v[200:203], v229 offset:36864
	s_waitcnt lgkmcnt(6)
	v_mfma_f32_32x32x16_bf16 v[112:127], v[188:191], v[204:207], v[112:127]
	v_mfma_f32_32x32x16_bf16 v[96:111], v[188:191], v[222:225], v[96:111]
	ds_read_b128 v[188:191], v228 offset:4096
	s_waitcnt lgkmcnt(6)
	v_mfma_f32_32x32x16_bf16 v[80:95], v[172:175], v[204:207], v[80:95]
	v_mfma_f32_32x32x16_bf16 v[64:79], v[172:175], v[222:225], v[64:79]
	ds_read_b128 v[172:175], v228 offset:8192
	s_waitcnt lgkmcnt(6)
	v_mfma_f32_32x32x16_bf16 v[48:63], v[176:179], v[204:207], v[48:63]
	v_mfma_f32_32x32x16_bf16 v[32:47], v[176:179], v[222:225], v[32:47]
	ds_read_b128 v[176:179], v228 offset:12288
	s_waitcnt lgkmcnt(6)
	v_mfma_f32_32x32x16_bf16 v[16:31], v[180:183], v[204:207], v[16:31]
	v_mfma_f32_32x32x16_bf16 v[0:15], v[180:183], v[222:225], v[0:15]
	v_add3_u32 v228, v167, v226, s0
	ds_read_b128 v[180:183], v228
	v_add3_u32 v229, v167, v227, s0
	ds_read_b128 v[204:207], v229 offset:32768
	ds_read_b128 v[222:225], v229 offset:36864
	s_waitcnt lgkmcnt(6)
	v_mfma_f32_32x32x16_bf16 v[112:127], v[184:187], v[192:195], v[112:127]
	v_mfma_f32_32x32x16_bf16 v[96:111], v[184:187], v[200:203], v[96:111]
	ds_read_b128 v[184:187], v228 offset:4096
	s_waitcnt lgkmcnt(6)
	v_mfma_f32_32x32x16_bf16 v[80:95], v[188:191], v[192:195], v[80:95]
	v_mfma_f32_32x32x16_bf16 v[64:79], v[188:191], v[200:203], v[64:79]
	ds_read_b128 v[188:191], v228 offset:8192
	s_waitcnt lgkmcnt(6)
	v_mfma_f32_32x32x16_bf16 v[48:63], v[172:175], v[192:195], v[48:63]
	v_mfma_f32_32x32x16_bf16 v[32:47], v[172:175], v[200:203], v[32:47]
	ds_read_b128 v[172:175], v228 offset:12288
	s_waitcnt lgkmcnt(6)
	v_mfma_f32_32x32x16_bf16 v[16:31], v[176:179], v[192:195], v[16:31]
	v_mfma_f32_32x32x16_bf16 v[0:15], v[176:179], v[200:203], v[0:15]
	s_waitcnt lgkmcnt(3)
	v_mfma_f32_32x32x16_bf16 v[112:127], v[180:183], v[204:207], v[112:127]
	v_mfma_f32_32x32x16_bf16 v[96:111], v[180:183], v[222:225], v[96:111]
	s_waitcnt lgkmcnt(2)
	v_mfma_f32_32x32x16_bf16 v[80:95], v[184:187], v[204:207], v[80:95]
	v_mfma_f32_32x32x16_bf16 v[64:79], v[184:187], v[222:225], v[64:79]
	s_waitcnt lgkmcnt(1)
	v_mfma_f32_32x32x16_bf16 v[48:63], v[188:191], v[204:207], v[48:63]
	v_mfma_f32_32x32x16_bf16 v[32:47], v[188:191], v[222:225], v[32:47]
	s_waitcnt lgkmcnt(0)
	v_mfma_f32_32x32x16_bf16 v[16:31], v[172:175], v[204:207], v[16:31]
	v_mfma_f32_32x32x16_bf16 v[0:15], v[172:175], v[222:225], v[0:15]
	s_waitcnt lgkmcnt(0)
	s_barrier
	v_readlane_b32 s36, v252, 6
	v_readlane_b32 s37, v252, 7
	v_readlane_b32 s38, v252, 8
	v_readlane_b32 s39, v252, 9
	v_readlane_b32 s40, v252, 10
	v_readlane_b32 s41, v252, 11
	v_readlane_b32 s42, v252, 12
	v_readlane_b32 s43, v252, 13
	v_readlane_b32 s44, v252, 14
	v_readlane_b32 s45, v252, 15
	v_readlane_b32 s46, v252, 16
	v_readlane_b32 s47, v252, 17
	v_readlane_b32 s48, v252, 18
	v_readlane_b32 s49, v252, 19
	v_readlane_b32 s50, v252, 20
	v_readlane_b32 s51, v252, 21
	s_add_i32 s2, s2, s92
	s_add_i32 s9, s9, s10
	v_lshl_add_u32 v211, v211, 7, s19
	v_lshl_or_b32 v212, v212, 2, v211
	v_lshl_or_b32 v208, v213, 6, s20
	v_or_b32_e32 v210, v208, v210
	v_lshl_add_u32 v128, v212, 10, v210
	v_lshlrev_b32_e32 v128, 2, v128
	global_load_dword v172, v128, s[36:37]
	global_load_dword v173, v128, s[36:37] offset:128
	v_add_u32_e32 v129, 0x1000, v128
	global_load_dword v174, v129, s[36:37]
	global_load_dword v175, v129, s[36:37] offset:128
	v_add_u32_e32 v130, 0x1000, v129
	global_load_dword v176, v130, s[36:37]
	global_load_dword v177, v130, s[36:37] offset:128
	v_add_u32_e32 v131, 0x1000, v130
	global_load_dword v178, v131, s[36:37]
	global_load_dword v179, v131, s[36:37] offset:128
	v_add_u32_e32 v132, 0x5000, v131
	global_load_dword v180, v132, s[36:37]
	global_load_dword v181, v132, s[36:37] offset:128
	v_add_u32_e32 v133, 0x1000, v132
	global_load_dword v182, v133, s[36:37]
	global_load_dword v183, v133, s[36:37] offset:128
	v_add_u32_e32 v134, 0x1000, v133
	global_load_dword v184, v134, s[36:37]
	global_load_dword v185, v134, s[36:37] offset:128
	v_add_u32_e32 v135, 0x1000, v134
	global_load_dword v186, v135, s[36:37]
	global_load_dword v187, v135, s[36:37] offset:128
	v_add_u32_e32 v136, 0x5000, v135
	global_load_dword v188, v136, s[36:37]
	global_load_dword v189, v136, s[36:37] offset:128
	v_add_u32_e32 v137, 0x1000, v136
	global_load_dword v190, v137, s[36:37]
	global_load_dword v191, v137, s[36:37] offset:128
	v_add_u32_e32 v138, 0x1000, v137
	global_load_dword v192, v138, s[36:37]
	global_load_dword v193, v138, s[36:37] offset:128
	v_add_u32_e32 v139, 0x1000, v138
	global_load_dword v194, v139, s[36:37]
	global_load_dword v195, v139, s[36:37] offset:128
	v_add_u32_e32 v140, 0x5000, v139
	global_load_dword v196, v140, s[36:37]
	global_load_dword v197, v140, s[36:37] offset:128
	v_add_u32_e32 v141, 0x1000, v140
	global_load_dword v198, v141, s[36:37]
	global_load_dword v199, v141, s[36:37] offset:128
	v_add_u32_e32 v142, 0x1000, v141
	global_load_dword v200, v142, s[36:37]
	global_load_dword v201, v142, s[36:37] offset:128
	v_add_u32_e32 v143, 0x1000, v142
	global_load_dword v202, v143, s[36:37]
	global_load_dword v203, v143, s[36:37] offset:128
	s_waitcnt vmcnt(16)
	v_add_f32_e32 v172, v112, v172
	v_add_f32_e32 v173, v96, v173
	global_store_dword v128, v172, s[84:85]
	global_store_dword v128, v173, s[84:85] offset:128
	v_add_f32_e32 v174, v113, v174
	v_add_f32_e32 v175, v97, v175
	global_store_dword v129, v174, s[84:85]
	global_store_dword v129, v175, s[84:85] offset:128
	v_add_f32_e32 v176, v114, v176
	v_add_f32_e32 v177, v98, v177
	global_store_dword v130, v176, s[84:85]
	global_store_dword v130, v177, s[84:85] offset:128
	v_add_f32_e32 v178, v115, v178
	v_add_f32_e32 v179, v99, v179
	global_store_dword v131, v178, s[84:85]
	global_store_dword v131, v179, s[84:85] offset:128
	v_add_f32_e32 v180, v116, v180
	v_add_f32_e32 v181, v100, v181
	global_store_dword v132, v180, s[84:85]
	global_store_dword v132, v181, s[84:85] offset:128
	v_add_f32_e32 v182, v117, v182
	v_add_f32_e32 v183, v101, v183
	global_store_dword v133, v182, s[84:85]
	global_store_dword v133, v183, s[84:85] offset:128
	v_add_f32_e32 v184, v118, v184
	v_add_f32_e32 v185, v102, v185
	global_store_dword v134, v184, s[84:85]
	global_store_dword v134, v185, s[84:85] offset:128
	v_add_f32_e32 v186, v119, v186
	v_add_f32_e32 v187, v103, v187
	global_store_dword v135, v186, s[84:85]
	global_store_dword v135, v187, s[84:85] offset:128
	v_add_u32_e32 v128, 0x5000, v143
	global_load_dword v172, v128, s[36:37]
	global_load_dword v173, v128, s[36:37] offset:128
	v_add_u32_e32 v129, 0x1000, v128
	global_load_dword v174, v129, s[36:37]
	global_load_dword v175, v129, s[36:37] offset:128
	v_add_u32_e32 v130, 0x1000, v129
	global_load_dword v176, v130, s[36:37]
	global_load_dword v177, v130, s[36:37] offset:128
	v_add_u32_e32 v131, 0x1000, v130
	global_load_dword v178, v131, s[36:37]
	global_load_dword v179, v131, s[36:37] offset:128
	v_add_u32_e32 v132, 0x5000, v131
	global_load_dword v180, v132, s[36:37]
	global_load_dword v181, v132, s[36:37] offset:128
	v_add_u32_e32 v133, 0x1000, v132
	global_load_dword v182, v133, s[36:37]
	global_load_dword v183, v133, s[36:37] offset:128
	v_add_u32_e32 v134, 0x1000, v133
	global_load_dword v184, v134, s[36:37]
	global_load_dword v185, v134, s[36:37] offset:128
	v_add_u32_e32 v135, 0x1000, v134
	global_load_dword v186, v135, s[36:37]
	global_load_dword v187, v135, s[36:37] offset:128
	s_waitcnt vmcnt(32)
	v_add_f32_e32 v188, v120, v188
	v_add_f32_e32 v189, v104, v189
	global_store_dword v136, v188, s[84:85]
	global_store_dword v136, v189, s[84:85] offset:128
	v_add_f32_e32 v190, v121, v190
	v_add_f32_e32 v191, v105, v191
	global_store_dword v137, v190, s[84:85]
	global_store_dword v137, v191, s[84:85] offset:128
	v_add_f32_e32 v192, v122, v192
	v_add_f32_e32 v193, v106, v193
	global_store_dword v138, v192, s[84:85]
	global_store_dword v138, v193, s[84:85] offset:128
	v_add_f32_e32 v194, v123, v194
	v_add_f32_e32 v195, v107, v195
	global_store_dword v139, v194, s[84:85]
	global_store_dword v139, v195, s[84:85] offset:128
	v_add_f32_e32 v196, v124, v196
	v_add_f32_e32 v197, v108, v197
	global_store_dword v140, v196, s[84:85]
	global_store_dword v140, v197, s[84:85] offset:128
	v_add_f32_e32 v198, v125, v198
	v_add_f32_e32 v199, v109, v199
	global_store_dword v141, v198, s[84:85]
	global_store_dword v141, v199, s[84:85] offset:128
	v_add_f32_e32 v200, v126, v200
	v_add_f32_e32 v201, v110, v201
	global_store_dword v142, v200, s[84:85]
	global_store_dword v142, v201, s[84:85] offset:128
	v_add_f32_e32 v202, v127, v202
	v_add_f32_e32 v203, v111, v203
	global_store_dword v143, v202, s[84:85]
	global_store_dword v143, v203, s[84:85] offset:128
	v_add_u32_e32 v136, 0x5000, v135
	global_load_dword v188, v136, s[36:37]
	global_load_dword v189, v136, s[36:37] offset:128
	v_add_u32_e32 v137, 0x1000, v136
	global_load_dword v190, v137, s[36:37]
	global_load_dword v191, v137, s[36:37] offset:128
	v_add_u32_e32 v138, 0x1000, v137
	global_load_dword v192, v138, s[36:37]
	global_load_dword v193, v138, s[36:37] offset:128
	v_add_u32_e32 v139, 0x1000, v138
	global_load_dword v194, v139, s[36:37]
	global_load_dword v195, v139, s[36:37] offset:128
	v_add_u32_e32 v140, 0x5000, v139
	global_load_dword v196, v140, s[36:37]
	global_load_dword v197, v140, s[36:37] offset:128
	v_add_u32_e32 v141, 0x1000, v140
	global_load_dword v198, v141, s[36:37]
	global_load_dword v199, v141, s[36:37] offset:128
	v_add_u32_e32 v142, 0x1000, v141
	global_load_dword v200, v142, s[36:37]
	global_load_dword v201, v142, s[36:37] offset:128
	v_add_u32_e32 v143, 0x1000, v142
	global_load_dword v202, v143, s[36:37]
	global_load_dword v203, v143, s[36:37] offset:128
	s_waitcnt vmcnt(32)
	v_add_f32_e32 v172, v80, v172
	v_add_f32_e32 v173, v64, v173
	global_store_dword v128, v172, s[84:85]
	global_store_dword v128, v173, s[84:85] offset:128
	v_add_f32_e32 v174, v81, v174
	v_add_f32_e32 v175, v65, v175
	global_store_dword v129, v174, s[84:85]
	global_store_dword v129, v175, s[84:85] offset:128
	v_add_f32_e32 v176, v82, v176
	v_add_f32_e32 v177, v66, v177
	global_store_dword v130, v176, s[84:85]
	global_store_dword v130, v177, s[84:85] offset:128
	v_add_f32_e32 v178, v83, v178
	v_add_f32_e32 v179, v67, v179
	global_store_dword v131, v178, s[84:85]
	global_store_dword v131, v179, s[84:85] offset:128
	v_add_f32_e32 v180, v84, v180
	v_add_f32_e32 v181, v68, v181
	global_store_dword v132, v180, s[84:85]
	global_store_dword v132, v181, s[84:85] offset:128
	v_add_f32_e32 v182, v85, v182
	v_add_f32_e32 v183, v69, v183
	global_store_dword v133, v182, s[84:85]
	global_store_dword v133, v183, s[84:85] offset:128
	v_add_f32_e32 v184, v86, v184
	v_add_f32_e32 v185, v70, v185
	global_store_dword v134, v184, s[84:85]
	global_store_dword v134, v185, s[84:85] offset:128
	v_add_f32_e32 v186, v87, v186
	v_add_f32_e32 v187, v71, v187
	global_store_dword v135, v186, s[84:85]
	global_store_dword v135, v187, s[84:85] offset:128
	v_add_u32_e32 v128, 0x5000, v143
	global_load_dword v172, v128, s[36:37]
	global_load_dword v173, v128, s[36:37] offset:128
	v_add_u32_e32 v129, 0x1000, v128
	global_load_dword v174, v129, s[36:37]
	global_load_dword v175, v129, s[36:37] offset:128
	v_add_u32_e32 v130, 0x1000, v129
	global_load_dword v176, v130, s[36:37]
	global_load_dword v177, v130, s[36:37] offset:128
	v_add_u32_e32 v131, 0x1000, v130
	global_load_dword v178, v131, s[36:37]
	global_load_dword v179, v131, s[36:37] offset:128
	v_add_u32_e32 v132, 0x5000, v131
	global_load_dword v180, v132, s[36:37]
	global_load_dword v181, v132, s[36:37] offset:128
	v_add_u32_e32 v133, 0x1000, v132
	global_load_dword v182, v133, s[36:37]
	global_load_dword v183, v133, s[36:37] offset:128
	v_add_u32_e32 v134, 0x1000, v133
	global_load_dword v184, v134, s[36:37]
	global_load_dword v185, v134, s[36:37] offset:128
	v_add_u32_e32 v135, 0x1000, v134
	global_load_dword v186, v135, s[36:37]
	global_load_dword v187, v135, s[36:37] offset:128
	s_waitcnt vmcnt(32)
	v_add_f32_e32 v188, v88, v188
	v_add_f32_e32 v189, v72, v189
	global_store_dword v136, v188, s[84:85]
	global_store_dword v136, v189, s[84:85] offset:128
	v_add_f32_e32 v190, v89, v190
	v_add_f32_e32 v191, v73, v191
	global_store_dword v137, v190, s[84:85]
	global_store_dword v137, v191, s[84:85] offset:128
	v_add_f32_e32 v192, v90, v192
	v_add_f32_e32 v193, v74, v193
	global_store_dword v138, v192, s[84:85]
	global_store_dword v138, v193, s[84:85] offset:128
	v_add_f32_e32 v194, v91, v194
	v_add_f32_e32 v195, v75, v195
	global_store_dword v139, v194, s[84:85]
	global_store_dword v139, v195, s[84:85] offset:128
	v_add_f32_e32 v196, v92, v196
	v_add_f32_e32 v197, v76, v197
	global_store_dword v140, v196, s[84:85]
	global_store_dword v140, v197, s[84:85] offset:128
	v_add_f32_e32 v198, v93, v198
	v_add_f32_e32 v199, v77, v199
	global_store_dword v141, v198, s[84:85]
	global_store_dword v141, v199, s[84:85] offset:128
	v_add_f32_e32 v200, v94, v200
	v_add_f32_e32 v201, v78, v201
	global_store_dword v142, v200, s[84:85]
	global_store_dword v142, v201, s[84:85] offset:128
	v_add_f32_e32 v202, v95, v202
	v_add_f32_e32 v203, v79, v203
	global_store_dword v143, v202, s[84:85]
	global_store_dword v143, v203, s[84:85] offset:128
	v_add_u32_e32 v136, 0x5000, v135
	global_load_dword v188, v136, s[36:37]
	global_load_dword v189, v136, s[36:37] offset:128
	v_add_u32_e32 v137, 0x1000, v136
	global_load_dword v190, v137, s[36:37]
	global_load_dword v191, v137, s[36:37] offset:128
	v_add_u32_e32 v138, 0x1000, v137
	global_load_dword v192, v138, s[36:37]
	global_load_dword v193, v138, s[36:37] offset:128
	v_add_u32_e32 v139, 0x1000, v138
	global_load_dword v194, v139, s[36:37]
	global_load_dword v195, v139, s[36:37] offset:128
	v_add_u32_e32 v140, 0x5000, v139
	global_load_dword v196, v140, s[36:37]
	global_load_dword v197, v140, s[36:37] offset:128
	v_add_u32_e32 v141, 0x1000, v140
	global_load_dword v198, v141, s[36:37]
	global_load_dword v199, v141, s[36:37] offset:128
	v_add_u32_e32 v142, 0x1000, v141
	global_load_dword v200, v142, s[36:37]
	global_load_dword v201, v142, s[36:37] offset:128
	v_add_u32_e32 v143, 0x1000, v142
	global_load_dword v202, v143, s[36:37]
	global_load_dword v203, v143, s[36:37] offset:128
	s_waitcnt vmcnt(32)
	v_add_f32_e32 v172, v48, v172
	v_add_f32_e32 v173, v32, v173
	global_store_dword v128, v172, s[84:85]
	global_store_dword v128, v173, s[84:85] offset:128
	v_add_f32_e32 v174, v49, v174
	v_add_f32_e32 v175, v33, v175
	global_store_dword v129, v174, s[84:85]
	global_store_dword v129, v175, s[84:85] offset:128
	v_add_f32_e32 v176, v50, v176
	v_add_f32_e32 v177, v34, v177
	global_store_dword v130, v176, s[84:85]
	global_store_dword v130, v177, s[84:85] offset:128
	v_add_f32_e32 v178, v51, v178
	v_add_f32_e32 v179, v35, v179
	global_store_dword v131, v178, s[84:85]
	global_store_dword v131, v179, s[84:85] offset:128
	v_add_f32_e32 v180, v52, v180
	v_add_f32_e32 v181, v36, v181
	global_store_dword v132, v180, s[84:85]
	global_store_dword v132, v181, s[84:85] offset:128
	v_add_f32_e32 v182, v53, v182
	v_add_f32_e32 v183, v37, v183
	global_store_dword v133, v182, s[84:85]
	global_store_dword v133, v183, s[84:85] offset:128
	v_add_f32_e32 v184, v54, v184
	v_add_f32_e32 v185, v38, v185
	global_store_dword v134, v184, s[84:85]
	global_store_dword v134, v185, s[84:85] offset:128
	v_add_f32_e32 v186, v55, v186
	v_add_f32_e32 v187, v39, v187
	global_store_dword v135, v186, s[84:85]
	global_store_dword v135, v187, s[84:85] offset:128
	v_add_u32_e32 v128, 0x5000, v143
	global_load_dword v172, v128, s[36:37]
	global_load_dword v173, v128, s[36:37] offset:128
	v_add_u32_e32 v129, 0x1000, v128
	global_load_dword v174, v129, s[36:37]
	global_load_dword v175, v129, s[36:37] offset:128
	v_add_u32_e32 v130, 0x1000, v129
	global_load_dword v176, v130, s[36:37]
	global_load_dword v177, v130, s[36:37] offset:128
	v_add_u32_e32 v131, 0x1000, v130
	global_load_dword v178, v131, s[36:37]
	global_load_dword v179, v131, s[36:37] offset:128
	v_add_u32_e32 v132, 0x5000, v131
	global_load_dword v180, v132, s[36:37]
	global_load_dword v181, v132, s[36:37] offset:128
	v_add_u32_e32 v133, 0x1000, v132
	global_load_dword v182, v133, s[36:37]
	global_load_dword v183, v133, s[36:37] offset:128
	v_add_u32_e32 v134, 0x1000, v133
	global_load_dword v184, v134, s[36:37]
	global_load_dword v185, v134, s[36:37] offset:128
	v_add_u32_e32 v135, 0x1000, v134
	global_load_dword v186, v135, s[36:37]
	global_load_dword v187, v135, s[36:37] offset:128
	s_waitcnt vmcnt(32)
	v_add_f32_e32 v188, v56, v188
	v_add_f32_e32 v189, v40, v189
	global_store_dword v136, v188, s[84:85]
	global_store_dword v136, v189, s[84:85] offset:128
	v_add_f32_e32 v190, v57, v190
	v_add_f32_e32 v191, v41, v191
	global_store_dword v137, v190, s[84:85]
	global_store_dword v137, v191, s[84:85] offset:128
	v_add_f32_e32 v192, v58, v192
	v_add_f32_e32 v193, v42, v193
	global_store_dword v138, v192, s[84:85]
	global_store_dword v138, v193, s[84:85] offset:128
	v_add_f32_e32 v194, v59, v194
	v_add_f32_e32 v195, v43, v195
	global_store_dword v139, v194, s[84:85]
	global_store_dword v139, v195, s[84:85] offset:128
	v_add_f32_e32 v196, v60, v196
	v_add_f32_e32 v197, v44, v197
	global_store_dword v140, v196, s[84:85]
	global_store_dword v140, v197, s[84:85] offset:128
	v_add_f32_e32 v198, v61, v198
	v_add_f32_e32 v199, v45, v199
	global_store_dword v141, v198, s[84:85]
	global_store_dword v141, v199, s[84:85] offset:128
	v_add_f32_e32 v200, v62, v200
	v_add_f32_e32 v201, v46, v201
	global_store_dword v142, v200, s[84:85]
	global_store_dword v142, v201, s[84:85] offset:128
	v_add_f32_e32 v202, v63, v202
	v_add_f32_e32 v203, v47, v203
	global_store_dword v143, v202, s[84:85]
	global_store_dword v143, v203, s[84:85] offset:128
	v_add_u32_e32 v136, 0x5000, v135
	global_load_dword v188, v136, s[36:37]
	global_load_dword v189, v136, s[36:37] offset:128
	v_add_u32_e32 v137, 0x1000, v136
	global_load_dword v190, v137, s[36:37]
	global_load_dword v191, v137, s[36:37] offset:128
	v_add_u32_e32 v138, 0x1000, v137
	global_load_dword v192, v138, s[36:37]
	global_load_dword v193, v138, s[36:37] offset:128
	v_add_u32_e32 v139, 0x1000, v138
	global_load_dword v194, v139, s[36:37]
	global_load_dword v195, v139, s[36:37] offset:128
	v_add_u32_e32 v140, 0x5000, v139
	global_load_dword v196, v140, s[36:37]
	global_load_dword v197, v140, s[36:37] offset:128
	v_add_u32_e32 v141, 0x1000, v140
	global_load_dword v198, v141, s[36:37]
	global_load_dword v199, v141, s[36:37] offset:128
	v_add_u32_e32 v142, 0x1000, v141
	global_load_dword v200, v142, s[36:37]
	global_load_dword v201, v142, s[36:37] offset:128
	v_add_u32_e32 v143, 0x1000, v142
	global_load_dword v202, v143, s[36:37]
	global_load_dword v203, v143, s[36:37] offset:128
	s_waitcnt vmcnt(32)
	v_add_f32_e32 v172, v16, v172
	v_add_f32_e32 v173, v0, v173
	global_store_dword v128, v172, s[84:85]
	global_store_dword v128, v173, s[84:85] offset:128
	v_add_f32_e32 v174, v17, v174
	v_add_f32_e32 v175, v1, v175
	global_store_dword v129, v174, s[84:85]
	global_store_dword v129, v175, s[84:85] offset:128
	v_add_f32_e32 v176, v18, v176
	v_add_f32_e32 v177, v2, v177
	global_store_dword v130, v176, s[84:85]
	global_store_dword v130, v177, s[84:85] offset:128
	v_add_f32_e32 v178, v19, v178
	v_add_f32_e32 v179, v3, v179
	global_store_dword v131, v178, s[84:85]
	global_store_dword v131, v179, s[84:85] offset:128
	v_add_f32_e32 v180, v20, v180
	v_add_f32_e32 v181, v4, v181
	global_store_dword v132, v180, s[84:85]
	global_store_dword v132, v181, s[84:85] offset:128
	v_add_f32_e32 v182, v21, v182
	v_add_f32_e32 v183, v5, v183
	global_store_dword v133, v182, s[84:85]
	global_store_dword v133, v183, s[84:85] offset:128
	v_add_f32_e32 v184, v22, v184
	v_add_f32_e32 v185, v6, v185
	global_store_dword v134, v184, s[84:85]
	global_store_dword v134, v185, s[84:85] offset:128
	v_add_f32_e32 v186, v23, v186
	v_add_f32_e32 v187, v7, v187
	global_store_dword v135, v186, s[84:85]
	global_store_dword v135, v187, s[84:85] offset:128
	s_waitcnt vmcnt(16)
	v_add_f32_e32 v188, v24, v188
	v_add_f32_e32 v189, v8, v189
	global_store_dword v136, v188, s[84:85]
	global_store_dword v136, v189, s[84:85] offset:128
	v_add_f32_e32 v190, v25, v190
	v_add_f32_e32 v191, v9, v191
	global_store_dword v137, v190, s[84:85]
	global_store_dword v137, v191, s[84:85] offset:128
	v_add_f32_e32 v192, v26, v192
	v_add_f32_e32 v193, v10, v193
	global_store_dword v138, v192, s[84:85]
	global_store_dword v138, v193, s[84:85] offset:128
	v_add_f32_e32 v194, v27, v194
	v_add_f32_e32 v195, v11, v195
	global_store_dword v139, v194, s[84:85]
	global_store_dword v139, v195, s[84:85] offset:128
	v_add_f32_e32 v196, v28, v196
	v_add_f32_e32 v197, v12, v197
	global_store_dword v140, v196, s[84:85]
	global_store_dword v140, v197, s[84:85] offset:128
	v_add_f32_e32 v198, v29, v198
	v_add_f32_e32 v199, v13, v199
	global_store_dword v141, v198, s[84:85]
	global_store_dword v141, v199, s[84:85] offset:128
	v_add_f32_e32 v200, v30, v200
	v_add_f32_e32 v201, v14, v201
	global_store_dword v142, v200, s[84:85]
	global_store_dword v142, v201, s[84:85] offset:128
	v_add_f32_e32 v202, v31, v202
	v_add_f32_e32 v203, v15, v203
	global_store_dword v143, v202, s[84:85]
	global_store_dword v143, v203, s[84:85] offset:128
	s_cmpk_lt_i32 s2, 0x100
	s_cbranch_scc1 .LBB0_619

.Lhy_ep1_comb_L1:
	s_mov_b32 s98, 0x5040100
	s_mov_b32 s99, 0x7060302
	v_lshlrev_b32_e32 v109, 1, v10
	v_add_u32_e32 v254, 0x1e00, v10
	v_add_u32_e32 v253, 0x1000, v109
	v_cmp_gt_i32_e32 vcc, 0x1fff, v254
	v_add_u32_e32 v251, 0x2000, v109
	v_add_u32_e32 v250, 0x3000, v109
	v_min_i32_e32 v254, 0x1ffe, v254
	v_cndmask_b32_e64 v255, 0, 1.0, vcc
	v_lshlrev_b32_e32 v254, 1, v254
	global_load_ushort v9, v109, s[0:1]
	global_load_ushort v11, v109, s[4:5]
	global_load_ushort v13, v109, s[36:37] offset:1022
	global_load_ushort v15, v109, s[36:37] offset:1024
	global_load_ushort v81, v109, s[36:37] offset:1026
	global_load_ushort v83, v109, s[72:73] offset:1022
	global_load_ushort v85, v109, s[72:73] offset:1024
	global_load_ushort v87, v109, s[72:73] offset:1026
	global_load_ushort v89, v109, s[0:1] offset:1024
	global_load_ushort v91, v109, s[4:5] offset:1024
	global_load_ushort v93, v109, s[36:37] offset:2046
	global_load_ushort v94, v109, s[36:37] offset:2048
	global_load_ushort v95, v109, s[36:37] offset:2050
	global_load_ushort v96, v109, s[72:73] offset:2046
	global_load_ushort v97, v109, s[72:73] offset:2048
	global_load_ushort v98, v109, s[72:73] offset:2050
	global_load_ushort v99, v109, s[0:1] offset:2048
	global_load_ushort v100, v109, s[4:5] offset:2048
	global_load_ushort v101, v109, s[36:37] offset:3070
	global_load_ushort v102, v109, s[36:37] offset:3072
	global_load_ushort v103, v109, s[36:37] offset:3074
	global_load_ushort v104, v109, s[72:73] offset:3070
	global_load_ushort v105, v109, s[72:73] offset:3072
	global_load_ushort v106, v109, s[72:73] offset:3074
	global_load_ushort v107, v109, s[0:1] offset:3072
	global_load_ushort v108, v109, s[4:5] offset:3072
	global_load_ushort v111, v253, s[36:37] offset:-2
	global_load_ushort v112, v253, s[36:37]
	global_load_ushort v113, v253, s[36:37] offset:2
	global_load_ushort v114, v253, s[72:73] offset:-2
	global_load_ushort v115, v253, s[72:73]
	global_load_ushort v116, v253, s[72:73] offset:2
	global_load_ushort v117, v253, s[0:1]
	global_load_ushort v118, v253, s[4:5]
	global_load_ushort v119, v253, s[36:37] offset:1022
	global_load_ushort v120, v253, s[36:37] offset:1024
	global_load_ushort v121, v253, s[36:37] offset:1026
	global_load_ushort v122, v253, s[72:73] offset:1022
	global_load_ushort v123, v253, s[72:73] offset:1024
	global_load_ushort v124, v253, s[72:73] offset:1026
	global_load_ushort v125, v253, s[0:1] offset:1024
	global_load_ushort v126, v253, s[4:5] offset:1024
	global_load_ushort v127, v253, s[36:37] offset:2046
	global_load_ushort v128, v253, s[36:37] offset:2048
	global_load_ushort v129, v253, s[36:37] offset:2050
	global_load_ushort v130, v253, s[72:73] offset:2046
	global_load_ushort v131, v253, s[72:73] offset:2048
	global_load_ushort v132, v253, s[72:73] offset:2050
	global_load_ushort v133, v253, s[0:1] offset:2048
	global_load_ushort v134, v253, s[4:5] offset:2048
	global_load_ushort v135, v253, s[36:37] offset:3070
	global_load_ushort v136, v253, s[36:37] offset:3072
	global_load_ushort v137, v253, s[36:37] offset:3074
	global_load_ushort v138, v253, s[72:73] offset:3070
	global_load_ushort v139, v253, s[72:73] offset:3072
	global_load_ushort v140, v253, s[72:73] offset:3074
	global_load_ushort v141, v253, s[0:1] offset:3072
	global_load_ushort v142, v253, s[4:5] offset:3072
	global_load_ushort v143, v251, s[36:37] offset:-2
	global_load_ushort v163, v251, s[36:37]
	global_load_ushort v164, v251, s[36:37] offset:2
	global_load_ushort v165, v251, s[72:73] offset:-2
	global_load_ushort v166, v251, s[72:73]
	global_load_ushort v167, v251, s[72:73] offset:2
	global_load_ushort v168, v251, s[0:1]
	global_load_ushort v169, v251, s[4:5]
	global_load_ushort v170, v251, s[36:37] offset:1022
	global_load_ushort v171, v251, s[36:37] offset:1024
	global_load_ushort v172, v251, s[36:37] offset:1026
	global_load_ushort v173, v251, s[72:73] offset:1022
	global_load_ushort v174, v251, s[72:73] offset:1024
	global_load_ushort v175, v251, s[72:73] offset:1026
	global_load_ushort v176, v251, s[0:1] offset:1024
	global_load_ushort v177, v251, s[4:5] offset:1024
	global_load_ushort v178, v251, s[36:37] offset:2046
	global_load_ushort v179, v251, s[36:37] offset:2048
	global_load_ushort v180, v251, s[36:37] offset:2050
	global_load_ushort v181, v251, s[72:73] offset:2046
	global_load_ushort v182, v251, s[72:73] offset:2048
	global_load_ushort v183, v251, s[72:73] offset:2050
	global_load_ushort v184, v251, s[0:1] offset:2048
	global_load_ushort v185, v251, s[4:5] offset:2048
	global_load_ushort v186, v251, s[36:37] offset:3070
	global_load_ushort v187, v251, s[36:37] offset:3072
	global_load_ushort v188, v251, s[36:37] offset:3074
	global_load_ushort v189, v251, s[72:73] offset:3070
	global_load_ushort v190, v251, s[72:73] offset:3072
	global_load_ushort v191, v251, s[72:73] offset:3074
	global_load_ushort v192, v251, s[0:1] offset:3072
	global_load_ushort v193, v251, s[4:5] offset:3072
	global_load_ushort v194, v250, s[36:37] offset:-2
	global_load_ushort v195, v250, s[36:37]
	global_load_ushort v196, v250, s[36:37] offset:2
	global_load_ushort v197, v250, s[72:73] offset:-2
	global_load_ushort v221, v250, s[72:73]
	global_load_ushort v222, v250, s[72:73] offset:2
	global_load_ushort v223, v250, s[0:1]
	global_load_ushort v224, v250, s[4:5]
	global_load_ushort v225, v250, s[36:37] offset:1022
	global_load_ushort v226, v250, s[36:37] offset:1024
	global_load_ushort v227, v250, s[36:37] offset:1026
	global_load_ushort v228, v250, s[72:73] offset:1022
	global_load_ushort v229, v250, s[72:73] offset:1024
	global_load_ushort v230, v250, s[72:73] offset:1026
	global_load_ushort v231, v250, s[0:1] offset:1024
	global_load_ushort v232, v250, s[4:5] offset:1024
	global_load_ushort v233, v250, s[36:37] offset:2046
	global_load_ushort v234, v250, s[36:37] offset:2048
	global_load_ushort v235, v250, s[36:37] offset:2050
	global_load_ushort v236, v250, s[72:73] offset:2046
	global_load_ushort v237, v250, s[72:73] offset:2048
	global_load_ushort v238, v250, s[72:73] offset:2050
	global_load_ushort v239, v250, s[0:1] offset:2048
	global_load_ushort v240, v250, s[4:5] offset:2048
	global_load_ushort v241, v250, s[36:37] offset:3070
	global_load_ushort v242, v250, s[36:37] offset:3072
	global_load_ushort v243, v254, s[36:37] offset:2
	global_load_ushort v244, v250, s[72:73] offset:3070
	global_load_ushort v245, v250, s[72:73] offset:3072
	global_load_ushort v246, v254, s[72:73] offset:2
	global_load_ushort v247, v250, s[0:1] offset:3072
	global_load_ushort v248, v250, s[4:5] offset:3072
	v_readlane_b32 s0, v252, 60
	v_readlane_b32 s1, v252, 61
	s_lshr_b32 s4, s62, 1
	s_lshl_b32 s4, s4, 16
	s_add_u32 s0, s0, s4
	s_addc_u32 s1, s1, 0
	s_add_u32 s4, s0, 0x8000
	s_addc_u32 s5, s1, 0
	s_waitcnt vmcnt(63)
	v_lshlrev_b32_e32 v26, 2, v10
	v_fma_f32 v27, v32, v8, v78
	v_mul_f32_e32 v70, v80, v27
	v_lshlrev_b32_e32 v9, 16, v9
	v_mul_f32_e32 v84, 0xbfb8aa3b, v9
	v_exp_f32_e32 v84, v84
	s_nop 0
	v_add_f32_e32 v84, 1.0, v84
	v_div_scale_f32 v71, s[74:75], v84, v84, v9
	v_rcp_f32_e32 v82, v71
	s_nop 0
	v_fma_f32 v92, -v71, v82, 1.0
	v_fmac_f32_e32 v82, v92, v82
	v_div_scale_f32 v88, vcc, v9, v84, v9
	v_mul_f32_e32 v90, v88, v82
	v_fma_f32 v92, -v71, v90, v88
	v_fmac_f32_e32 v90, v92, v82
	v_fma_f32 v71, -v71, v90, v88
	v_div_fmas_f32 v71, v71, v82, v90
	v_div_fixup_f32 v9, v71, v84, v9
	v_mul_f32_e32 v70, v70, v9
	v_fma_f32 v27, v34, v8, v79
	v_mul_f32_e32 v110, v86, v27
	v_lshlrev_b32_e32 v11, 16, v11
	v_mul_f32_e32 v84, 0xbfb8aa3b, v11
	v_exp_f32_e32 v84, v84
	s_nop 0
	v_add_f32_e32 v84, 1.0, v84
	v_div_scale_f32 v71, s[74:75], v84, v84, v11
	v_rcp_f32_e32 v82, v71
	s_nop 0
	v_fma_f32 v92, -v71, v82, 1.0
	v_fmac_f32_e32 v82, v92, v82
	v_div_scale_f32 v88, vcc, v11, v84, v11
	v_mul_f32_e32 v90, v88, v82
	v_fma_f32 v92, -v71, v90, v88
	v_fmac_f32_e32 v90, v92, v82
	v_fma_f32 v71, -v71, v90, v88
	v_div_fmas_f32 v71, v71, v82, v90
	v_div_fixup_f32 v11, v71, v84, v11
	v_mul_f32_e32 v110, v110, v11
	v_cvt_pk_bf16_f32 v70, v70, v110
	v_perm_b32 v110, v70, v198, s98
	v_perm_b32 v70, v70, v198, s99
	global_store_dword v26, v110, s[0:1]
	global_store_dword v26, v70, s[4:5]
	v_add_u32_e32 v26, 0x800, v26
	v_lshlrev_b32_e32 v15, 16, v15
	v_lshlrev_b32_e32 v81, 16, v81
	v_lshlrev_b32_e32 v13, 16, v13
	v_mul_f32_e32 v13, v16, v13
	v_fmac_f32_e32 v13, v14, v15
	v_fmac_f32_e32 v13, v17, v81
	v_add_f32_e32 v13, v12, v13
	v_fma_f32 v27, v33, v8, v76
	v_mul_f32_e32 v70, v27, v13
	v_lshlrev_b32_e32 v89, 16, v89
	v_mul_f32_e32 v84, 0xbfb8aa3b, v89
	v_exp_f32_e32 v84, v84
	s_nop 0
	v_add_f32_e32 v84, 1.0, v84
	v_div_scale_f32 v71, s[74:75], v84, v84, v89
	v_rcp_f32_e32 v82, v71
	s_nop 0
	v_fma_f32 v92, -v71, v82, 1.0
	v_fmac_f32_e32 v82, v92, v82
	v_div_scale_f32 v88, vcc, v89, v84, v89
	v_mul_f32_e32 v90, v88, v82
	v_fma_f32 v92, -v71, v90, v88
	v_fmac_f32_e32 v90, v92, v82
	v_fma_f32 v71, -v71, v90, v88
	v_div_fmas_f32 v71, v71, v82, v90
	v_div_fixup_f32 v89, v71, v84, v89
	v_mul_f32_e32 v70, v70, v89
	v_lshlrev_b32_e32 v85, 16, v85
	v_lshlrev_b32_e32 v87, 16, v87
	v_lshlrev_b32_e32 v83, 16, v83
	v_mul_f32_e32 v83, v16, v83
	v_fmac_f32_e32 v83, v14, v85
	v_fmac_f32_e32 v83, v17, v87
	v_add_f32_e32 v83, v12, v83
	v_fma_f32 v27, v35, v8, v77
	v_mul_f32_e32 v110, v27, v83
	v_lshlrev_b32_e32 v91, 16, v91
	v_mul_f32_e32 v84, 0xbfb8aa3b, v91
	v_exp_f32_e32 v84, v84
	s_nop 0
	v_add_f32_e32 v84, 1.0, v84
	v_div_scale_f32 v71, s[74:75], v84, v84, v91
	v_rcp_f32_e32 v82, v71
	s_nop 0
	v_fma_f32 v92, -v71, v82, 1.0
	v_fmac_f32_e32 v82, v92, v82
	v_div_scale_f32 v88, vcc, v91, v84, v91
	v_mul_f32_e32 v90, v88, v82
	v_fma_f32 v92, -v71, v90, v88
	v_fmac_f32_e32 v90, v92, v82
	v_fma_f32 v71, -v71, v90, v88
	v_div_fmas_f32 v71, v71, v82, v90
	v_div_fixup_f32 v91, v71, v84, v91
	v_mul_f32_e32 v110, v110, v91
	v_cvt_pk_bf16_f32 v70, v70, v110
	v_perm_b32 v110, v70, v199, s98
	v_perm_b32 v70, v70, v199, s99
	global_store_dword v26, v110, s[0:1]
	global_store_dword v26, v70, s[4:5]
	v_add_u32_e32 v26, 0x800, v26
	v_lshlrev_b32_e32 v94, 16, v94
	v_lshlrev_b32_e32 v95, 16, v95
	v_lshlrev_b32_e32 v93, 16, v93
	v_mul_f32_e32 v93, v16, v93
	v_fmac_f32_e32 v93, v14, v94
	v_fmac_f32_e32 v93, v17, v95
	v_add_f32_e32 v93, v12, v93
	v_fma_f32 v27, v37, v8, v72
	v_mul_f32_e32 v70, v27, v93
	v_lshlrev_b32_e32 v99, 16, v99
	v_mul_f32_e32 v84, 0xbfb8aa3b, v99
	v_exp_f32_e32 v84, v84
	s_nop 0
	v_add_f32_e32 v84, 1.0, v84
	v_div_scale_f32 v71, s[74:75], v84, v84, v99
	v_rcp_f32_e32 v82, v71
	s_nop 0
	v_fma_f32 v92, -v71, v82, 1.0
	v_fmac_f32_e32 v82, v92, v82
	v_div_scale_f32 v88, vcc, v99, v84, v99
	v_mul_f32_e32 v90, v88, v82
	v_fma_f32 v92, -v71, v90, v88
	v_fmac_f32_e32 v90, v92, v82
	v_fma_f32 v71, -v71, v90, v88
	v_div_fmas_f32 v71, v71, v82, v90
	v_div_fixup_f32 v99, v71, v84, v99
	v_mul_f32_e32 v70, v70, v99
	v_lshlrev_b32_e32 v97, 16, v97
	v_lshlrev_b32_e32 v98, 16, v98
	v_lshlrev_b32_e32 v96, 16, v96
	v_mul_f32_e32 v96, v16, v96
	v_fmac_f32_e32 v96, v14, v97
	v_fmac_f32_e32 v96, v17, v98
	v_add_f32_e32 v96, v12, v96
	v_fma_f32 v27, v31, v8, v73
	v_mul_f32_e32 v110, v27, v96
	v_lshlrev_b32_e32 v100, 16, v100
	v_mul_f32_e32 v84, 0xbfb8aa3b, v100
	v_exp_f32_e32 v84, v84
	s_nop 0
	v_add_f32_e32 v84, 1.0, v84
	v_div_scale_f32 v71, s[74:75], v84, v84, v100
	v_rcp_f32_e32 v82, v71
	s_nop 0
	v_fma_f32 v92, -v71, v82, 1.0
	v_fmac_f32_e32 v82, v92, v82
	v_div_scale_f32 v88, vcc, v100, v84, v100
	v_mul_f32_e32 v90, v88, v82
	v_fma_f32 v92, -v71, v90, v88
	v_fmac_f32_e32 v90, v92, v82
	v_fma_f32 v71, -v71, v90, v88
	v_div_fmas_f32 v71, v71, v82, v90
	v_div_fixup_f32 v100, v71, v84, v100
	v_mul_f32_e32 v110, v110, v100
	v_cvt_pk_bf16_f32 v70, v70, v110
	v_perm_b32 v110, v70, v200, s98
	v_perm_b32 v70, v70, v200, s99
	global_store_dword v26, v110, s[0:1]
	global_store_dword v26, v70, s[4:5]
	v_add_u32_e32 v26, 0x800, v26
	v_lshlrev_b32_e32 v102, 16, v102
	v_lshlrev_b32_e32 v103, 16, v103
	v_lshlrev_b32_e32 v101, 16, v101
	v_mul_f32_e32 v101, v16, v101
	v_fmac_f32_e32 v101, v14, v102
	v_fmac_f32_e32 v101, v17, v103
	v_add_f32_e32 v101, v12, v101
	v_fma_f32 v27, v36, v8, v74
	v_mul_f32_e32 v70, v27, v101
	v_lshlrev_b32_e32 v107, 16, v107
	v_mul_f32_e32 v84, 0xbfb8aa3b, v107
	v_exp_f32_e32 v84, v84
	s_nop 0
	v_add_f32_e32 v84, 1.0, v84
	v_div_scale_f32 v71, s[74:75], v84, v84, v107
	v_rcp_f32_e32 v82, v71
	s_nop 0
	v_fma_f32 v92, -v71, v82, 1.0
	v_fmac_f32_e32 v82, v92, v82
	v_div_scale_f32 v88, vcc, v107, v84, v107
	v_mul_f32_e32 v90, v88, v82
	v_fma_f32 v92, -v71, v90, v88
	v_fmac_f32_e32 v90, v92, v82
	v_fma_f32 v71, -v71, v90, v88
	v_div_fmas_f32 v71, v71, v82, v90
	v_div_fixup_f32 v107, v71, v84, v107
	v_mul_f32_e32 v70, v70, v107
	v_lshlrev_b32_e32 v105, 16, v105
	v_lshlrev_b32_e32 v106, 16, v106
	v_lshlrev_b32_e32 v104, 16, v104
	v_mul_f32_e32 v104, v16, v104
	v_fmac_f32_e32 v104, v14, v105
	v_fmac_f32_e32 v104, v17, v106
	v_add_f32_e32 v104, v12, v104
	v_fma_f32 v27, v30, v8, v75
	v_mul_f32_e32 v110, v27, v104
	v_lshlrev_b32_e32 v108, 16, v108
	v_mul_f32_e32 v84, 0xbfb8aa3b, v108
	v_exp_f32_e32 v84, v84
	s_nop 0
	v_add_f32_e32 v84, 1.0, v84
	v_div_scale_f32 v71, s[74:75], v84, v84, v108
	v_rcp_f32_e32 v82, v71
	s_nop 0
	v_fma_f32 v92, -v71, v82, 1.0
	v_fmac_f32_e32 v82, v92, v82
	v_div_scale_f32 v88, vcc, v108, v84, v108
	v_mul_f32_e32 v90, v88, v82
	v_fma_f32 v92, -v71, v90, v88
	v_fmac_f32_e32 v90, v92, v82
	v_fma_f32 v71, -v71, v90, v88
	v_div_fmas_f32 v71, v71, v82, v90
	v_div_fixup_f32 v108, v71, v84, v108
	v_mul_f32_e32 v110, v110, v108
	v_cvt_pk_bf16_f32 v70, v70, v110
	v_perm_b32 v110, v70, v201, s98
	v_perm_b32 v70, v70, v201, s99
	global_store_dword v26, v110, s[0:1]
	global_store_dword v26, v70, s[4:5]
	s_waitcnt vmcnt(63)
	v_add_u32_e32 v26, 0x800, v26
	v_lshlrev_b32_e32 v112, 16, v112
	v_lshlrev_b32_e32 v113, 16, v113
	v_lshlrev_b32_e32 v111, 16, v111
	v_mul_f32_e32 v111, v16, v111
	v_fmac_f32_e32 v111, v14, v112
	v_fmac_f32_e32 v111, v17, v113
	v_add_f32_e32 v111, v12, v111
	v_fma_f32 v27, v39, v8, v66
	v_mul_f32_e32 v70, v27, v111
	v_lshlrev_b32_e32 v117, 16, v117
	v_mul_f32_e32 v84, 0xbfb8aa3b, v117
	v_exp_f32_e32 v84, v84
	s_nop 0
	v_add_f32_e32 v84, 1.0, v84
	v_div_scale_f32 v71, s[74:75], v84, v84, v117
	v_rcp_f32_e32 v82, v71
	s_nop 0
	v_fma_f32 v92, -v71, v82, 1.0
	v_fmac_f32_e32 v82, v92, v82
	v_div_scale_f32 v88, vcc, v117, v84, v117
	v_mul_f32_e32 v90, v88, v82
	v_fma_f32 v92, -v71, v90, v88
	v_fmac_f32_e32 v90, v92, v82
	v_fma_f32 v71, -v71, v90, v88
	v_div_fmas_f32 v71, v71, v82, v90
	v_div_fixup_f32 v117, v71, v84, v117
	v_mul_f32_e32 v70, v70, v117
	v_lshlrev_b32_e32 v115, 16, v115
	v_lshlrev_b32_e32 v116, 16, v116
	v_lshlrev_b32_e32 v114, 16, v114
	v_mul_f32_e32 v114, v16, v114
	v_fmac_f32_e32 v114, v14, v115
	v_fmac_f32_e32 v114, v17, v116
	v_add_f32_e32 v114, v12, v114
	v_fma_f32 v27, v41, v8, v67
	v_mul_f32_e32 v110, v27, v114
	v_lshlrev_b32_e32 v118, 16, v118
	v_mul_f32_e32 v84, 0xbfb8aa3b, v118
	v_exp_f32_e32 v84, v84
	s_nop 0
	v_add_f32_e32 v84, 1.0, v84
	v_div_scale_f32 v71, s[74:75], v84, v84, v118
	v_rcp_f32_e32 v82, v71
	s_nop 0
	v_fma_f32 v92, -v71, v82, 1.0
	v_fmac_f32_e32 v82, v92, v82
	v_div_scale_f32 v88, vcc, v118, v84, v118
	v_mul_f32_e32 v90, v88, v82
	v_fma_f32 v92, -v71, v90, v88
	v_fmac_f32_e32 v90, v92, v82
	v_fma_f32 v71, -v71, v90, v88
	v_div_fmas_f32 v71, v71, v82, v90
	v_div_fixup_f32 v118, v71, v84, v118
	v_mul_f32_e32 v110, v110, v118
	v_cvt_pk_bf16_f32 v70, v70, v110
	v_perm_b32 v110, v70, v202, s98
	v_perm_b32 v70, v70, v202, s99
	global_store_dword v26, v110, s[0:1]
	global_store_dword v26, v70, s[4:5]
	v_add_u32_e32 v26, 0x800, v26
	v_lshlrev_b32_e32 v120, 16, v120
	v_lshlrev_b32_e32 v121, 16, v121
	v_lshlrev_b32_e32 v119, 16, v119
	v_mul_f32_e32 v119, v16, v119
	v_fmac_f32_e32 v119, v14, v120
	v_fmac_f32_e32 v119, v17, v121
	v_add_f32_e32 v119, v12, v119
	v_fma_f32 v27, v38, v8, v68
	v_mul_f32_e32 v70, v27, v119
	v_lshlrev_b32_e32 v125, 16, v125
	v_mul_f32_e32 v84, 0xbfb8aa3b, v125
	v_exp_f32_e32 v84, v84
	s_nop 0
	v_add_f32_e32 v84, 1.0, v84
	v_div_scale_f32 v71, s[74:75], v84, v84, v125
	v_rcp_f32_e32 v82, v71
	s_nop 0
	v_fma_f32 v92, -v71, v82, 1.0
	v_fmac_f32_e32 v82, v92, v82
	v_div_scale_f32 v88, vcc, v125, v84, v125
	v_mul_f32_e32 v90, v88, v82
	v_fma_f32 v92, -v71, v90, v88
	v_fmac_f32_e32 v90, v92, v82
	v_fma_f32 v71, -v71, v90, v88
	v_div_fmas_f32 v71, v71, v82, v90
	v_div_fixup_f32 v125, v71, v84, v125
	v_mul_f32_e32 v70, v70, v125
	v_lshlrev_b32_e32 v123, 16, v123
	v_lshlrev_b32_e32 v124, 16, v124
	v_lshlrev_b32_e32 v122, 16, v122
	v_mul_f32_e32 v122, v16, v122
	v_fmac_f32_e32 v122, v14, v123
	v_fmac_f32_e32 v122, v17, v124
	v_add_f32_e32 v122, v12, v122
	v_fma_f32 v27, v40, v8, v69
	v_mul_f32_e32 v110, v27, v122
	v_lshlrev_b32_e32 v126, 16, v126
	v_mul_f32_e32 v84, 0xbfb8aa3b, v126
	v_exp_f32_e32 v84, v84
	s_nop 0
	v_add_f32_e32 v84, 1.0, v84
	v_div_scale_f32 v71, s[74:75], v84, v84, v126
	v_rcp_f32_e32 v82, v71
	s_nop 0
	v_fma_f32 v92, -v71, v82, 1.0
	v_fmac_f32_e32 v82, v92, v82
	v_div_scale_f32 v88, vcc, v126, v84, v126
	v_mul_f32_e32 v90, v88, v82
	v_fma_f32 v92, -v71, v90, v88
	v_fmac_f32_e32 v90, v92, v82
	v_fma_f32 v71, -v71, v90, v88
	v_div_fmas_f32 v71, v71, v82, v90
	v_div_fixup_f32 v126, v71, v84, v126
	v_mul_f32_e32 v110, v110, v126
	v_cvt_pk_bf16_f32 v70, v70, v110
	v_perm_b32 v110, v70, v203, s98
	v_perm_b32 v70, v70, v203, s99
	global_store_dword v26, v110, s[0:1]
	global_store_dword v26, v70, s[4:5]
	v_add_u32_e32 v26, 0x800, v26
	v_lshlrev_b32_e32 v128, 16, v128
	v_lshlrev_b32_e32 v129, 16, v129
	v_lshlrev_b32_e32 v127, 16, v127
	v_mul_f32_e32 v127, v16, v127
	v_fmac_f32_e32 v127, v14, v128
	v_fmac_f32_e32 v127, v17, v129
	v_add_f32_e32 v127, v12, v127
	v_fma_f32 v27, v43, v8, v62
	v_mul_f32_e32 v70, v27, v127
	v_lshlrev_b32_e32 v133, 16, v133
	v_mul_f32_e32 v84, 0xbfb8aa3b, v133
	v_exp_f32_e32 v84, v84
	s_nop 0
	v_add_f32_e32 v84, 1.0, v84
	v_div_scale_f32 v71, s[74:75], v84, v84, v133
	v_rcp_f32_e32 v82, v71
	s_nop 0
	v_fma_f32 v92, -v71, v82, 1.0
	v_fmac_f32_e32 v82, v92, v82
	v_div_scale_f32 v88, vcc, v133, v84, v133
	v_mul_f32_e32 v90, v88, v82
	v_fma_f32 v92, -v71, v90, v88
	v_fmac_f32_e32 v90, v92, v82
	v_fma_f32 v71, -v71, v90, v88
	v_div_fmas_f32 v71, v71, v82, v90
	v_div_fixup_f32 v133, v71, v84, v133
	v_mul_f32_e32 v70, v70, v133
	v_lshlrev_b32_e32 v131, 16, v131
	v_lshlrev_b32_e32 v132, 16, v132
	v_lshlrev_b32_e32 v130, 16, v130
	v_mul_f32_e32 v130, v16, v130
	v_fmac_f32_e32 v130, v14, v131
	v_fmac_f32_e32 v130, v17, v132
	v_add_f32_e32 v130, v12, v130
	v_fma_f32 v27, v45, v8, v63
	v_mul_f32_e32 v110, v27, v130
	v_lshlrev_b32_e32 v134, 16, v134
	v_mul_f32_e32 v84, 0xbfb8aa3b, v134
	v_exp_f32_e32 v84, v84
	s_nop 0
	v_add_f32_e32 v84, 1.0, v84
	v_div_scale_f32 v71, s[74:75], v84, v84, v134
	v_rcp_f32_e32 v82, v71
	s_nop 0
	v_fma_f32 v92, -v71, v82, 1.0
	v_fmac_f32_e32 v82, v92, v82
	v_div_scale_f32 v88, vcc, v134, v84, v134
	v_mul_f32_e32 v90, v88, v82
	v_fma_f32 v92, -v71, v90, v88
	v_fmac_f32_e32 v90, v92, v82
	v_fma_f32 v71, -v71, v90, v88
	v_div_fmas_f32 v71, v71, v82, v90
	v_div_fixup_f32 v134, v71, v84, v134
	v_mul_f32_e32 v110, v110, v134
	v_cvt_pk_bf16_f32 v70, v70, v110
	v_perm_b32 v110, v70, v204, s98
	v_perm_b32 v70, v70, v204, s99
	global_store_dword v26, v110, s[0:1]
	global_store_dword v26, v70, s[4:5]
	v_add_u32_e32 v26, 0x800, v26
	v_lshlrev_b32_e32 v136, 16, v136
	v_lshlrev_b32_e32 v137, 16, v137
	v_lshlrev_b32_e32 v135, 16, v135
	v_mul_f32_e32 v135, v16, v135
	v_fmac_f32_e32 v135, v14, v136
	v_fmac_f32_e32 v135, v17, v137
	v_add_f32_e32 v135, v12, v135
	v_fma_f32 v27, v42, v8, v64
	v_mul_f32_e32 v70, v27, v135
	v_lshlrev_b32_e32 v141, 16, v141
	v_mul_f32_e32 v84, 0xbfb8aa3b, v141
	v_exp_f32_e32 v84, v84
	s_nop 0
	v_add_f32_e32 v84, 1.0, v84
	v_div_scale_f32 v71, s[74:75], v84, v84, v141
	v_rcp_f32_e32 v82, v71
	s_nop 0
	v_fma_f32 v92, -v71, v82, 1.0
	v_fmac_f32_e32 v82, v92, v82
	v_div_scale_f32 v88, vcc, v141, v84, v141
	v_mul_f32_e32 v90, v88, v82
	v_fma_f32 v92, -v71, v90, v88
	v_fmac_f32_e32 v90, v92, v82
	v_fma_f32 v71, -v71, v90, v88
	v_div_fmas_f32 v71, v71, v82, v90
	v_div_fixup_f32 v141, v71, v84, v141
	v_mul_f32_e32 v70, v70, v141
	v_lshlrev_b32_e32 v139, 16, v139
	v_lshlrev_b32_e32 v140, 16, v140
	v_lshlrev_b32_e32 v138, 16, v138
	v_mul_f32_e32 v138, v16, v138
	v_fmac_f32_e32 v138, v14, v139
	v_fmac_f32_e32 v138, v17, v140
	v_add_f32_e32 v138, v12, v138
	v_fma_f32 v27, v44, v8, v65
	v_mul_f32_e32 v110, v27, v138
	v_lshlrev_b32_e32 v142, 16, v142
	v_mul_f32_e32 v84, 0xbfb8aa3b, v142
	v_exp_f32_e32 v84, v84
	s_nop 0
	v_add_f32_e32 v84, 1.0, v84
	v_div_scale_f32 v71, s[74:75], v84, v84, v142
	v_rcp_f32_e32 v82, v71
	s_nop 0
	v_fma_f32 v92, -v71, v82, 1.0
	v_fmac_f32_e32 v82, v92, v82
	v_div_scale_f32 v88, vcc, v142, v84, v142
	v_mul_f32_e32 v90, v88, v82
	v_fma_f32 v92, -v71, v90, v88
	v_fmac_f32_e32 v90, v92, v82
	v_fma_f32 v71, -v71, v90, v88
	v_div_fmas_f32 v71, v71, v82, v90
	v_div_fixup_f32 v142, v71, v84, v142
	v_mul_f32_e32 v110, v110, v142
	v_cvt_pk_bf16_f32 v70, v70, v110
	v_perm_b32 v110, v70, v205, s98
	v_perm_b32 v70, v70, v205, s99
	global_store_dword v26, v110, s[0:1]
	global_store_dword v26, v70, s[4:5]
	s_waitcnt vmcnt(48)
	v_add_u32_e32 v26, 0x800, v26
	v_lshlrev_b32_e32 v163, 16, v163
	v_lshlrev_b32_e32 v164, 16, v164
	v_lshlrev_b32_e32 v143, 16, v143
	v_mul_f32_e32 v143, v16, v143
	v_fmac_f32_e32 v143, v14, v163
	v_fmac_f32_e32 v143, v17, v164
	v_add_f32_e32 v143, v12, v143
	v_fma_f32 v27, v47, v8, v22
	v_mul_f32_e32 v70, v27, v143
	v_lshlrev_b32_e32 v168, 16, v168
	v_mul_f32_e32 v84, 0xbfb8aa3b, v168
	v_exp_f32_e32 v84, v84
	s_nop 0
	v_add_f32_e32 v84, 1.0, v84
	v_div_scale_f32 v71, s[74:75], v84, v84, v168
	v_rcp_f32_e32 v82, v71
	s_nop 0
	v_fma_f32 v92, -v71, v82, 1.0
	v_fmac_f32_e32 v82, v92, v82
	v_div_scale_f32 v88, vcc, v168, v84, v168
	v_mul_f32_e32 v90, v88, v82
	v_fma_f32 v92, -v71, v90, v88
	v_fmac_f32_e32 v90, v92, v82
	v_fma_f32 v71, -v71, v90, v88
	v_div_fmas_f32 v71, v71, v82, v90
	v_div_fixup_f32 v168, v71, v84, v168
	v_mul_f32_e32 v70, v70, v168
	v_lshlrev_b32_e32 v166, 16, v166
	v_lshlrev_b32_e32 v167, 16, v167
	v_lshlrev_b32_e32 v165, 16, v165
	v_mul_f32_e32 v165, v16, v165
	v_fmac_f32_e32 v165, v14, v166
	v_fmac_f32_e32 v165, v17, v167
	v_add_f32_e32 v165, v12, v165
	v_fma_f32 v27, v49, v8, v23
	v_mul_f32_e32 v110, v27, v165
	v_lshlrev_b32_e32 v169, 16, v169
	v_mul_f32_e32 v84, 0xbfb8aa3b, v169
	v_exp_f32_e32 v84, v84
	s_nop 0
	v_add_f32_e32 v84, 1.0, v84
	v_div_scale_f32 v71, s[74:75], v84, v84, v169
	v_rcp_f32_e32 v82, v71
	s_nop 0
	v_fma_f32 v92, -v71, v82, 1.0
	v_fmac_f32_e32 v82, v92, v82
	v_div_scale_f32 v88, vcc, v169, v84, v169
	v_mul_f32_e32 v90, v88, v82
	v_fma_f32 v92, -v71, v90, v88
	v_fmac_f32_e32 v90, v92, v82
	v_fma_f32 v71, -v71, v90, v88
	v_div_fmas_f32 v71, v71, v82, v90
	v_div_fixup_f32 v169, v71, v84, v169
	v_mul_f32_e32 v110, v110, v169
	v_cvt_pk_bf16_f32 v70, v70, v110
	v_perm_b32 v110, v70, v206, s98
	v_perm_b32 v70, v70, v206, s99
	global_store_dword v26, v110, s[0:1]
	global_store_dword v26, v70, s[4:5]
	v_add_u32_e32 v26, 0x800, v26
	v_lshlrev_b32_e32 v171, 16, v171
	v_lshlrev_b32_e32 v172, 16, v172
	v_lshlrev_b32_e32 v170, 16, v170
	v_mul_f32_e32 v170, v16, v170
	v_fmac_f32_e32 v170, v14, v171
	v_fmac_f32_e32 v170, v17, v172
	v_add_f32_e32 v170, v12, v170
	v_fma_f32 v27, v46, v8, v24
	v_mul_f32_e32 v70, v27, v170
	v_lshlrev_b32_e32 v176, 16, v176
	v_mul_f32_e32 v84, 0xbfb8aa3b, v176
	v_exp_f32_e32 v84, v84
	s_nop 0
	v_add_f32_e32 v84, 1.0, v84
	v_div_scale_f32 v71, s[74:75], v84, v84, v176
	v_rcp_f32_e32 v82, v71
	s_nop 0
	v_fma_f32 v92, -v71, v82, 1.0
	v_fmac_f32_e32 v82, v92, v82
	v_div_scale_f32 v88, vcc, v176, v84, v176
	v_mul_f32_e32 v90, v88, v82
	v_fma_f32 v92, -v71, v90, v88
	v_fmac_f32_e32 v90, v92, v82
	v_fma_f32 v71, -v71, v90, v88
	v_div_fmas_f32 v71, v71, v82, v90
	v_div_fixup_f32 v176, v71, v84, v176
	v_mul_f32_e32 v70, v70, v176
	v_lshlrev_b32_e32 v174, 16, v174
	v_lshlrev_b32_e32 v175, 16, v175
	v_lshlrev_b32_e32 v173, 16, v173
	v_mul_f32_e32 v173, v16, v173
	v_fmac_f32_e32 v173, v14, v174
	v_fmac_f32_e32 v173, v17, v175
	v_add_f32_e32 v173, v12, v173
	v_fma_f32 v27, v48, v8, v25
	v_mul_f32_e32 v110, v27, v173
	v_lshlrev_b32_e32 v177, 16, v177
	v_mul_f32_e32 v84, 0xbfb8aa3b, v177
	v_exp_f32_e32 v84, v84
	s_nop 0
	v_add_f32_e32 v84, 1.0, v84
	v_div_scale_f32 v71, s[74:75], v84, v84, v177
	v_rcp_f32_e32 v82, v71
	s_nop 0
	v_fma_f32 v92, -v71, v82, 1.0
	v_fmac_f32_e32 v82, v92, v82
	v_div_scale_f32 v88, vcc, v177, v84, v177
	v_mul_f32_e32 v90, v88, v82
	v_fma_f32 v92, -v71, v90, v88
	v_fmac_f32_e32 v90, v92, v82
	v_fma_f32 v71, -v71, v90, v88
	v_div_fmas_f32 v71, v71, v82, v90
	v_div_fixup_f32 v177, v71, v84, v177
	v_mul_f32_e32 v110, v110, v177
	v_cvt_pk_bf16_f32 v70, v70, v110
	v_perm_b32 v110, v70, v207, s98
	v_perm_b32 v70, v70, v207, s99
	global_store_dword v26, v110, s[0:1]
	global_store_dword v26, v70, s[4:5]
	v_add_u32_e32 v26, 0x800, v26
	v_lshlrev_b32_e32 v179, 16, v179
	v_lshlrev_b32_e32 v180, 16, v180
	v_lshlrev_b32_e32 v178, 16, v178
	v_mul_f32_e32 v178, v16, v178
	v_fmac_f32_e32 v178, v14, v179
	v_fmac_f32_e32 v178, v17, v180
	v_add_f32_e32 v178, v12, v178
	v_fma_f32 v27, v51, v8, v18
	v_mul_f32_e32 v70, v27, v178
	v_lshlrev_b32_e32 v184, 16, v184
	v_mul_f32_e32 v84, 0xbfb8aa3b, v184
	v_exp_f32_e32 v84, v84
	s_nop 0
	v_add_f32_e32 v84, 1.0, v84
	v_div_scale_f32 v71, s[74:75], v84, v84, v184
	v_rcp_f32_e32 v82, v71
	s_nop 0
	v_fma_f32 v92, -v71, v82, 1.0
	v_fmac_f32_e32 v82, v92, v82
	v_div_scale_f32 v88, vcc, v184, v84, v184
	v_mul_f32_e32 v90, v88, v82
	v_fma_f32 v92, -v71, v90, v88
	v_fmac_f32_e32 v90, v92, v82
	v_fma_f32 v71, -v71, v90, v88
	v_div_fmas_f32 v71, v71, v82, v90
	v_div_fixup_f32 v184, v71, v84, v184
	v_mul_f32_e32 v70, v70, v184
	v_lshlrev_b32_e32 v182, 16, v182
	v_lshlrev_b32_e32 v183, 16, v183
	v_lshlrev_b32_e32 v181, 16, v181
	v_mul_f32_e32 v181, v16, v181
	v_fmac_f32_e32 v181, v14, v182
	v_fmac_f32_e32 v181, v17, v183
	v_add_f32_e32 v181, v12, v181
	v_fma_f32 v27, v53, v8, v19
	v_mul_f32_e32 v110, v27, v181
	v_lshlrev_b32_e32 v185, 16, v185
	v_mul_f32_e32 v84, 0xbfb8aa3b, v185
	v_exp_f32_e32 v84, v84
	s_nop 0
	v_add_f32_e32 v84, 1.0, v84
	v_div_scale_f32 v71, s[74:75], v84, v84, v185
	v_rcp_f32_e32 v82, v71
	s_nop 0
	v_fma_f32 v92, -v71, v82, 1.0
	v_fmac_f32_e32 v82, v92, v82
	v_div_scale_f32 v88, vcc, v185, v84, v185
	v_mul_f32_e32 v90, v88, v82
	v_fma_f32 v92, -v71, v90, v88
	v_fmac_f32_e32 v90, v92, v82
	v_fma_f32 v71, -v71, v90, v88
	v_div_fmas_f32 v71, v71, v82, v90
	v_div_fixup_f32 v185, v71, v84, v185
	v_mul_f32_e32 v110, v110, v185
	v_cvt_pk_bf16_f32 v70, v70, v110
	v_perm_b32 v110, v70, v208, s98
	v_perm_b32 v70, v70, v208, s99
	global_store_dword v26, v110, s[0:1]
	global_store_dword v26, v70, s[4:5]
	v_add_u32_e32 v26, 0x800, v26
	v_lshlrev_b32_e32 v187, 16, v187
	v_lshlrev_b32_e32 v188, 16, v188
	v_lshlrev_b32_e32 v186, 16, v186
	v_mul_f32_e32 v186, v16, v186
	v_fmac_f32_e32 v186, v14, v187
	v_fmac_f32_e32 v186, v17, v188
	v_add_f32_e32 v186, v12, v186
	v_fma_f32 v27, v50, v8, v20
	v_mul_f32_e32 v70, v27, v186
	v_lshlrev_b32_e32 v192, 16, v192
	v_mul_f32_e32 v84, 0xbfb8aa3b, v192
	v_exp_f32_e32 v84, v84
	s_nop 0
	v_add_f32_e32 v84, 1.0, v84
	v_div_scale_f32 v71, s[74:75], v84, v84, v192
	v_rcp_f32_e32 v82, v71
	s_nop 0
	v_fma_f32 v92, -v71, v82, 1.0
	v_fmac_f32_e32 v82, v92, v82
	v_div_scale_f32 v88, vcc, v192, v84, v192
	v_mul_f32_e32 v90, v88, v82
	v_fma_f32 v92, -v71, v90, v88
	v_fmac_f32_e32 v90, v92, v82
	v_fma_f32 v71, -v71, v90, v88
	v_div_fmas_f32 v71, v71, v82, v90
	v_div_fixup_f32 v192, v71, v84, v192
	v_mul_f32_e32 v70, v70, v192
	v_lshlrev_b32_e32 v190, 16, v190
	v_lshlrev_b32_e32 v191, 16, v191
	v_lshlrev_b32_e32 v189, 16, v189
	v_mul_f32_e32 v189, v16, v189
	v_fmac_f32_e32 v189, v14, v190
	v_fmac_f32_e32 v189, v17, v191
	v_add_f32_e32 v189, v12, v189
	v_fma_f32 v27, v52, v8, v21
	v_mul_f32_e32 v110, v27, v189
	v_lshlrev_b32_e32 v193, 16, v193
	v_mul_f32_e32 v84, 0xbfb8aa3b, v193
	v_exp_f32_e32 v84, v84
	s_nop 0
	v_add_f32_e32 v84, 1.0, v84
	v_div_scale_f32 v71, s[74:75], v84, v84, v193
	v_rcp_f32_e32 v82, v71
	s_nop 0
	v_fma_f32 v92, -v71, v82, 1.0
	v_fmac_f32_e32 v82, v92, v82
	v_div_scale_f32 v88, vcc, v193, v84, v193
	v_mul_f32_e32 v90, v88, v82
	v_fma_f32 v92, -v71, v90, v88
	v_fmac_f32_e32 v90, v92, v82
	v_fma_f32 v71, -v71, v90, v88
	v_div_fmas_f32 v71, v71, v82, v90
	v_div_fixup_f32 v193, v71, v84, v193
	v_mul_f32_e32 v110, v110, v193
	v_cvt_pk_bf16_f32 v70, v70, v110
	v_perm_b32 v110, v70, v209, s98
	v_perm_b32 v70, v70, v209, s99
	global_store_dword v26, v110, s[0:1]
	global_store_dword v26, v70, s[4:5]
	s_waitcnt vmcnt(24)
	v_add_u32_e32 v26, 0x800, v26
	v_lshlrev_b32_e32 v195, 16, v195
	v_lshlrev_b32_e32 v196, 16, v196
	v_lshlrev_b32_e32 v194, 16, v194
	v_mul_f32_e32 v194, v16, v194
	v_fmac_f32_e32 v194, v14, v195
	v_fmac_f32_e32 v194, v17, v196
	v_add_f32_e32 v194, v12, v194
	v_fma_f32 v27, v55, v8, v4
	v_mul_f32_e32 v70, v27, v194
	v_lshlrev_b32_e32 v223, 16, v223
	v_mul_f32_e32 v84, 0xbfb8aa3b, v223
	v_exp_f32_e32 v84, v84
	s_nop 0
	v_add_f32_e32 v84, 1.0, v84
	v_div_scale_f32 v71, s[74:75], v84, v84, v223
	v_rcp_f32_e32 v82, v71
	s_nop 0
	v_fma_f32 v92, -v71, v82, 1.0
	v_fmac_f32_e32 v82, v92, v82
	v_div_scale_f32 v88, vcc, v223, v84, v223
	v_mul_f32_e32 v90, v88, v82
	v_fma_f32 v92, -v71, v90, v88
	v_fmac_f32_e32 v90, v92, v82
	v_fma_f32 v71, -v71, v90, v88
	v_div_fmas_f32 v71, v71, v82, v90
	v_div_fixup_f32 v223, v71, v84, v223
	v_mul_f32_e32 v70, v70, v223
	v_lshlrev_b32_e32 v221, 16, v221
	v_lshlrev_b32_e32 v222, 16, v222
	v_lshlrev_b32_e32 v197, 16, v197
	v_mul_f32_e32 v197, v16, v197
	v_fmac_f32_e32 v197, v14, v221
	v_fmac_f32_e32 v197, v17, v222
	v_add_f32_e32 v197, v12, v197
	v_fma_f32 v27, v57, v8, v5
	v_mul_f32_e32 v110, v27, v197
	v_lshlrev_b32_e32 v224, 16, v224
	v_mul_f32_e32 v84, 0xbfb8aa3b, v224
	v_exp_f32_e32 v84, v84
	s_nop 0
	v_add_f32_e32 v84, 1.0, v84
	v_div_scale_f32 v71, s[74:75], v84, v84, v224
	v_rcp_f32_e32 v82, v71
	s_nop 0
	v_fma_f32 v92, -v71, v82, 1.0
	v_fmac_f32_e32 v82, v92, v82
	v_div_scale_f32 v88, vcc, v224, v84, v224
	v_mul_f32_e32 v90, v88, v82
	v_fma_f32 v92, -v71, v90, v88
	v_fmac_f32_e32 v90, v92, v82
	v_fma_f32 v71, -v71, v90, v88
	v_div_fmas_f32 v71, v71, v82, v90
	v_div_fixup_f32 v224, v71, v84, v224
	v_mul_f32_e32 v110, v110, v224
	v_cvt_pk_bf16_f32 v70, v70, v110
	v_perm_b32 v110, v70, v210, s98
	v_perm_b32 v70, v70, v210, s99
	global_store_dword v26, v110, s[0:1]
	global_store_dword v26, v70, s[4:5]
	v_add_u32_e32 v26, 0x800, v26
	v_lshlrev_b32_e32 v226, 16, v226
	v_lshlrev_b32_e32 v227, 16, v227
	v_lshlrev_b32_e32 v225, 16, v225
	v_mul_f32_e32 v225, v16, v225
	v_fmac_f32_e32 v225, v14, v226
	v_fmac_f32_e32 v225, v17, v227
	v_add_f32_e32 v225, v12, v225
	v_fma_f32 v27, v54, v8, v6
	v_mul_f32_e32 v70, v27, v225
	v_lshlrev_b32_e32 v231, 16, v231
	v_mul_f32_e32 v84, 0xbfb8aa3b, v231
	v_exp_f32_e32 v84, v84
	s_nop 0
	v_add_f32_e32 v84, 1.0, v84
	v_div_scale_f32 v71, s[74:75], v84, v84, v231
	v_rcp_f32_e32 v82, v71
	s_nop 0
	v_fma_f32 v92, -v71, v82, 1.0
	v_fmac_f32_e32 v82, v92, v82
	v_div_scale_f32 v88, vcc, v231, v84, v231
	v_mul_f32_e32 v90, v88, v82
	v_fma_f32 v92, -v71, v90, v88
	v_fmac_f32_e32 v90, v92, v82
	v_fma_f32 v71, -v71, v90, v88
	v_div_fmas_f32 v71, v71, v82, v90
	v_div_fixup_f32 v231, v71, v84, v231
	v_mul_f32_e32 v70, v70, v231
	v_lshlrev_b32_e32 v229, 16, v229
	v_lshlrev_b32_e32 v230, 16, v230
	v_lshlrev_b32_e32 v228, 16, v228
	v_mul_f32_e32 v228, v16, v228
	v_fmac_f32_e32 v228, v14, v229
	v_fmac_f32_e32 v228, v17, v230
	v_add_f32_e32 v228, v12, v228
	v_fma_f32 v27, v56, v8, v7
	v_mul_f32_e32 v110, v27, v228
	v_lshlrev_b32_e32 v232, 16, v232
	v_mul_f32_e32 v84, 0xbfb8aa3b, v232
	v_exp_f32_e32 v84, v84
	s_nop 0
	v_add_f32_e32 v84, 1.0, v84
	v_div_scale_f32 v71, s[74:75], v84, v84, v232
	v_rcp_f32_e32 v82, v71
	s_nop 0
	v_fma_f32 v92, -v71, v82, 1.0
	v_fmac_f32_e32 v82, v92, v82
	v_div_scale_f32 v88, vcc, v232, v84, v232
	v_mul_f32_e32 v90, v88, v82
	v_fma_f32 v92, -v71, v90, v88
	v_fmac_f32_e32 v90, v92, v82
	v_fma_f32 v71, -v71, v90, v88
	v_div_fmas_f32 v71, v71, v82, v90
	v_div_fixup_f32 v232, v71, v84, v232
	v_mul_f32_e32 v110, v110, v232
	v_cvt_pk_bf16_f32 v70, v70, v110
	v_perm_b32 v110, v70, v211, s98
	v_perm_b32 v70, v70, v211, s99
	global_store_dword v26, v110, s[0:1]
	global_store_dword v26, v70, s[4:5]
	v_add_u32_e32 v26, 0x800, v26
	v_lshlrev_b32_e32 v234, 16, v234
	v_lshlrev_b32_e32 v235, 16, v235
	v_lshlrev_b32_e32 v233, 16, v233
	v_mul_f32_e32 v233, v16, v233
	v_fmac_f32_e32 v233, v14, v234
	v_fmac_f32_e32 v233, v17, v235
	v_add_f32_e32 v233, v12, v233
	v_fma_f32 v27, v59, v8, v0
	v_mul_f32_e32 v70, v27, v233
	v_lshlrev_b32_e32 v239, 16, v239
	v_mul_f32_e32 v84, 0xbfb8aa3b, v239
	v_exp_f32_e32 v84, v84
	s_nop 0
	v_add_f32_e32 v84, 1.0, v84
	v_div_scale_f32 v71, s[74:75], v84, v84, v239
	v_rcp_f32_e32 v82, v71
	s_nop 0
	v_fma_f32 v92, -v71, v82, 1.0
	v_fmac_f32_e32 v82, v92, v82
	v_div_scale_f32 v88, vcc, v239, v84, v239
	v_mul_f32_e32 v90, v88, v82
	v_fma_f32 v92, -v71, v90, v88
	v_fmac_f32_e32 v90, v92, v82
	v_fma_f32 v71, -v71, v90, v88
	v_div_fmas_f32 v71, v71, v82, v90
	v_div_fixup_f32 v239, v71, v84, v239
	v_mul_f32_e32 v70, v70, v239
	v_lshlrev_b32_e32 v237, 16, v237
	v_lshlrev_b32_e32 v238, 16, v238
	v_lshlrev_b32_e32 v236, 16, v236
	v_mul_f32_e32 v236, v16, v236
	v_fmac_f32_e32 v236, v14, v237
	v_fmac_f32_e32 v236, v17, v238
	v_add_f32_e32 v236, v12, v236
	v_fma_f32 v27, v61, v8, v1
	v_mul_f32_e32 v110, v27, v236
	v_lshlrev_b32_e32 v240, 16, v240
	v_mul_f32_e32 v84, 0xbfb8aa3b, v240
	v_exp_f32_e32 v84, v84
	s_nop 0
	v_add_f32_e32 v84, 1.0, v84
	v_div_scale_f32 v71, s[74:75], v84, v84, v240
	v_rcp_f32_e32 v82, v71
	s_nop 0
	v_fma_f32 v92, -v71, v82, 1.0
	v_fmac_f32_e32 v82, v92, v82
	v_div_scale_f32 v88, vcc, v240, v84, v240
	v_mul_f32_e32 v90, v88, v82
	v_fma_f32 v92, -v71, v90, v88
	v_fmac_f32_e32 v90, v92, v82
	v_fma_f32 v71, -v71, v90, v88
	v_div_fmas_f32 v71, v71, v82, v90
	v_div_fixup_f32 v240, v71, v84, v240
	v_mul_f32_e32 v110, v110, v240
	v_cvt_pk_bf16_f32 v70, v70, v110
	v_perm_b32 v110, v70, v212, s98
	v_perm_b32 v70, v70, v212, s99
	global_store_dword v26, v110, s[0:1]
	global_store_dword v26, v70, s[4:5]
	v_add_u32_e32 v26, 0x800, v26
	v_lshlrev_b32_e32 v242, 16, v242
	v_lshlrev_b32_e32 v243, 16, v243
	v_lshlrev_b32_e32 v241, 16, v241
	v_mul_f32_e32 v241, v16, v241
	v_mul_f32_e32 v243, v255, v243
	v_fmac_f32_e32 v241, v14, v242
	v_fmac_f32_e32 v241, v17, v243
	v_add_f32_e32 v241, v12, v241
	v_fma_f32 v27, v58, v8, v2
	v_mul_f32_e32 v70, v27, v241
	v_lshlrev_b32_e32 v247, 16, v247
	v_mul_f32_e32 v84, 0xbfb8aa3b, v247
	v_exp_f32_e32 v84, v84
	s_nop 0
	v_add_f32_e32 v84, 1.0, v84
	v_div_scale_f32 v71, s[74:75], v84, v84, v247
	v_rcp_f32_e32 v82, v71
	s_nop 0
	v_fma_f32 v92, -v71, v82, 1.0
	v_fmac_f32_e32 v82, v92, v82
	v_div_scale_f32 v88, vcc, v247, v84, v247
	v_mul_f32_e32 v90, v88, v82
	v_fma_f32 v92, -v71, v90, v88
	v_fmac_f32_e32 v90, v92, v82
	v_fma_f32 v71, -v71, v90, v88
	v_div_fmas_f32 v71, v71, v82, v90
	v_div_fixup_f32 v247, v71, v84, v247
	v_mul_f32_e32 v70, v70, v247
	v_lshlrev_b32_e32 v245, 16, v245
	v_lshlrev_b32_e32 v246, 16, v246
	v_lshlrev_b32_e32 v244, 16, v244
	v_mul_f32_e32 v244, v16, v244
	v_mul_f32_e32 v246, v255, v246
	v_fmac_f32_e32 v244, v14, v245
	v_fmac_f32_e32 v244, v17, v246
	v_add_f32_e32 v244, v12, v244
	v_fma_f32 v27, v60, v8, v3
	v_mul_f32_e32 v110, v27, v244
	v_lshlrev_b32_e32 v248, 16, v248
	v_mul_f32_e32 v84, 0xbfb8aa3b, v248
	v_exp_f32_e32 v84, v84
	s_nop 0
	v_add_f32_e32 v84, 1.0, v84
	v_div_scale_f32 v71, s[74:75], v84, v84, v248
	v_rcp_f32_e32 v82, v71
	s_nop 0
	v_fma_f32 v92, -v71, v82, 1.0
	v_fmac_f32_e32 v82, v92, v82
	v_div_scale_f32 v88, vcc, v248, v84, v248
	v_mul_f32_e32 v90, v88, v82
	v_fma_f32 v92, -v71, v90, v88
	v_fmac_f32_e32 v90, v92, v82
	v_fma_f32 v71, -v71, v90, v88
	v_div_fmas_f32 v71, v71, v82, v90
	v_div_fixup_f32 v248, v71, v84, v248
	v_mul_f32_e32 v110, v110, v248
	v_cvt_pk_bf16_f32 v70, v70, v110
	v_perm_b32 v110, v70, v213, s98
	v_perm_b32 v70, v70, v213, s99
	global_store_dword v26, v110, s[0:1]
	global_store_dword v26, v70, s[4:5]

.LBB0_991:
	v_and_b32_e32 v235, 31, v214
	v_bfe_u32 v236, v214, 5, 1
	v_lshrrev_b32_e32 v237, 6, v214
	v_lshlrev_b32_e32 v230, 16, v235
	v_lshl_or_b32 v230, v237, 7, v230
	v_lshl_or_b32 v230, v236, 4, v230
	v_and_b32_e32 v238, 3, v235
	v_lshrrev_b32_e32 v235, 2, v235
	v_lshlrev_b32_e32 v237, 12, v237
	v_lshl_or_b32 v237, v236, 9, v237
	v_lshl_or_b32 v237, v238, 2, v237
	v_add_u32_e32 v237, 16, v237
	v_lshlrev_b32_e32 v236, 1, v236
	v_xor_b32_e32 v235, v235, v236
	v_lshl_add_u32 v231, v235, 4, v237
	v_xor_b32_e32 v236, 1, v235
	v_lshl_add_u32 v232, v236, 4, v237
	v_xor_b32_e32 v236, 4, v235
	v_lshl_add_u32 v233, v236, 4, v237
	v_xor_b32_e32 v236, 5, v235
	v_lshl_add_u32 v234, v236, 4, v237
	s_lshl_b32 s0, s2, 8
	s_and_b32 s19, s0, 0x3f00
	s_lshl_b32 s0, s2, 2
	s_and_b32 s21, s9, 0xffffff00
	s_and_b32 s20, s0, 0xffffff00
	v_mov_b32_e32 v35, v176
	s_lshl_b32 s22, s19, 9
	s_lshl_b32 s0, s19, 10
	s_add_u32 s0, s7, s0
	v_lshlrev_b32_e32 v0, 3, v35
	v_ashrrev_i32_e32 v32, 3, v35
	s_addc_u32 s1, s8, 0
	s_mul_i32 s4, s20, 0xc00
	v_and_b32_e32 v34, 56, v0
	s_mul_hi_i32 s5, s20, 0xc00
	s_add_u32 s4, s3, s4
	v_lshlrev_b32_e32 v164, 1, v34
	v_ashrrev_i32_e32 v33, 31, v32
	s_addc_u32 s5, s6, s5
	v_lshl_add_u64 v[20:21], s[0:1], 0, v[164:165]
	v_lshlrev_b64 v[128:129], 10, v[32:33]
	v_lshl_add_u64 v[28:29], s[4:5], 0, v[164:165]
	v_lshl_add_u64 v[8:9], v[20:21], 0, v[128:129]
	s_barrier
	v_mad_i64_i32 v[10:11], s[0:1], v32, s11, v[28:29]
	global_load_dwordx4 v[0:3], v[8:9], off
	global_load_dwordx4 v[4:7], v[10:11], off
	v_add_u32_e32 v8, 64, v32
	v_ashrrev_i32_e32 v9, 31, v8
	v_add_u32_e32 v22, 0x80, v32
	v_add_u32_e32 v36, 0xc0, v32
	v_lshlrev_b64 v[130:131], 10, v[8:9]
	v_ashrrev_i32_e32 v23, 31, v22
	v_ashrrev_i32_e32 v37, 31, v36
	v_lshl_add_u64 v[16:17], v[20:21], 0, v[130:131]
	v_lshlrev_b64 v[132:133], 10, v[22:23]
	v_lshlrev_b64 v[134:135], 10, v[36:37]
	v_mad_i64_i32 v[18:19], s[0:1], v8, s11, v[28:29]
	global_load_dwordx4 v[8:11], v[16:17], off
	global_load_dwordx4 v[12:15], v[18:19], off
	v_lshl_add_u64 v[16:17], v[20:21], 0, v[132:133]
	v_lshl_add_u64 v[38:39], v[20:21], 0, v[134:135]
	global_load_dwordx4 v[16:19], v[16:17], off
	v_mad_i64_i32 v[30:31], s[0:1], v22, s11, v[28:29]
	global_load_dwordx4 v[20:23], v[38:39], off
	global_load_dwordx4 v[24:27], v[30:31], off
	v_mad_i64_i32 v[28:29], s[0:1], v36, s11, v[28:29]
	global_load_dwordx4 v[28:31], v[28:29], off
	v_lshrrev_b32_e32 v33, 5, v35
	v_bfe_u32 v38, v35, 1, 3
	v_lshrrev_b32_e32 v40, 1, v32
	v_bitop3_b32 v33, v33, v38, 1 bitop3:0x6c
	v_xor_b32_e32 v40, v40, v35
	v_lshlrev_b32_e32 v39, 7, v32
	v_lshlrev_b32_e32 v143, 4, v33
	v_lshlrev_b32_e32 v33, 4, v40
	v_and_or_b32 v33, v33, s12, v39
	s_mul_hi_i32 s0, s21, 0xc00
	s_mulk_i32 s21, 0xc00
	v_bfe_u32 v168, v35, 5, 1
	v_add_u32_e32 v144, 16, v33
	v_mov_b32_e32 v36, s21
	v_mov_b32_e32 v37, s0
	v_ashrrev_i32_e32 v166, 8, v35
	v_and_b32_e32 v167, 31, v35
	v_bfe_u32 v169, v35, 6, 2
	v_bitop3_b32 v41, v168, v38, 2 bitop3:0x36
	v_bitop3_b32 v42, v168, v38, 4 bitop3:0x36
	v_lshlrev_b32_e32 v140, 14, v166
	v_lshlrev_b32_e32 v138, 7, v167
	v_lshlrev_b32_e32 v139, 13, v169
	v_lshlrev_b32_e32 v142, 4, v41
	v_lshlrev_b32_e32 v141, 4, v42
	s_lshl_b32 s21, s22, 1
	v_lshlrev_b32_e32 v164, 1, v34
	s_mov_b32 s22, 64
	s_mov_b32 s23, 0
	s_mov_b32 s4, 0
	v_mov_b32_e32 v33, v165
	v_mov_b32_e32 v34, v165
	v_mov_b32_e32 v39, v165
	v_mov_b32_e32 v40, v165
	v_mov_b32_e32 v41, v165
	v_mov_b32_e32 v42, v165
	v_mov_b32_e32 v43, v165
	v_mov_b32_e32 v44, v165
	v_mov_b32_e32 v45, v165
	v_mov_b32_e32 v46, v165
	v_mov_b32_e32 v47, v165
	s_waitcnt vmcnt(7)
	ds_write_b128 v144, v[0:3]
	s_waitcnt vmcnt(5)
	ds_write_b128 v144, v[8:11] offset:8192
	s_waitcnt vmcnt(3)
	ds_write_b128 v144, v[16:19] offset:16384
	s_waitcnt vmcnt(2)
	ds_write_b128 v144, v[20:23] offset:24576
	ds_write_b128 v144, v[4:7] offset:32768
	ds_write_b128 v144, v[12:15] offset:40960
	s_waitcnt vmcnt(1)
	ds_write_b128 v144, v[24:27] offset:49152
	s_waitcnt vmcnt(0)
	ds_write_b128 v144, v[28:31] offset:57344
	v_bitop3_b32 v0, v168, v38, 6 bitop3:0x36
	v_lshlrev_b32_e32 v170, 4, v0
	v_mad_i64_i32 v[0:1], s[0:1], v32, s11, v[36:37]
	v_and_b32_e32 v2, 7, v35
	v_lshl_or_b32 v0, v2, 4, v0
	v_lshl_add_u64 v[136:137], s[86:87], 0, v[0:1]
	s_mov_b64 s[0:1], 0
	v_mov_b32_e32 v0, v165
	v_mov_b32_e32 v1, v165
	v_mov_b32_e32 v2, v165
	v_mov_b32_e32 v3, v165
	v_mov_b32_e32 v4, v165
	v_mov_b32_e32 v5, v165
	v_mov_b32_e32 v6, v165
	v_mov_b32_e32 v7, v165
	v_mov_b32_e32 v8, v165
	v_mov_b32_e32 v9, v165
	v_mov_b32_e32 v10, v165
	v_mov_b32_e32 v11, v165
	v_mov_b32_e32 v12, v165
	v_mov_b32_e32 v13, v165
	v_mov_b32_e32 v14, v165
	v_mov_b32_e32 v15, v165
	v_mov_b32_e32 v16, v165
	v_mov_b32_e32 v17, v165
	v_mov_b32_e32 v18, v165
	v_mov_b32_e32 v19, v165
	v_mov_b32_e32 v20, v165
	v_mov_b32_e32 v21, v165
	v_mov_b32_e32 v22, v165
	v_mov_b32_e32 v23, v165
	v_mov_b32_e32 v24, v165
	v_mov_b32_e32 v25, v165
	v_mov_b32_e32 v26, v165
	v_mov_b32_e32 v27, v165
	v_mov_b32_e32 v28, v165
	v_mov_b32_e32 v29, v165
	v_mov_b32_e32 v30, v165
	v_mov_b32_e32 v31, v165
	v_mov_b32_e32 v32, v165
	v_mov_b32_e32 v35, v165
	v_mov_b32_e32 v36, v165
	v_mov_b32_e32 v37, v165
	v_mov_b32_e32 v38, v165
	v_mov_b32_e32 v48, v165
	v_mov_b32_e32 v49, v165
	v_mov_b32_e32 v50, v165
	v_mov_b32_e32 v51, v165
	v_mov_b32_e32 v52, v165
	v_mov_b32_e32 v53, v165
	v_mov_b32_e32 v54, v165
	v_mov_b32_e32 v55, v165
	v_mov_b32_e32 v56, v165
	v_mov_b32_e32 v57, v165
	v_mov_b32_e32 v58, v165
	v_mov_b32_e32 v59, v165
	v_mov_b32_e32 v60, v165
	v_mov_b32_e32 v61, v165
	v_mov_b32_e32 v62, v165
	v_mov_b32_e32 v63, v165
	v_mov_b32_e32 v64, v165
	v_mov_b32_e32 v65, v165
	v_mov_b32_e32 v66, v165
	v_mov_b32_e32 v67, v165
	v_mov_b32_e32 v68, v165
	v_mov_b32_e32 v69, v165
	v_mov_b32_e32 v70, v165
	v_mov_b32_e32 v71, v165
	v_mov_b32_e32 v72, v165
	v_mov_b32_e32 v73, v165
	v_mov_b32_e32 v74, v165
	v_mov_b32_e32 v75, v165
	v_mov_b32_e32 v76, v165
	v_mov_b32_e32 v77, v165
	v_mov_b32_e32 v78, v165
	v_mov_b32_e32 v79, v165
	v_mov_b32_e32 v80, v165
	v_mov_b32_e32 v81, v165
	v_mov_b32_e32 v82, v165
	v_mov_b32_e32 v83, v165
	v_mov_b32_e32 v84, v165
	v_mov_b32_e32 v85, v165
	v_mov_b32_e32 v86, v165
	v_mov_b32_e32 v87, v165
	v_mov_b32_e32 v88, v165
	v_mov_b32_e32 v89, v165
	v_mov_b32_e32 v90, v165
	v_mov_b32_e32 v91, v165
	v_mov_b32_e32 v92, v165
	v_mov_b32_e32 v93, v165
	v_mov_b32_e32 v94, v165
	v_mov_b32_e32 v95, v165
	v_mov_b32_e32 v96, v165
	v_mov_b32_e32 v97, v165
	v_mov_b32_e32 v98, v165
	v_mov_b32_e32 v99, v165
	v_mov_b32_e32 v100, v165
	v_mov_b32_e32 v101, v165
	v_mov_b32_e32 v102, v165
	v_mov_b32_e32 v103, v165
	v_mov_b32_e32 v104, v165
	v_mov_b32_e32 v105, v165
	v_mov_b32_e32 v106, v165
	v_mov_b32_e32 v107, v165
	v_mov_b32_e32 v108, v165
	v_mov_b32_e32 v109, v165
	v_mov_b32_e32 v110, v165
	v_mov_b32_e32 v111, v165
	v_mov_b32_e32 v112, v165
	v_mov_b32_e32 v113, v165
	v_mov_b32_e32 v114, v165
	v_mov_b32_e32 v115, v165
	v_mov_b32_e32 v116, v165
	v_mov_b32_e32 v117, v165
	v_mov_b32_e32 v118, v165
	v_mov_b32_e32 v119, v165
	v_mov_b32_e32 v120, v165
	v_mov_b32_e32 v121, v165
	v_mov_b32_e32 v122, v165
	v_mov_b32_e32 v123, v165
	v_mov_b32_e32 v124, v165
	v_mov_b32_e32 v125, v165
	v_mov_b32_e32 v126, v165
	v_mov_b32_e32 v127, v165
	s_waitcnt lgkmcnt(0)
	s_barrier
.LBB0_992:
	s_add_i32 s24, s4, 1
	s_and_b32 s5, s24, 56
	s_cmp_eq_u32 s5, 8
	s_cselect_b32 s5, s13, 0x3000000
	s_add_u32 s5, s86, s5
	s_addc_u32 s25, s87, 0
	s_cmp_lt_u32 s4, 7
	s_cselect_b32 s4, s8, s25
	s_cselect_b32 s5, s7, s5
	s_and_b32 s25, s22, 0x1c0
	s_add_u32 s5, s5, s21
	s_addc_u32 s26, s4, 0
	s_lshl_b32 s4, s25, 1
	s_add_u32 s4, s5, s4
	s_addc_u32 s5, s26, 0
	s_and_b32 s25, s23, 0x10000
	s_add_i32 s25, s25, 16
	v_add_u32_e32 v145, s25, v143
	v_add3_u32 v162, v145, v140, v138
	v_add3_u32 v145, v145, v139, v138
	ds_read_b128 v[146:149], v162
	ds_read_b128 v[150:153], v145 offset:32768
	ds_read_b128 v[154:157], v162 offset:4096
	ds_read_b128 v[158:161], v145 offset:36864
	s_waitcnt lgkmcnt(2)
	v_mfma_f32_32x32x16_bf16 v[112:127], v[146:149], v[150:153], v[112:127]
	v_add_u32_e32 v145, s25, v142
	s_add_i32 s23, s23, 0x10000
	s_waitcnt lgkmcnt(0)
	v_mfma_f32_32x32x16_bf16 v[96:111], v[146:149], v[158:161], v[96:111]
	v_mfma_f32_32x32x16_bf16 v[80:95], v[154:157], v[150:153], v[80:95]
	v_mfma_f32_32x32x16_bf16 v[64:79], v[154:157], v[158:161], v[64:79]
	ds_read_b128 v[146:149], v162 offset:8192
	ds_read_b128 v[154:157], v162 offset:12288
	v_add3_u32 v162, v145, v140, v138
	v_add3_u32 v145, v145, v139, v138
	s_waitcnt lgkmcnt(1)
	v_mfma_f32_32x32x16_bf16 v[48:63], v[146:149], v[150:153], v[48:63]
	v_mfma_f32_32x32x16_bf16 v[32:47], v[146:149], v[158:161], v[32:47]
	s_waitcnt lgkmcnt(0)
	v_mfma_f32_32x32x16_bf16 v[16:31], v[154:157], v[150:153], v[16:31]
	v_mfma_f32_32x32x16_bf16 v[0:15], v[154:157], v[158:161], v[0:15]
	ds_read_b128 v[146:149], v162
	ds_read_b128 v[150:153], v145 offset:32768
	ds_read_b128 v[154:157], v162 offset:4096
	ds_read_b128 v[158:161], v145 offset:36864
	v_add_u32_e32 v145, s25, v141
	s_waitcnt lgkmcnt(2)
	v_mfma_f32_32x32x16_bf16 v[112:127], v[146:149], v[150:153], v[112:127]
	s_waitcnt lgkmcnt(0)
	v_mfma_f32_32x32x16_bf16 v[96:111], v[146:149], v[158:161], v[96:111]
	v_mfma_f32_32x32x16_bf16 v[80:95], v[154:157], v[150:153], v[80:95]
	v_mfma_f32_32x32x16_bf16 v[64:79], v[154:157], v[158:161], v[64:79]
	ds_read_b128 v[146:149], v162 offset:8192
	ds_read_b128 v[154:157], v162 offset:12288
	v_add3_u32 v162, v145, v140, v138
	v_add3_u32 v145, v145, v139, v138
	s_waitcnt lgkmcnt(1)
	v_mfma_f32_32x32x16_bf16 v[48:63], v[146:149], v[150:153], v[48:63]
	v_mfma_f32_32x32x16_bf16 v[32:47], v[146:149], v[158:161], v[32:47]
	s_waitcnt lgkmcnt(0)
	v_mfma_f32_32x32x16_bf16 v[16:31], v[154:157], v[150:153], v[16:31]
	v_mfma_f32_32x32x16_bf16 v[0:15], v[154:157], v[158:161], v[0:15]
	ds_read_b128 v[146:149], v162
	ds_read_b128 v[150:153], v145 offset:32768
	ds_read_b128 v[154:157], v162 offset:4096
	ds_read_b128 v[158:161], v145 offset:36864
	v_add_u32_e32 v145, s25, v170
	v_add3_u32 v171, v145, v140, v138
	v_add3_u32 v145, v145, v139, v138
	s_waitcnt lgkmcnt(2)
	v_mfma_f32_32x32x16_bf16 v[112:127], v[146:149], v[150:153], v[112:127]
	s_waitcnt lgkmcnt(0)
	v_mfma_f32_32x32x16_bf16 v[96:111], v[146:149], v[158:161], v[96:111]
	v_mfma_f32_32x32x16_bf16 v[80:95], v[154:157], v[150:153], v[80:95]
	v_mfma_f32_32x32x16_bf16 v[64:79], v[154:157], v[158:161], v[64:79]
	ds_read_b128 v[146:149], v162 offset:8192
	ds_read_b128 v[154:157], v162 offset:12288
	v_lshl_add_u64 v[162:163], v[136:137], 0, s[0:1]
	v_add_co_u32_e32 v172, vcc, s14, v162
	s_nop 1
	v_addc_co_u32_e32 v173, vcc, 0, v163, vcc
	v_add_co_u32_e32 v174, vcc, s15, v162
	s_waitcnt lgkmcnt(1)
	v_mfma_f32_32x32x16_bf16 v[48:63], v[146:149], v[150:153], v[48:63]
	v_addc_co_u32_e32 v175, vcc, 0, v163, vcc
	v_add_co_u32_e32 v178, vcc, s16, v162
	s_nop 1
	v_addc_co_u32_e32 v179, vcc, 0, v163, vcc
	v_mfma_f32_32x32x16_bf16 v[32:47], v[146:149], v[158:161], v[32:47]
	v_add_co_u32_e32 v162, vcc, s17, v162
	s_nop 1
	v_addc_co_u32_e32 v163, vcc, 0, v163, vcc
	s_waitcnt lgkmcnt(0)
	v_mfma_f32_32x32x16_bf16 v[16:31], v[154:157], v[150:153], v[16:31]
	v_mfma_f32_32x32x16_bf16 v[0:15], v[154:157], v[158:161], v[0:15]
	ds_read_b128 v[146:149], v171
	ds_read_b128 v[150:153], v145 offset:32768
	ds_read_b128 v[154:157], v171 offset:4096
	ds_read_b128 v[158:161], v145 offset:36864
	s_waitcnt lgkmcnt(2)
	v_mfma_f32_32x32x16_bf16 v[112:127], v[146:149], v[150:153], v[112:127]
	s_waitcnt lgkmcnt(0)
	v_mfma_f32_32x32x16_bf16 v[96:111], v[146:149], v[158:161], v[96:111]
	global_load_dwordx4 v[146:149], v[172:173], off offset:128
	s_nop 0
	global_load_dwordx4 v[172:175], v[174:175], off offset:128
	s_nop 0
	global_load_dwordx4 v[178:181], v[178:179], off offset:128
	s_nop 0
	global_load_dwordx4 v[182:185], v[162:163], off offset:128
	v_lshl_add_u64 v[162:163], s[4:5], 0, v[164:165]
	v_lshl_add_u64 v[190:191], v[162:163], 0, v[128:129]
	v_lshl_add_u64 v[194:195], v[162:163], 0, v[130:131]
	v_lshl_add_u64 v[198:199], v[162:163], 0, v[132:133]
	v_lshl_add_u64 v[162:163], v[162:163], 0, v[134:135]
	s_and_b32 s98, s24, 56
	s_cmp_eq_u32 s98, 8
	s_cselect_b64 vcc, -1, 0
	s_sub_i32 s98, s24, 8
	s_lshl_b32 s98, s98, 21
	s_lshl_b32 s99, s19, 2
	s_add_u32 s98, s98, s99
	s_add_u32 s98, s98, 0xa000000
	s_add_u32 s98, s86, s98
	s_addc_u32 s99, s87, 0
	s_and_b32 s5, s23, 0x10000
	v_mfma_f32_32x32x16_bf16 v[80:95], v[154:157], v[150:153], v[80:95]
	s_add_u32 s0, s0, 0x80
	s_addc_u32 s1, s1, 0
	s_add_i32 s22, s22, 64
	s_mov_b32 s4, s24
	v_add_u32_e32 v145, s5, v144
	s_cmpk_lg_i32 s0, 0xb80
	v_mfma_f32_32x32x16_bf16 v[64:79], v[154:157], v[158:161], v[64:79]
	ds_read_b128 v[154:157], v171 offset:8192
	ds_read_b128 v[186:189], v171 offset:12288
	s_cbranch_vccnz .Lyb_ld_L1
	global_load_dwordx4 v[190:193], v[190:191], off
	s_nop 0
	global_load_dwordx4 v[194:197], v[194:195], off
	s_nop 0
	global_load_dwordx4 v[198:201], v[198:199], off
	s_waitcnt lgkmcnt(1)
	v_mfma_f32_32x32x16_bf16 v[48:63], v[154:157], v[150:153], v[48:63]
	v_mfma_f32_32x32x16_bf16 v[32:47], v[154:157], v[158:161], v[32:47]
	global_load_dwordx4 v[154:157], v[162:163], off
	s_branch .Lyb_ld_done_L1
.Lyb_ld_L1:
	global_load_dwordx4 v[190:193], v230, s[98:99]
	global_load_dwordx4 v[194:197], v230, s[98:99] offset:32
	global_load_dwordx4 v[198:201], v230, s[98:99] offset:64
	s_waitcnt lgkmcnt(1)
	v_mfma_f32_32x32x16_bf16 v[48:63], v[154:157], v[150:153], v[48:63]
	v_mfma_f32_32x32x16_bf16 v[32:47], v[154:157], v[158:161], v[32:47]
	global_load_dwordx4 v[154:157], v230, s[98:99] offset:96
.Lyb_ld_done_L1:
	s_waitcnt vmcnt(7)
	ds_write_b128 v145, v[146:149] offset:32768
	s_waitcnt vmcnt(6)
	ds_write_b128 v145, v[172:175] offset:40960
	s_waitcnt vmcnt(5)
	ds_write_b128 v145, v[178:181] offset:49152
	s_waitcnt vmcnt(4)
	ds_write_b128 v145, v[182:185] offset:57344
	s_cbranch_vccnz .Lyb_wr_L1
	s_waitcnt vmcnt(3)
	ds_write_b128 v145, v[190:193]
	s_waitcnt vmcnt(2)
	ds_write_b128 v145, v[194:197] offset:8192
	s_waitcnt vmcnt(1)
	ds_write_b128 v145, v[198:201] offset:16384
	s_waitcnt vmcnt(0)
	ds_write_b128 v145, v[154:157] offset:24576
	s_branch .Lyb_wr_done_L1
.Lyb_wr_L1:
	v_add_u32_e32 v235, s5, v231
	v_add_u32_e32 v236, s5, v232
	v_add_u32_e32 v237, s5, v233
	v_add_u32_e32 v238, s5, v234
	s_waitcnt vmcnt(3)
	ds_write_b32 v235, v190
	ds_write_b32 v235, v191 offset:128
	ds_write_b32 v236, v192 offset:256
	ds_write_b32 v236, v193 offset:384
	s_waitcnt vmcnt(2)
	ds_write_b32 v237, v194 offset:1024
	ds_write_b32 v237, v195 offset:1152
	ds_write_b32 v238, v196 offset:1280
	ds_write_b32 v238, v197 offset:1408
	s_waitcnt vmcnt(1)
	ds_write_b32 v235, v198 offset:2048
	ds_write_b32 v235, v199 offset:2176
	ds_write_b32 v236, v200 offset:2304
	ds_write_b32 v236, v201 offset:2432
	s_waitcnt vmcnt(0)
	ds_write_b32 v237, v154 offset:3072
	ds_write_b32 v237, v155 offset:3200
	ds_write_b32 v238, v156 offset:3328
	ds_write_b32 v238, v157 offset:3456
.Lyb_wr_done_L1:
	s_waitcnt lgkmcnt(8)
	v_mfma_f32_32x32x16_bf16 v[16:31], v[186:189], v[150:153], v[16:31]
	s_waitcnt lgkmcnt(0)
	s_barrier
	v_mfma_f32_32x32x16_bf16 v[0:15], v[186:189], v[158:161], v[0:15]
	s_cbranch_scc1 .LBB0_992
	s_add_i32 s0, 16, 0x10000
	v_add_u32_e32 v128, s0, v143
	v_add3_u32 v136, v128, v140, v138
	ds_read_b128 v[128:131], v136
	v_add_u32_e32 v132, s18, v143
	v_add3_u32 v137, v132, v139, v138
	ds_read_b128 v[132:135], v137
	ds_read_b128 v[144:147], v137 offset:4096
	ds_read_b128 v[148:151], v136 offset:4096
	v_lshl_or_b32 v164, v169, 6, s20
	v_lshl_add_u32 v166, v166, 7, s19
	s_waitcnt lgkmcnt(0)
	v_mfma_f32_32x32x16_bf16 v[80:95], v[148:151], v[132:135], v[80:95]
	v_lshl_or_b32 v166, v168, 2, v166
	v_ashrrev_i32_e32 v169, 31, v164
	v_or_b32_e32 v168, v164, v167
	v_ashrrev_i32_e32 v167, 31, v166
	v_lshlrev_b64 v[168:169], 2, v[168:169]
	s_add_i32 s2, s2, s50
	s_add_i32 s9, s9, s10
	v_mfma_f32_32x32x16_bf16 v[112:127], v[128:131], v[132:135], v[112:127]
	s_cmpk_lt_i32 s2, 0x100
	v_mfma_f32_32x32x16_bf16 v[96:111], v[128:131], v[144:147], v[96:111]
	ds_read_b128 v[128:131], v136 offset:8192
	ds_read_b128 v[152:155], v136 offset:12288
	v_add_u32_e32 v136, s0, v142
	v_add3_u32 v136, v136, v140, v138
	ds_read_b128 v[172:175], v136
	ds_read_b128 v[178:181], v136 offset:4096
	ds_read_b128 v[182:185], v136 offset:8192
	ds_read_b128 v[186:189], v136 offset:12288
	s_waitcnt lgkmcnt(5)
	v_mfma_f32_32x32x16_bf16 v[48:63], v[128:131], v[132:135], v[48:63]
	v_mfma_f32_32x32x16_bf16 v[32:47], v[128:131], v[144:147], v[32:47]
	v_add_u32_e32 v128, s18, v142
	v_add3_u32 v128, v128, v139, v138
	ds_read_b128 v[190:193], v128
	ds_read_b128 v[194:197], v128 offset:4096
	v_add_u32_e32 v128, s0, v141
	v_add3_u32 v128, v128, v140, v138
	v_mfma_f32_32x32x16_bf16 v[64:79], v[148:151], v[144:147], v[64:79]
	ds_read_b128 v[198:201], v128
	ds_read_b128 v[202:205], v128 offset:4096
	ds_read_b128 v[160:163], v128 offset:8192
	ds_read_b128 v[148:151], v128 offset:12288
	v_add_u32_e32 v128, s18, v141
	v_add3_u32 v128, v128, v139, v138
	s_waitcnt lgkmcnt(10)
	v_mfma_f32_32x32x16_bf16 v[16:31], v[152:155], v[132:135], v[16:31]
	v_add_u32_e32 v132, s18, v170
	v_add3_u32 v132, v132, v139, v138
	v_mfma_f32_32x32x16_bf16 v[0:15], v[152:155], v[144:147], v[0:15]
	ds_read_b128 v[156:159], v128
	ds_read_b128 v[152:155], v128 offset:4096
	v_add_u32_e32 v128, s0, v170
	v_lshl_add_u64 v[170:171], s[84:85], 0, v[168:169]
	v_add3_u32 v128, v128, v140, v138
	ds_read_b128 v[206:209], v128
	ds_read_b128 v[144:147], v128 offset:4096
	ds_read_b128 v[140:143], v128 offset:8192
	ds_read_b128 v[128:131], v128 offset:12288
	ds_read_b128 v[136:139], v132
	ds_read_b128 v[132:135], v132 offset:4096
	s_waitcnt lgkmcnt(0)
	v_mfma_f32_32x32x16_bf16 v[112:127], v[172:175], v[190:193], v[112:127]
	s_barrier
	v_mfma_f32_32x32x16_bf16 v[96:111], v[172:175], v[194:197], v[96:111]
	v_lshlrev_b64 v[172:173], 12, v[166:167]
	v_lshl_add_u64 v[172:173], v[170:171], 0, v[172:173]
	v_or_b32_e32 v170, 1, v166
	v_ashrrev_i32_e32 v171, 31, v170
	v_lshlrev_b64 v[170:171], 12, v[170:171]
	v_lshl_add_u64 v[170:171], s[84:85], 0, v[170:171]
	v_lshl_add_u64 v[174:175], v[170:171], 0, v[168:169]
	v_or_b32_e32 v170, 2, v166
	v_ashrrev_i32_e32 v171, 31, v170
	v_lshlrev_b64 v[170:171], 12, v[170:171]
	v_lshl_add_u64 v[170:171], s[84:85], 0, v[170:171]
	v_lshl_add_u64 v[210:211], v[170:171], 0, v[168:169]
	v_or_b32_e32 v170, 3, v166
	v_ashrrev_i32_e32 v171, 31, v170
	v_lshlrev_b64 v[170:171], 12, v[170:171]
	v_lshl_add_u64 v[170:171], s[84:85], 0, v[170:171]
	global_load_dword v164, v[172:173], off
	v_mfma_f32_32x32x16_bf16 v[112:127], v[198:201], v[156:159], v[112:127]
	v_lshl_add_u64 v[170:171], v[170:171], 0, v[168:169]
	v_mfma_f32_32x32x16_bf16 v[96:111], v[198:201], v[152:155], v[96:111]
	global_load_dword v167, v[172:173], off offset:128
	global_load_dword v177, v[174:175], off
	global_load_dword v198, v[174:175], off offset:128
	global_load_dword v199, v[210:211], off
	global_load_dword v200, v[210:211], off offset:128
	global_load_dword v201, v[170:171], off
	v_mfma_f32_32x32x16_bf16 v[96:111], v[206:209], v[132:135], v[96:111]
	v_mfma_f32_32x32x16_bf16 v[112:127], v[206:209], v[136:139], v[112:127]
	global_load_dword v206, v[170:171], off offset:128
	s_waitcnt vmcnt(6)
	s_nop 8
	v_add_f32_e32 v96, v96, v167
	global_store_dword v[172:173], v96, off offset:128
	s_waitcnt vmcnt(6)
	v_add_f32_e32 v96, v113, v177
	global_store_dword v[174:175], v96, off
	s_waitcnt vmcnt(6)
	v_add_f32_e32 v96, v97, v198
	global_store_dword v[174:175], v96, off offset:128
	s_waitcnt vmcnt(6)
	v_add_f32_e32 v96, v114, v199
	global_store_dword v[210:211], v96, off
	s_waitcnt vmcnt(6)
	v_add_f32_e32 v96, v98, v200
	global_store_dword v[210:211], v96, off offset:128
	s_waitcnt vmcnt(6)
	v_add_f32_e32 v96, v115, v201
	global_store_dword v[170:171], v96, off
	v_or_b32_e32 v96, 8, v166
	v_ashrrev_i32_e32 v97, 31, v96
	v_lshlrev_b64 v[96:97], 12, v[96:97]
	v_add_f32_e32 v112, v112, v164
	v_lshl_add_u64 v[96:97], s[84:85], 0, v[96:97]
	global_store_dword v[172:173], v112, off
	v_lshl_add_u64 v[112:113], v[96:97], 0, v[168:169]
	v_or_b32_e32 v96, 9, v166
	v_ashrrev_i32_e32 v97, 31, v96
	v_lshlrev_b64 v[96:97], 12, v[96:97]
	v_lshl_add_u64 v[96:97], s[84:85], 0, v[96:97]
	v_lshl_add_u64 v[114:115], v[96:97], 0, v[168:169]
	v_or_b32_e32 v96, 10, v166
	v_ashrrev_i32_e32 v97, 31, v96
	v_lshlrev_b64 v[96:97], 12, v[96:97]
	v_lshl_add_u64 v[96:97], s[84:85], 0, v[96:97]
	v_lshl_add_u64 v[172:173], v[96:97], 0, v[168:169]
	v_or_b32_e32 v96, 11, v166
	v_ashrrev_i32_e32 v97, 31, v96
	v_lshlrev_b64 v[96:97], 12, v[96:97]
	v_lshl_add_u64 v[96:97], s[84:85], 0, v[96:97]
	v_lshl_add_u64 v[174:175], v[96:97], 0, v[168:169]
	v_or_b32_e32 v96, 16, v166
	v_ashrrev_i32_e32 v97, 31, v96
	v_lshlrev_b64 v[96:97], 12, v[96:97]
	v_lshl_add_u64 v[96:97], s[84:85], 0, v[96:97]
	v_mfma_f32_32x32x16_bf16 v[80:95], v[178:181], v[190:193], v[80:95]
	s_waitcnt vmcnt(7)
	v_add_f32_e32 v99, v99, v206
	v_mfma_f32_32x32x16_bf16 v[64:79], v[178:181], v[194:197], v[64:79]
	v_lshl_add_u64 v[178:179], v[96:97], 0, v[168:169]
	v_or_b32_e32 v96, 17, v166
	v_ashrrev_i32_e32 v97, 31, v96
	v_lshlrev_b64 v[96:97], 12, v[96:97]
	v_lshl_add_u64 v[96:97], s[84:85], 0, v[96:97]
	v_lshl_add_u64 v[180:181], v[96:97], 0, v[168:169]
	v_or_b32_e32 v96, 18, v166
	v_ashrrev_i32_e32 v97, 31, v96
	v_lshlrev_b64 v[96:97], 12, v[96:97]
	v_lshl_add_u64 v[96:97], s[84:85], 0, v[96:97]
	v_mfma_f32_32x32x16_bf16 v[48:63], v[182:185], v[190:193], v[48:63]
	v_mfma_f32_32x32x16_bf16 v[32:47], v[182:185], v[194:197], v[32:47]
	v_lshl_add_u64 v[182:183], v[96:97], 0, v[168:169]
	v_or_b32_e32 v96, 19, v166
	v_ashrrev_i32_e32 v97, 31, v96
	v_lshlrev_b64 v[96:97], 12, v[96:97]
	v_lshl_add_u64 v[96:97], s[84:85], 0, v[96:97]
	v_lshl_add_u64 v[184:185], v[96:97], 0, v[168:169]
	v_or_b32_e32 v96, 24, v166
	v_ashrrev_i32_e32 v97, 31, v96
	v_lshlrev_b64 v[96:97], 12, v[96:97]
	v_lshl_add_u64 v[96:97], s[84:85], 0, v[96:97]
	v_mfma_f32_32x32x16_bf16 v[16:31], v[186:189], v[190:193], v[16:31]
	v_mfma_f32_32x32x16_bf16 v[0:15], v[186:189], v[194:197], v[0:15]
	v_lshl_add_u64 v[186:187], v[96:97], 0, v[168:169]
	v_or_b32_e32 v96, 25, v166
	v_ashrrev_i32_e32 v97, 31, v96
	v_lshlrev_b64 v[96:97], 12, v[96:97]
	v_lshl_add_u64 v[96:97], s[84:85], 0, v[96:97]
	global_load_dword v98, v[112:113], off
	global_load_dword v164, v[112:113], off offset:128
	global_load_dword v167, v[114:115], off
	global_load_dword v177, v[114:115], off offset:128
	global_load_dword v188, v[172:173], off
	global_load_dword v189, v[172:173], off offset:128
	global_load_dword v190, v[174:175], off
	global_load_dword v191, v[174:175], off offset:128
	global_load_dword v192, v[178:179], off
	global_load_dword v193, v[178:179], off offset:128
	global_load_dword v194, v[180:181], off
	global_load_dword v195, v[180:181], off offset:128
	global_load_dword v196, v[182:183], off
	global_load_dword v197, v[182:183], off offset:128
	global_load_dword v198, v[184:185], off
	global_load_dword v199, v[184:185], off offset:128
	v_mfma_f32_32x32x16_bf16 v[48:63], v[160:163], v[156:159], v[48:63]
	s_waitcnt vmcnt(15)
	v_add_f32_e32 v98, v116, v98
	v_mfma_f32_32x32x16_bf16 v[32:47], v[160:163], v[152:155], v[32:47]
	v_lshl_add_u64 v[160:161], v[96:97], 0, v[168:169]
	v_or_b32_e32 v96, 26, v166
	v_ashrrev_i32_e32 v97, 31, v96
	v_lshlrev_b64 v[96:97], 12, v[96:97]
	v_lshl_add_u64 v[96:97], s[84:85], 0, v[96:97]
	v_mfma_f32_32x32x16_bf16 v[80:95], v[202:205], v[156:159], v[80:95]
	v_mfma_f32_32x32x16_bf16 v[16:31], v[148:151], v[156:159], v[16:31]
	v_lshl_add_u64 v[156:157], v[96:97], 0, v[168:169]
	v_or_b32_e32 v96, 27, v166
	v_ashrrev_i32_e32 v97, 31, v96
	v_lshlrev_b64 v[96:97], 12, v[96:97]
	v_lshl_add_u64 v[96:97], s[84:85], 0, v[96:97]
	v_lshl_add_u64 v[158:159], v[96:97], 0, v[168:169]
	v_or_b32_e32 v96, 32, v166
	v_ashrrev_i32_e32 v97, 31, v96
	v_lshlrev_b64 v[96:97], 12, v[96:97]
	v_lshl_add_u64 v[96:97], s[84:85], 0, v[96:97]
	v_mfma_f32_32x32x16_bf16 v[64:79], v[202:205], v[152:155], v[64:79]
	v_mfma_f32_32x32x16_bf16 v[0:15], v[148:151], v[152:155], v[0:15]
	v_lshl_add_u64 v[148:149], v[96:97], 0, v[168:169]
	v_or_b32_e32 v96, 33, v166
	v_ashrrev_i32_e32 v97, 31, v96
	v_lshlrev_b64 v[96:97], 12, v[96:97]
	v_lshl_add_u64 v[96:97], s[84:85], 0, v[96:97]
	v_lshl_add_u64 v[150:151], v[96:97], 0, v[168:169]
	v_or_b32_e32 v96, 34, v166
	v_ashrrev_i32_e32 v97, 31, v96
	v_lshlrev_b64 v[96:97], 12, v[96:97]
	v_lshl_add_u64 v[96:97], s[84:85], 0, v[96:97]
	v_mfma_f32_32x32x16_bf16 v[80:95], v[144:147], v[136:139], v[80:95]
	global_load_dword v152, v[186:187], off
	global_load_dword v153, v[186:187], off offset:128
	global_load_dword v154, v[160:161], off
	global_load_dword v155, v[160:161], off offset:128
	global_load_dword v162, v[156:157], off
	global_load_dword v163, v[156:157], off offset:128
	global_load_dword v200, v[158:159], off
	global_load_dword v201, v[158:159], off offset:128
	v_mfma_f32_32x32x16_bf16 v[64:79], v[144:147], v[132:135], v[64:79]
	v_lshl_add_u64 v[144:145], v[96:97], 0, v[168:169]
	v_or_b32_e32 v96, 35, v166
	v_ashrrev_i32_e32 v97, 31, v96
	v_lshlrev_b64 v[96:97], 12, v[96:97]
	v_lshl_add_u64 v[96:97], s[84:85], 0, v[96:97]
	v_lshl_add_u64 v[146:147], v[96:97], 0, v[168:169]
	v_or_b32_e32 v96, 40, v166
	v_ashrrev_i32_e32 v97, 31, v96
	v_lshlrev_b64 v[96:97], 12, v[96:97]
	v_lshl_add_u64 v[96:97], s[84:85], 0, v[96:97]
	v_mfma_f32_32x32x16_bf16 v[48:63], v[140:143], v[136:139], v[48:63]
	global_load_dword v202, v[148:149], off
	global_load_dword v203, v[148:149], off offset:128
	global_load_dword v204, v[150:151], off
	global_load_dword v205, v[150:151], off offset:128
	global_load_dword v207, v[144:145], off
	global_load_dword v208, v[144:145], off offset:128
	global_load_dword v209, v[146:147], off
	global_load_dword v210, v[146:147], off offset:128
	s_waitcnt vmcnt(7)
	v_add_f32_e32 v80, v80, v202
	v_mfma_f32_32x32x16_bf16 v[32:47], v[140:143], v[132:135], v[32:47]
	v_lshl_add_u64 v[140:141], v[96:97], 0, v[168:169]
	v_or_b32_e32 v96, 41, v166
	v_ashrrev_i32_e32 v97, 31, v96
	v_lshlrev_b64 v[96:97], 12, v[96:97]
	v_lshl_add_u64 v[96:97], s[84:85], 0, v[96:97]
	global_load_dword v142, v[140:141], off
	s_waitcnt vmcnt(7)
	v_add_f32_e32 v64, v64, v203
	v_mfma_f32_32x32x16_bf16 v[16:31], v[128:131], v[136:139], v[16:31]
	v_lshl_add_u64 v[136:137], v[96:97], 0, v[168:169]
	v_or_b32_e32 v96, 42, v166
	v_ashrrev_i32_e32 v97, 31, v96
	v_lshlrev_b64 v[96:97], 12, v[96:97]
	v_lshl_add_u64 v[96:97], s[84:85], 0, v[96:97]
	v_lshl_add_u64 v[138:139], v[96:97], 0, v[168:169]
	v_or_b32_e32 v96, 43, v166
	v_ashrrev_i32_e32 v97, 31, v96
	v_lshlrev_b64 v[96:97], 12, v[96:97]
	v_lshl_add_u64 v[96:97], s[84:85], 0, v[96:97]
	v_mfma_f32_32x32x16_bf16 v[0:15], v[128:131], v[132:135], v[0:15]
	global_load_dword v128, v[140:141], off offset:128
	global_load_dword v129, v[136:137], off
	global_load_dword v130, v[136:137], off offset:128
	global_load_dword v131, v[138:139], off
	global_load_dword v132, v[138:139], off offset:128
	v_lshl_add_u64 v[96:97], v[96:97], 0, v[168:169]
	global_load_dword v133, v[96:97], off
	s_nop 0
	global_store_dword v[112:113], v98, off
	v_add_f32_e32 v98, v100, v164
	global_store_dword v[112:113], v98, off offset:128
	v_add_f32_e32 v98, v117, v167
	global_store_dword v[114:115], v98, off
	v_add_f32_e32 v98, v101, v177
	global_store_dword v[114:115], v98, off offset:128
	v_add_f32_e32 v98, v118, v188
	global_store_dword v[148:149], v64, off offset:128
	s_waitcnt vmcnt(17)
	v_add_f32_e32 v64, v81, v204
	global_store_dword v[172:173], v98, off
	v_add_f32_e32 v98, v102, v189
	global_store_dword v[150:151], v64, off
	s_waitcnt vmcnt(18)
	v_add_f32_e32 v64, v65, v205
	global_store_dword v[172:173], v98, off offset:128
	v_add_f32_e32 v98, v119, v190
	global_store_dword v[150:151], v64, off offset:128
	s_waitcnt vmcnt(19)
	v_add_f32_e32 v64, v82, v207
	global_store_dword v[174:175], v98, off
	v_add_f32_e32 v98, v103, v191
	global_store_dword v[144:145], v64, off
	s_waitcnt vmcnt(20)
	v_add_f32_e32 v64, v66, v208
	global_store_dword v[174:175], v98, off offset:128
	v_add_f32_e32 v98, v120, v192
	global_store_dword v[144:145], v64, off offset:128
	s_waitcnt vmcnt(21)
	v_add_f32_e32 v64, v83, v209
	global_store_dword v[178:179], v98, off
	v_add_f32_e32 v98, v104, v193
	global_store_dword v[146:147], v64, off
	s_waitcnt vmcnt(22)
	v_add_f32_e32 v64, v67, v210
	global_store_dword v[178:179], v98, off offset:128
	v_add_f32_e32 v98, v121, v194
	global_store_dword v[146:147], v64, off offset:128
	global_store_dword v[180:181], v98, off
	v_add_f32_e32 v98, v105, v195
	global_store_dword v[180:181], v98, off offset:128
	v_add_f32_e32 v98, v122, v196
	global_store_dword v[182:183], v98, off
	v_add_f32_e32 v98, v106, v197
	global_store_dword v[182:183], v98, off offset:128
	v_add_f32_e32 v98, v123, v198
	global_store_dword v[184:185], v98, off
	v_add_f32_e32 v98, v107, v199
	global_store_dword v[184:185], v98, off offset:128
	v_add_f32_e32 v98, v124, v152
	global_load_dword v124, v[96:97], off offset:128
	s_waitcnt vmcnt(30)
	v_add_f32_e32 v64, v84, v142
	global_store_dword v[140:141], v64, off
	global_store_dword v[148:149], v80, off
	global_store_dword v[186:187], v98, off
	v_add_f32_e32 v98, v108, v153
	global_store_dword v[186:187], v98, off offset:128
	v_add_f32_e32 v98, v125, v154
	global_store_dword v[160:161], v98, off
	v_add_f32_e32 v98, v109, v155
	global_store_dword v[160:161], v98, off offset:128
	s_waitcnt vmcnt(35)
	v_add_f32_e32 v64, v68, v128
	global_store_dword v[140:141], v64, off offset:128
	s_waitcnt vmcnt(35)
	v_add_f32_e32 v64, v85, v129
	global_store_dword v[136:137], v64, off
	s_waitcnt vmcnt(35)
	v_add_f32_e32 v64, v69, v130
	global_store_dword v[136:137], v64, off offset:128
	s_waitcnt vmcnt(35)
	v_add_f32_e32 v64, v86, v131
	global_store_dword v[138:139], v64, off
	s_waitcnt vmcnt(35)
	v_add_f32_e32 v64, v70, v132
	global_store_dword v[138:139], v64, off offset:128
	s_waitcnt vmcnt(35)
	v_add_f32_e32 v64, v87, v133
	global_store_dword v[96:97], v64, off
	v_or_b32_e32 v64, 48, v166
	v_ashrrev_i32_e32 v65, 31, v64
	v_lshlrev_b64 v[64:65], 12, v[64:65]
	v_lshl_add_u64 v[64:65], s[84:85], 0, v[64:65]
	v_lshl_add_u64 v[66:67], v[64:65], 0, v[168:169]
	v_or_b32_e32 v64, 49, v166
	v_ashrrev_i32_e32 v65, 31, v64
	v_lshlrev_b64 v[64:65], 12, v[64:65]
	v_lshl_add_u64 v[64:65], s[84:85], 0, v[64:65]
	v_lshl_add_u64 v[68:69], v[64:65], 0, v[168:169]
	v_or_b32_e32 v64, 50, v166
	v_ashrrev_i32_e32 v65, 31, v64
	v_lshlrev_b64 v[64:65], 12, v[64:65]
	v_lshl_add_u64 v[64:65], s[84:85], 0, v[64:65]
	v_lshl_add_u64 v[80:81], v[64:65], 0, v[168:169]
	v_or_b32_e32 v64, 51, v166
	v_ashrrev_i32_e32 v65, 31, v64
	v_lshlrev_b64 v[64:65], 12, v[64:65]
	v_lshl_add_u64 v[64:65], s[84:85], 0, v[64:65]
	v_lshl_add_u64 v[82:83], v[64:65], 0, v[168:169]
	v_or_b32_e32 v64, 56, v166
	v_ashrrev_i32_e32 v65, 31, v64
	v_lshlrev_b64 v[64:65], 12, v[64:65]
	v_lshl_add_u64 v[64:65], s[84:85], 0, v[64:65]
	v_lshl_add_u64 v[84:85], v[64:65], 0, v[168:169]
	v_or_b32_e32 v64, 57, v166
	v_ashrrev_i32_e32 v65, 31, v64
	v_lshlrev_b64 v[64:65], 12, v[64:65]
	v_add_f32_e32 v98, v126, v162
	v_lshl_add_u64 v[64:65], s[84:85], 0, v[64:65]
	global_store_dword v[156:157], v98, off
	v_add_f32_e32 v98, v110, v163
	v_lshl_add_u64 v[86:87], v[64:65], 0, v[168:169]
	v_or_b32_e32 v64, 58, v166
	global_store_dword v[156:157], v98, off offset:128
	v_add_f32_e32 v98, v127, v200
	v_ashrrev_i32_e32 v65, 31, v64
	global_store_dword v[158:159], v98, off
	v_add_f32_e32 v98, v111, v201
	v_lshlrev_b64 v[64:65], 12, v[64:65]
	global_store_dword v[170:171], v99, off offset:128
	global_store_dword v[158:159], v98, off offset:128
	v_lshl_add_u64 v[64:65], s[84:85], 0, v[64:65]
	global_load_dword v70, v[66:67], off
	global_load_dword v125, v[66:67], off offset:128
	global_load_dword v126, v[68:69], off
	global_load_dword v127, v[68:69], off offset:128
	global_load_dword v128, v[80:81], off
	global_load_dword v129, v[80:81], off offset:128
	global_load_dword v130, v[82:83], off
	global_load_dword v131, v[82:83], off offset:128
	v_lshl_add_u64 v[98:99], v[64:65], 0, v[168:169]
	v_or_b32_e32 v64, 59, v166
	v_ashrrev_i32_e32 v65, 31, v64
	v_lshlrev_b64 v[64:65], 12, v[64:65]
	v_lshl_add_u64 v[64:65], s[84:85], 0, v[64:65]
	v_lshl_add_u64 v[100:101], v[64:65], 0, v[168:169]
	v_or_b32_e32 v64, 64, v166
	v_ashrrev_i32_e32 v65, 31, v64
	v_lshlrev_b64 v[64:65], 12, v[64:65]
	v_lshl_add_u64 v[64:65], s[84:85], 0, v[64:65]
	global_load_dword v132, v[84:85], off
	global_load_dword v133, v[84:85], off offset:128
	global_load_dword v134, v[86:87], off
	global_load_dword v135, v[86:87], off offset:128
	global_load_dword v136, v[98:99], off
	global_load_dword v137, v[98:99], off offset:128
	global_load_dword v138, v[100:101], off
	global_load_dword v139, v[100:101], off offset:128
	v_lshl_add_u64 v[102:103], v[64:65], 0, v[168:169]
	v_or_b32_e32 v64, 0x41, v166
	v_ashrrev_i32_e32 v65, 31, v64
	v_lshlrev_b64 v[64:65], 12, v[64:65]
	v_lshl_add_u64 v[64:65], s[84:85], 0, v[64:65]
	v_lshl_add_u64 v[104:105], v[64:65], 0, v[168:169]
	v_or_b32_e32 v64, 0x42, v166
	v_ashrrev_i32_e32 v65, 31, v64
	v_lshlrev_b64 v[64:65], 12, v[64:65]
	v_lshl_add_u64 v[64:65], s[84:85], 0, v[64:65]
	v_lshl_add_u64 v[106:107], v[64:65], 0, v[168:169]
	v_or_b32_e32 v64, 0x43, v166
	v_ashrrev_i32_e32 v65, 31, v64
	v_lshlrev_b64 v[64:65], 12, v[64:65]
	v_lshl_add_u64 v[64:65], s[84:85], 0, v[64:65]
	v_lshl_add_u64 v[108:109], v[64:65], 0, v[168:169]
	v_or_b32_e32 v64, 0x48, v166
	v_ashrrev_i32_e32 v65, 31, v64
	v_lshlrev_b64 v[64:65], 12, v[64:65]
	v_lshl_add_u64 v[64:65], s[84:85], 0, v[64:65]
	v_lshl_add_u64 v[110:111], v[64:65], 0, v[168:169]
	v_or_b32_e32 v64, 0x49, v166
	v_ashrrev_i32_e32 v65, 31, v64
	v_lshlrev_b64 v[64:65], 12, v[64:65]
	v_lshl_add_u64 v[64:65], s[84:85], 0, v[64:65]
	v_lshl_add_u64 v[112:113], v[64:65], 0, v[168:169]
	v_or_b32_e32 v64, 0x4a, v166
	v_ashrrev_i32_e32 v65, 31, v64
	v_lshlrev_b64 v[64:65], 12, v[64:65]
	v_lshl_add_u64 v[64:65], s[84:85], 0, v[64:65]
	v_lshl_add_u64 v[114:115], v[64:65], 0, v[168:169]
	v_or_b32_e32 v64, 0x4b, v166
	v_ashrrev_i32_e32 v65, 31, v64
	v_lshlrev_b64 v[64:65], 12, v[64:65]
	v_lshl_add_u64 v[64:65], s[84:85], 0, v[64:65]
	v_lshl_add_u64 v[116:117], v[64:65], 0, v[168:169]
	v_or_b32_e32 v64, 0x50, v166
	v_ashrrev_i32_e32 v65, 31, v64
	global_load_dword v140, v[102:103], off
	global_load_dword v141, v[102:103], off offset:128
	global_load_dword v142, v[104:105], off
	global_load_dword v143, v[104:105], off offset:128
	global_load_dword v144, v[106:107], off
	global_load_dword v145, v[106:107], off offset:128
	global_load_dword v146, v[108:109], off
	global_load_dword v147, v[108:109], off offset:128
	v_lshlrev_b64 v[64:65], 12, v[64:65]
	v_lshl_add_u64 v[64:65], s[84:85], 0, v[64:65]
	v_lshl_add_u64 v[118:119], v[64:65], 0, v[168:169]
	v_or_b32_e32 v64, 0x51, v166
	v_ashrrev_i32_e32 v65, 31, v64
	v_lshlrev_b64 v[64:65], 12, v[64:65]
	v_lshl_add_u64 v[64:65], s[84:85], 0, v[64:65]
	v_lshl_add_u64 v[120:121], v[64:65], 0, v[168:169]
	v_or_b32_e32 v64, 0x52, v166
	v_ashrrev_i32_e32 v65, 31, v64
	global_load_dword v148, v[110:111], off
	global_load_dword v149, v[110:111], off offset:128
	global_load_dword v150, v[112:113], off
	global_load_dword v151, v[112:113], off offset:128
	global_load_dword v152, v[114:115], off
	global_load_dword v153, v[114:115], off offset:128
	global_load_dword v154, v[116:117], off
	global_load_dword v155, v[116:117], off offset:128
	v_lshlrev_b64 v[64:65], 12, v[64:65]
	global_load_dword v156, v[118:119], off
	v_lshl_add_u64 v[64:65], s[84:85], 0, v[64:65]
	v_lshl_add_u64 v[122:123], v[64:65], 0, v[168:169]
	v_or_b32_e32 v64, 0x53, v166
	v_ashrrev_i32_e32 v65, 31, v64
	v_lshlrev_b64 v[64:65], 12, v[64:65]
	v_lshl_add_u64 v[64:65], s[84:85], 0, v[64:65]
	global_load_dword v157, v[118:119], off offset:128
	global_load_dword v158, v[120:121], off
	global_load_dword v159, v[120:121], off offset:128
	global_load_dword v160, v[122:123], off
	global_load_dword v161, v[122:123], off offset:128
	v_lshl_add_u64 v[64:65], v[64:65], 0, v[168:169]
	global_load_dword v162, v[64:65], off
	s_waitcnt vmcnt(38)
	v_add_f32_e32 v70, v88, v70
	global_store_dword v[66:67], v70, off
	s_waitcnt vmcnt(38)
	v_add_f32_e32 v70, v72, v125
	global_store_dword v[66:67], v70, off offset:128
	s_waitcnt vmcnt(38)
	v_add_f32_e32 v66, v89, v126
	global_store_dword v[68:69], v66, off
	s_waitcnt vmcnt(38)
	v_add_f32_e32 v66, v73, v127
	global_store_dword v[68:69], v66, off offset:128
	s_waitcnt vmcnt(38)
	v_add_f32_e32 v66, v90, v128
	global_store_dword v[80:81], v66, off
	s_waitcnt vmcnt(38)
	v_add_f32_e32 v66, v74, v129
	global_store_dword v[80:81], v66, off offset:128
	s_waitcnt vmcnt(38)
	v_add_f32_e32 v66, v91, v130
	global_store_dword v[82:83], v66, off
	s_waitcnt vmcnt(38)
	v_add_f32_e32 v66, v75, v131
	global_store_dword v[82:83], v66, off offset:128
	s_waitcnt vmcnt(38)
	v_add_f32_e32 v66, v92, v132
	global_store_dword v[84:85], v66, off
	s_waitcnt vmcnt(38)
	v_add_f32_e32 v66, v76, v133
	global_store_dword v[84:85], v66, off offset:128
	global_load_dword v84, v[64:65], off offset:128
	s_waitcnt vmcnt(39)
	v_add_f32_e32 v66, v93, v134
	global_store_dword v[86:87], v66, off
	s_waitcnt vmcnt(39)
	v_add_f32_e32 v66, v77, v135
	global_store_dword v[86:87], v66, off offset:128
	s_waitcnt vmcnt(39)
	v_add_f32_e32 v66, v94, v136
	global_store_dword v[98:99], v66, off
	s_waitcnt vmcnt(39)
	v_add_f32_e32 v66, v78, v137
	global_store_dword v[98:99], v66, off offset:128
	s_waitcnt vmcnt(39)
	v_add_f32_e32 v66, v95, v138
	v_add_f32_e32 v71, v71, v124
	global_store_dword v[100:101], v66, off
	s_waitcnt vmcnt(39)
	v_add_f32_e32 v66, v79, v139
	global_store_dword v[96:97], v71, off offset:128
	global_store_dword v[100:101], v66, off offset:128
	v_or_b32_e32 v66, 0x6b, v166
	v_ashrrev_i32_e32 v67, 31, v66
	v_lshlrev_b64 v[66:67], 12, v[66:67]
	v_lshl_add_u64 v[66:67], s[84:85], 0, v[66:67]
	v_lshl_add_u64 v[66:67], v[66:67], 0, v[168:169]
	v_or_b32_e32 v68, 0x70, v166
	v_ashrrev_i32_e32 v69, 31, v68
	v_or_b32_e32 v70, 0x71, v166
	v_or_b32_e32 v72, 0x72, v166
	v_or_b32_e32 v74, 0x73, v166
	v_or_b32_e32 v76, 0x78, v166
	v_lshlrev_b64 v[68:69], 12, v[68:69]
	v_ashrrev_i32_e32 v71, 31, v70
	v_ashrrev_i32_e32 v73, 31, v72
	v_ashrrev_i32_e32 v75, 31, v74
	s_waitcnt vmcnt(40)
	v_add_f32_e32 v48, v48, v140
	s_waitcnt vmcnt(39)
	v_add_f32_e32 v32, v32, v141
	global_store_dword v[102:103], v32, off offset:128
	s_waitcnt vmcnt(39)
	v_add_f32_e32 v32, v49, v142
	global_store_dword v[104:105], v32, off
	s_waitcnt vmcnt(39)
	v_add_f32_e32 v32, v33, v143
	global_store_dword v[104:105], v32, off offset:128
	s_waitcnt vmcnt(39)
	v_add_f32_e32 v32, v50, v144
	global_store_dword v[106:107], v32, off
	s_waitcnt vmcnt(39)
	v_add_f32_e32 v32, v34, v145
	global_store_dword v[106:107], v32, off offset:128
	s_waitcnt vmcnt(39)
	v_add_f32_e32 v32, v51, v146
	global_store_dword v[108:109], v32, off
	s_waitcnt vmcnt(39)
	v_add_f32_e32 v32, v35, v147
	global_store_dword v[108:109], v32, off offset:128
	s_waitcnt vmcnt(39)
	v_add_f32_e32 v32, v52, v148
	global_store_dword v[110:111], v32, off
	s_waitcnt vmcnt(39)
	v_add_f32_e32 v32, v36, v149
	global_store_dword v[110:111], v32, off offset:128
	s_waitcnt vmcnt(39)
	v_add_f32_e32 v32, v53, v150
	global_store_dword v[112:113], v32, off
	s_waitcnt vmcnt(39)
	v_add_f32_e32 v32, v37, v151
	global_store_dword v[112:113], v32, off offset:128
	s_waitcnt vmcnt(39)
	v_add_f32_e32 v32, v54, v152
	global_store_dword v[114:115], v32, off
	s_waitcnt vmcnt(39)
	v_add_f32_e32 v32, v38, v153
	global_store_dword v[114:115], v32, off offset:128
	s_waitcnt vmcnt(39)
	v_add_f32_e32 v32, v55, v154
	global_store_dword v[116:117], v32, off
	s_waitcnt vmcnt(39)
	v_add_f32_e32 v32, v39, v155
	global_store_dword v[116:117], v32, off offset:128
	s_waitcnt vmcnt(39)
	v_add_f32_e32 v32, v56, v156
	global_store_dword v[118:119], v32, off
	s_waitcnt vmcnt(39)
	v_add_f32_e32 v32, v40, v157
	global_store_dword v[118:119], v32, off offset:128
	s_waitcnt vmcnt(39)
	v_add_f32_e32 v32, v57, v158
	global_store_dword v[120:121], v32, off
	s_waitcnt vmcnt(39)
	v_add_f32_e32 v32, v41, v159
	global_store_dword v[120:121], v32, off offset:128
	s_waitcnt vmcnt(39)
	v_add_f32_e32 v32, v58, v160
	global_store_dword v[122:123], v32, off
	s_waitcnt vmcnt(39)
	v_add_f32_e32 v32, v42, v161
	global_store_dword v[122:123], v32, off offset:128
	s_waitcnt vmcnt(39)
	v_add_f32_e32 v32, v59, v162
	global_store_dword v[64:65], v32, off
	v_or_b32_e32 v32, 0x58, v166
	v_or_b32_e32 v40, 0x60, v166
	global_store_dword v[102:103], v48, off
	v_ashrrev_i32_e32 v33, 31, v32
	v_or_b32_e32 v34, 0x59, v166
	v_or_b32_e32 v36, 0x5a, v166
	v_or_b32_e32 v38, 0x5b, v166
	v_ashrrev_i32_e32 v41, 31, v40
	v_or_b32_e32 v48, 0x61, v166
	v_or_b32_e32 v50, 0x62, v166
	v_or_b32_e32 v52, 0x63, v166
	v_lshlrev_b64 v[32:33], 12, v[32:33]
	v_ashrrev_i32_e32 v35, 31, v34
	v_ashrrev_i32_e32 v37, 31, v36
	v_ashrrev_i32_e32 v39, 31, v38
	v_lshlrev_b64 v[40:41], 12, v[40:41]
	v_ashrrev_i32_e32 v49, 31, v48
	v_ashrrev_i32_e32 v51, 31, v50
	v_ashrrev_i32_e32 v53, 31, v52
	v_lshl_add_u64 v[32:33], s[84:85], 0, v[32:33]
	v_lshlrev_b64 v[34:35], 12, v[34:35]
	v_lshlrev_b64 v[36:37], 12, v[36:37]
	v_lshlrev_b64 v[38:39], 12, v[38:39]
	v_lshl_add_u64 v[40:41], s[84:85], 0, v[40:41]
	v_lshlrev_b64 v[48:49], 12, v[48:49]
	v_lshlrev_b64 v[50:51], 12, v[50:51]
	v_lshlrev_b64 v[52:53], 12, v[52:53]
	v_lshl_add_u64 v[32:33], v[32:33], 0, v[168:169]
	v_lshl_add_u64 v[34:35], s[84:85], 0, v[34:35]
	v_lshl_add_u64 v[36:37], s[84:85], 0, v[36:37]
	v_lshl_add_u64 v[38:39], s[84:85], 0, v[38:39]
	v_lshl_add_u64 v[40:41], v[40:41], 0, v[168:169]
	v_lshl_add_u64 v[48:49], s[84:85], 0, v[48:49]
	v_lshl_add_u64 v[50:51], s[84:85], 0, v[50:51]
	v_lshl_add_u64 v[52:53], s[84:85], 0, v[52:53]
	v_lshl_add_u64 v[34:35], v[34:35], 0, v[168:169]
	v_lshl_add_u64 v[36:37], v[36:37], 0, v[168:169]
	v_lshl_add_u64 v[38:39], v[38:39], 0, v[168:169]
	global_load_dword v42, v[32:33], off
	global_load_dword v85, v[32:33], off offset:128
	global_load_dword v86, v[34:35], off
	global_load_dword v87, v[34:35], off offset:128
	global_load_dword v88, v[36:37], off
	global_load_dword v89, v[36:37], off offset:128
	global_load_dword v90, v[38:39], off
	global_load_dword v91, v[38:39], off offset:128
	v_lshl_add_u64 v[48:49], v[48:49], 0, v[168:169]
	v_lshl_add_u64 v[50:51], v[50:51], 0, v[168:169]
	v_lshl_add_u64 v[52:53], v[52:53], 0, v[168:169]
	global_load_dword v92, v[40:41], off
	global_load_dword v93, v[40:41], off offset:128
	global_load_dword v94, v[48:49], off
	global_load_dword v95, v[48:49], off offset:128
	global_load_dword v96, v[50:51], off
	global_load_dword v97, v[50:51], off offset:128
	global_load_dword v98, v[52:53], off
	global_load_dword v99, v[52:53], off offset:128
	v_or_b32_e32 v54, 0x68, v166
	v_ashrrev_i32_e32 v55, 31, v54
	v_or_b32_e32 v56, 0x69, v166
	v_or_b32_e32 v58, 0x6a, v166
	v_lshlrev_b64 v[54:55], 12, v[54:55]
	v_ashrrev_i32_e32 v57, 31, v56
	v_ashrrev_i32_e32 v59, 31, v58
	v_lshl_add_u64 v[54:55], s[84:85], 0, v[54:55]
	v_lshlrev_b64 v[56:57], 12, v[56:57]
	v_lshlrev_b64 v[58:59], 12, v[58:59]
	v_lshl_add_u64 v[54:55], v[54:55], 0, v[168:169]
	v_lshl_add_u64 v[56:57], s[84:85], 0, v[56:57]
	v_lshl_add_u64 v[58:59], s[84:85], 0, v[58:59]
	v_lshl_add_u64 v[56:57], v[56:57], 0, v[168:169]
	v_lshl_add_u64 v[58:59], v[58:59], 0, v[168:169]
	global_load_dword v100, v[54:55], off
	global_load_dword v101, v[54:55], off offset:128
	global_load_dword v102, v[56:57], off
	global_load_dword v103, v[56:57], off offset:128
	global_load_dword v104, v[58:59], off
	global_load_dword v105, v[58:59], off offset:128
	global_load_dword v106, v[66:67], off
	global_load_dword v107, v[66:67], off offset:128
	v_ashrrev_i32_e32 v77, 31, v76
	v_lshl_add_u64 v[68:69], s[84:85], 0, v[68:69]
	v_lshlrev_b64 v[70:71], 12, v[70:71]
	v_lshlrev_b64 v[72:73], 12, v[72:73]
	v_lshlrev_b64 v[74:75], 12, v[74:75]
	v_lshlrev_b64 v[76:77], 12, v[76:77]
	v_lshl_add_u64 v[68:69], v[68:69], 0, v[168:169]
	v_lshl_add_u64 v[70:71], s[84:85], 0, v[70:71]
	v_lshl_add_u64 v[72:73], s[84:85], 0, v[72:73]
	v_lshl_add_u64 v[74:75], s[84:85], 0, v[74:75]
	v_lshl_add_u64 v[76:77], s[84:85], 0, v[76:77]
	v_lshl_add_u64 v[70:71], v[70:71], 0, v[168:169]
	v_lshl_add_u64 v[72:73], v[72:73], 0, v[168:169]
	v_lshl_add_u64 v[74:75], v[74:75], 0, v[168:169]
	global_load_dword v108, v[68:69], off
	global_load_dword v109, v[68:69], off offset:128
	global_load_dword v110, v[70:71], off
	global_load_dword v111, v[70:71], off offset:128
	global_load_dword v112, v[72:73], off
	global_load_dword v113, v[72:73], off offset:128
	global_load_dword v114, v[74:75], off
	global_load_dword v115, v[74:75], off offset:128
	v_lshl_add_u64 v[76:77], v[76:77], 0, v[168:169]
	global_load_dword v116, v[76:77], off
	v_or_b32_e32 v78, 0x79, v166
	v_or_b32_e32 v80, 0x7a, v166
	v_or_b32_e32 v82, 0x7b, v166
	v_ashrrev_i32_e32 v79, 31, v78
	v_ashrrev_i32_e32 v81, 31, v80
	v_ashrrev_i32_e32 v83, 31, v82
	v_lshlrev_b64 v[78:79], 12, v[78:79]
	v_lshlrev_b64 v[80:81], 12, v[80:81]
	v_lshlrev_b64 v[82:83], 12, v[82:83]
	v_lshl_add_u64 v[78:79], s[84:85], 0, v[78:79]
	v_lshl_add_u64 v[80:81], s[84:85], 0, v[80:81]
	v_lshl_add_u64 v[82:83], s[84:85], 0, v[82:83]
	v_lshl_add_u64 v[78:79], v[78:79], 0, v[168:169]
	v_lshl_add_u64 v[80:81], v[80:81], 0, v[168:169]
	global_load_dword v117, v[76:77], off offset:128
	global_load_dword v118, v[78:79], off
	global_load_dword v119, v[78:79], off offset:128
	global_load_dword v120, v[80:81], off
	global_load_dword v121, v[80:81], off offset:128
	v_lshl_add_u64 v[82:83], v[82:83], 0, v[168:169]
	global_load_dword v122, v[82:83], off
	s_waitcnt vmcnt(62)
	v_add_f32_e32 v43, v43, v84
	global_load_dword v84, v[82:83], off offset:128
	s_waitcnt vmcnt(39)
	v_add_f32_e32 v42, v60, v42
	global_store_dword v[32:33], v42, off
	s_waitcnt vmcnt(39)
	v_add_f32_e32 v42, v44, v85
	global_store_dword v[32:33], v42, off offset:128
	s_waitcnt vmcnt(39)
	v_add_f32_e32 v32, v61, v86
	s_waitcnt vmcnt(32)
	v_add_f32_e32 v0, v0, v93
	global_store_dword v[40:41], v0, off offset:128
	s_waitcnt vmcnt(32)
	v_add_f32_e32 v0, v17, v94
	global_store_dword v[48:49], v0, off
	s_waitcnt vmcnt(32)
	v_add_f32_e32 v0, v1, v95
	global_store_dword v[48:49], v0, off offset:128
	s_waitcnt vmcnt(32)
	v_add_f32_e32 v0, v18, v96
	global_store_dword v[50:51], v0, off
	s_waitcnt vmcnt(32)
	v_add_f32_e32 v0, v2, v97
	global_store_dword v[50:51], v0, off offset:128
	s_waitcnt vmcnt(32)
	v_add_f32_e32 v0, v19, v98
	global_store_dword v[52:53], v0, off
	s_waitcnt vmcnt(32)
	v_add_f32_e32 v0, v3, v99
	global_store_dword v[52:53], v0, off offset:128
	global_store_dword v[34:35], v32, off
	s_waitcnt vmcnt(33)
	v_add_f32_e32 v0, v20, v100
	global_store_dword v[54:55], v0, off
	s_waitcnt vmcnt(33)
	v_add_f32_e32 v0, v4, v101
	global_store_dword v[54:55], v0, off offset:128
	s_waitcnt vmcnt(33)
	v_add_f32_e32 v0, v21, v102
	global_store_dword v[56:57], v0, off
	s_waitcnt vmcnt(33)
	v_add_f32_e32 v0, v5, v103
	global_store_dword v[56:57], v0, off offset:128
	s_waitcnt vmcnt(33)
	v_add_f32_e32 v0, v22, v104
	global_store_dword v[58:59], v0, off
	s_waitcnt vmcnt(33)
	v_add_f32_e32 v0, v6, v105
	global_store_dword v[58:59], v0, off offset:128
	s_waitcnt vmcnt(33)
	v_add_f32_e32 v0, v23, v106
	global_store_dword v[66:67], v0, off
	s_waitcnt vmcnt(33)
	v_add_f32_e32 v0, v7, v107
	global_store_dword v[66:67], v0, off offset:128
	s_waitcnt vmcnt(33)
	v_add_f32_e32 v0, v24, v108
	global_store_dword v[68:69], v0, off
	s_waitcnt vmcnt(33)
	v_add_f32_e32 v0, v8, v109
	global_store_dword v[68:69], v0, off offset:128
	s_waitcnt vmcnt(33)
	v_add_f32_e32 v0, v25, v110
	global_store_dword v[70:71], v0, off
	s_waitcnt vmcnt(33)
	v_add_f32_e32 v0, v9, v111
	global_store_dword v[70:71], v0, off offset:128
	s_waitcnt vmcnt(33)
	v_add_f32_e32 v0, v26, v112
	global_store_dword v[72:73], v0, off
	s_waitcnt vmcnt(33)
	v_add_f32_e32 v0, v10, v113
	global_store_dword v[72:73], v0, off offset:128
	s_waitcnt vmcnt(33)
	v_add_f32_e32 v0, v27, v114
	global_store_dword v[74:75], v0, off
	s_waitcnt vmcnt(33)
	v_add_f32_e32 v0, v11, v115
	global_store_dword v[74:75], v0, off offset:128
	s_waitcnt vmcnt(33)
	v_add_f32_e32 v0, v28, v116
	global_store_dword v[76:77], v0, off
	v_add_f32_e32 v32, v45, v87
	s_waitcnt vmcnt(33)
	v_add_f32_e32 v0, v12, v117
	global_store_dword v[76:77], v0, off offset:128
	s_waitcnt vmcnt(33)
	v_add_f32_e32 v0, v29, v118
	global_store_dword v[78:79], v0, off
	s_waitcnt vmcnt(33)
	v_add_f32_e32 v0, v13, v119
	global_store_dword v[34:35], v32, off offset:128
	v_add_f32_e32 v32, v62, v88
	global_store_dword v[78:79], v0, off offset:128
	s_waitcnt vmcnt(34)
	v_add_f32_e32 v0, v30, v120
	global_store_dword v[36:37], v32, off
	v_add_f32_e32 v32, v46, v89
	global_store_dword v[80:81], v0, off
	s_waitcnt vmcnt(35)
	v_add_f32_e32 v0, v14, v121
	global_store_dword v[36:37], v32, off offset:128
	v_add_f32_e32 v32, v63, v90
	global_store_dword v[80:81], v0, off offset:128
	s_waitcnt vmcnt(36)
	v_add_f32_e32 v0, v31, v122
	global_store_dword v[38:39], v32, off
	v_add_f32_e32 v32, v47, v91
	v_add_f32_e32 v16, v16, v92
	global_store_dword v[82:83], v0, off
	s_waitcnt vmcnt(37)
	v_add_f32_e32 v0, v15, v84
	global_store_dword v[64:65], v43, off offset:128
	global_store_dword v[38:39], v32, off offset:128
	global_store_dword v[40:41], v16, off
	global_store_dword v[82:83], v0, off offset:128
	s_cbranch_scc1 .LBB0_991
	v_readlane_b32 s16, v252, 39
